# static s_setprio 1 for waves 4-7 during the two attention phases
# baseline (speedup 1.0000x reference)
.LBB0_868:
.LBB0_869:
	s_lshr_b32 s99, s88, 2
	s_cmp_lg_u32 s99, 1
	s_cbranch_scc1 .Lat_prio0
	s_setprio 1
.Lat_prio0:
	s_add_i32 s0, 0, 0x23f94
	s_waitcnt vmcnt(0)
	v_mov_b32_e32 v0, s0
	v_mbcnt_lo_u32_b32 v58, -1, 0
	v_mbcnt_hi_u32_b32 v58, -1, v58
	ds_read_b32 v0, v0
	v_lshlrev_b32_e32 v71, 4, v58
	v_and_b32_e32 v59, 15, v58
	s_mov_b32 s1, 0
	v_ashrrev_i32_e32 v70, 4, v58
	s_waitcnt lgkmcnt(0)
	v_readfirstlane_b32 s0, v0
	s_and_b32 s4, s0, 7
	s_mul_i32 s5, s4, 0x1400000
	s_add_u32 s5, s94, s5
	s_addc_u32 s6, s95, 0
	s_lshl_b32 s4, s4, 22
	s_sub_u32 s4, 0, s4
	s_subb_u32 s7, 0, 0
	s_add_u32 s4, s5, s4
	s_addc_u32 s5, s6, s7
	s_lshl_b32 s8, s88, 10
	v_add_u32_e32 v0, s8, v71
	v_ashrrev_i32_e32 v1, 31, v0
	v_lshrrev_b32_e32 v1, 22, v1
	v_add_u32_e32 v1, v0, v1
	v_ashrrev_i32_e32 v1, 10, v1
	v_mul_i32_i24_e32 v2, 0x400, v1
	v_sub_u32_e32 v2, v0, v2
	v_lshrrev_b32_e32 v3, 4, v2
	v_bitop3_b32 v2, v3, v2, 32 bitop3:0x6c
	v_ashrrev_i32_e32 v4, 31, v2
	v_lshrrev_b32_e32 v4, 26, v4
	v_lshlrev_b32_e32 v3, 3, v1
	v_add_u32_e32 v4, v2, v4
	v_and_b32_e32 v3, -16, v3
	v_ashrrev_i32_e32 v5, 6, v4
	v_add_u32_e32 v104, v5, v3
	v_and_b32_e32 v3, 0xc0, v4
	v_lshlrev_b32_e32 v1, 5, v1
	v_sub_u32_e32 v2, v2, v3
	v_mov_b32_e32 v3, 1
	v_and_b32_e32 v1, 32, v1
	v_ashrrev_i16_sdwa v2, v3, sext(v2) dst_sel:DWORD dst_unused:UNUSED_PAD src0_sel:DWORD src1_sel:BYTE_0
	v_add_u32_sdwa v1, v1, sext(v2) dst_sel:DWORD dst_unused:UNUSED_PAD src0_sel:DWORD src1_sel:WORD_0
	v_lshlrev_b32_e32 v2, 10, v104
	v_add_u32_e32 v0, 0x2000, v0
	v_lshl_add_u32 v62, v1, 1, v2
	v_ashrrev_i32_e32 v1, 31, v0
	v_lshrrev_b32_e32 v1, 22, v1
	v_add_u32_e32 v1, v0, v1
	v_ashrrev_i32_e32 v1, 10, v1
	v_mul_i32_i24_e32 v2, 0x400, v1
	v_sub_u32_e32 v0, v0, v2
	v_lshrrev_b32_e32 v2, 4, v0
	s_lshl_b32 s6, s0, 3
	v_bitop3_b32 v0, v2, v0, 32 bitop3:0x6c
	s_and_b32 s6, s6, 56
	s_ashr_i32 s7, s0, 5
	v_ashrrev_i32_e32 v4, 31, v0
	s_add_i32 s9, s6, s7
	v_lshrrev_b32_e32 v4, 26, v4
	s_ashr_i32 s12, s9, 5
	v_lshlrev_b32_e32 v2, 3, v1
	v_add_u32_e32 v4, v0, v4
	s_bfe_u32 s0, s0, 0x20003
	s_lshl_b32 s6, s12, 2
	v_and_b32_e32 v2, -16, v2
	v_ashrrev_i32_e32 v5, 6, v4
	s_or_b32 s6, s6, s0
	v_add_u32_e32 v108, v5, v2
	v_and_b32_e32 v2, 0xffc0, v4
	s_ashr_i32 s7, s6, 31
	v_sub_u32_e32 v0, v0, v2
	s_lshl_b64 s[6:7], s[6:7], 18
	v_lshrrev_b16_e32 v2, 7, v0
	s_add_u32 s10, s94, s6
	v_and_b32_e32 v2, 1, v2
	s_addc_u32 s11, s95, s7
	v_lshlrev_b32_e32 v1, 5, v1
	v_add_u16_e32 v0, v0, v2
	s_add_u32 s6, s10, 0x11400000
	v_and_b32_e32 v1, 32, v1
	v_ashrrev_i16_sdwa v0, v3, sext(v0) dst_sel:DWORD dst_unused:UNUSED_PAD src0_sel:DWORD src1_sel:BYTE_0
	s_addc_u32 s7, s11, 0
	s_lshl_b32 s9, s9, 7
	v_add_u32_sdwa v0, v1, sext(v0) dst_sel:DWORD dst_unused:UNUSED_PAD src0_sel:DWORD src1_sel:WORD_0
	v_lshlrev_b32_e32 v1, 10, v108
	s_lshl_b32 s12, s12, 12
	s_and_b32 s9, s9, 0xf80
	v_lshl_add_u32 v64, v0, 1, v1
	v_lshl_or_b32 v1, s88, 4, v59
	s_or_b32 s9, s12, s9
	v_add_u32_e32 v2, s9, v1
	v_ashrrev_i32_e32 v3, 31, v2
	v_lshlrev_b64 v[2:3], 12, v[2:3]
	s_lshl_b32 s0, s0, 10
	v_lshl_add_u64 v[2:3], s[4:5], 0, v[2:3]
	v_lshlrev_b32_e32 v0, 3, v70
	v_lshl_add_u64 v[2:3], v[2:3], 0, s[0:1]
	s_mov_b64 s[0:1], 0x13000000
	v_ashrrev_i32_e32 v1, 31, v0
	v_lshl_add_u64 v[60:61], v[2:3], 0, s[0:1]
	v_lshl_add_u64 v[0:1], v[0:1], 1, v[60:61]
	s_mov_b64 s[0:1], 0xc00000
	v_lshl_add_u64 v[2:3], v[0:1], 0, s[0:1]
	s_mov_b32 s0, 0xc00000
	v_add_co_u32_e32 v0, vcc, s0, v0
	s_add_i32 s22, s8, 0
	s_nop 0
	v_addc_co_u32_e32 v1, vcc, 0, v1, vcc
	v_mov_b32_e32 v63, 0
	s_mov_b32 m0, s22
	s_add_i32 s21, s22, 0x2000
	global_load_dwordx4 v[72:75], v[2:3], off offset:64
	global_load_dwordx4 v[52:55], v[2:3], off offset:128
	global_load_dwordx4 v[48:51], v[2:3], off offset:192
	global_load_dwordx4 v[76:79], v[0:1], off
	v_mov_b32_e32 v65, v63
	global_load_lds_dwordx4 v62, s[6:7]
	v_mov_b32_e32 v240, v62
	s_mov_b32 m0, s21
	v_lshl_add_u64 v[66:67], s[6:7], 0, v[62:63]
	v_lshl_add_u64 v[68:69], s[6:7], 0, v[64:65]
	global_load_lds_dwordx4 v64, s[6:7]
	s_add_i32 s20, s22, 0x4000
	s_mov_b64 s[6:7], 0x80
	s_add_i32 s23, s22, 0x6000
	v_lshl_add_u64 v[56:57], v[66:67], 0, s[6:7]
	s_mov_b32 m0, s20
	s_add_u32 s0, s10, 0x11420000
	global_load_lds_dwordx4 v[56:57], off
	v_lshl_add_u64 v[56:57], v[68:69], 0, s[6:7]
	s_mov_b32 m0, s23
	s_addc_u32 s1, s11, 0
	s_add_i32 s24, s22, 0x8000
	global_load_lds_dwordx4 v[56:57], off
	s_mov_b32 m0, s24
	s_add_i32 s25, s22, 0xa000
	global_load_lds_dwordx4 v62, s[0:1]
	s_mov_b32 m0, s25
	s_mov_b64 s[4:5], 0x180
	global_load_lds_dwordx4 v64, s[0:1]
	s_add_u32 s0, s10, 0x11420080
	s_addc_u32 s1, s11, 0
	s_add_i32 s26, s22, 0xc000
	s_mov_b32 m0, s26
	s_add_i32 s27, s22, 0xe000
	global_load_lds_dwordx4 v62, s[0:1]
	s_mov_b32 m0, s27
	s_add_u32 s8, s10, 0x11c00000
	global_load_lds_dwordx4 v64, s[0:1]
	s_addc_u32 s9, s11, 0
	s_add_i32 s19, s22, 0x10000
	s_mov_b64 s[0:1], 0x100
	v_lshl_add_u64 v[56:57], v[66:67], 0, s[0:1]
	s_mov_b32 m0, s19
	s_add_i32 s13, s22, 0x12000
	global_load_dwordx4 v[44:47], v[2:3], off offset:256
	global_load_dwordx4 v[40:43], v[2:3], off offset:320
	global_load_dwordx4 v[36:39], v[2:3], off offset:384
	global_load_dwordx4 v[32:35], v[2:3], off offset:448
	global_load_dwordx4 v[28:31], v[2:3], off offset:512
	global_load_dwordx4 v[24:27], v[2:3], off offset:576
	global_load_dwordx4 v[20:23], v[2:3], off offset:640
	global_load_dwordx4 v[16:19], v[2:3], off offset:704
	global_load_dwordx4 v[12:15], v[2:3], off offset:768
	global_load_dwordx4 v[8:11], v[2:3], off offset:832
	global_load_dwordx4 v[4:7], v[2:3], off offset:896
	s_nop 0
	global_load_dwordx4 v[0:3], v[2:3], off offset:960
	s_waitcnt vmcnt(12)
	s_waitcnt vmcnt(12) lgkmcnt(0)
	s_barrier
	global_load_lds_dwordx4 v[56:57], off
	v_lshl_add_u64 v[56:57], v[68:69], 0, s[0:1]
	s_mov_b32 m0, s13
	s_add_i32 s12, s22, 0x14000
	s_add_i32 s14, s22, 0x16000
	global_load_lds_dwordx4 v[56:57], off
	v_lshl_add_u64 v[56:57], v[66:67], 0, s[4:5]
	s_mov_b32 m0, s12
	s_add_u32 s28, s10, 0x11420100
	global_load_lds_dwordx4 v[56:57], off
	v_lshl_add_u64 v[56:57], v[68:69], 0, s[4:5]
	s_mov_b32 m0, s14
	s_addc_u32 s29, s11, 0
	s_add_i32 s15, s22, 0x18000
	global_load_lds_dwordx4 v[56:57], off
	s_mov_b32 m0, s15
	s_add_i32 s16, s22, 0x1a000
	global_load_lds_dwordx4 v62, s[28:29]
	s_mov_b32 m0, s16
	v_and_b32_e32 v57, 48, v58
	global_load_lds_dwordx4 v64, s[28:29]
	s_add_u32 s28, s10, 0x11420180
	s_addc_u32 s29, s11, 0
	s_add_i32 s17, s22, 0x1c000
	s_mov_b32 m0, s17
	s_add_i32 s18, s22, 0x1e000
	global_load_lds_dwordx4 v62, s[28:29]
	s_mov_b32 m0, s18
	v_lshlrev_b32_e32 v58, 2, v58
	global_load_lds_dwordx4 v64, s[28:29]
	v_lshlrev_b32_e32 v56, 6, v59
	v_and_b32_e32 v58, 32, v58
	v_bitop3_b32 v56, v56, v58, v57 bitop3:0x36
	v_and_b32_e32 v57, 0xfffffc00, v71
	v_add3_u32 v65, 0, v56, v57
	v_mov_b32_e32 v71, v65
	ds_read_b128 v[56:59], v71
	ds_read_b128 v[80:83], v71 offset:2048
	s_waitcnt lgkmcnt(0)
	v_mfma_f32_16x16x32_bf16 v[84:87], v[56:59], v[76:79], 0
	ds_read_b128 v[56:59], v71 offset:4096
	ds_read_b128 v[88:91], v71 offset:6144
	ds_read_b128 v[96:99], v71 offset:8192
	ds_read_b128 v[100:103], v71 offset:10240
	s_waitcnt lgkmcnt(0)
	v_mfma_f32_16x16x32_bf16 v[92:95], v[56:59], v[76:79], 0
	v_lshlrev_b32_e32 v56, 9, v104
	ds_read_b128 v[104:107], v71 offset:12288
	v_lshlrev_b32_e32 v57, 9, v108
	ds_read_b128 v[108:111], v71 offset:14336
	ds_read_b128 v[112:115], v71 offset:32768
	ds_read_b128 v[116:119], v71 offset:34816
	ds_read_b128 v[120:123], v71 offset:36864
	ds_read_b128 v[124:127], v71 offset:38912
	ds_read_b128 v[128:131], v71 offset:40960
	ds_read_b128 v[132:135], v71 offset:43008
	ds_read_b128 v[136:139], v71 offset:45056
	ds_read_b128 v[140:143], v71 offset:47104
	v_mfma_f32_16x16x32_bf16 v[80:83], v[80:83], v[76:79], 0
	v_sub_u32_e32 v56, v62, v56
	v_mov_b32_e32 v241, v56
	v_sub_u32_e32 v58, v64, v57
	v_mfma_f32_16x16x32_bf16 v[88:91], v[88:91], v[76:79], 0
	v_mfma_f32_16x16x32_bf16 v[96:99], v[96:99], v[76:79], 0
	v_mfma_f32_16x16x32_bf16 v[100:103], v[100:103], v[76:79], 0
	s_waitcnt lgkmcnt(0)
	v_mfma_f32_16x16x32_bf16 v[104:107], v[104:107], v[76:79], 0
	v_mfma_f32_16x16x32_bf16 v[108:111], v[108:111], v[76:79], 0
	ds_read_b128 v[144:147], v71 offset:15360
	ds_read_b128 v[148:151], v71 offset:13312
	ds_read_b128 v[152:155], v71 offset:11264
	ds_read_b128 v[156:159], v71 offset:9216
	ds_read_b128 v[160:163], v71 offset:7168
	ds_read_b128 v[164:167], v71 offset:5120
	ds_read_b128 v[168:171], v71 offset:3072
	ds_read_b128 v[172:175], v71 offset:1024
	v_mfma_f32_16x16x32_bf16 v[112:115], v[112:115], v[76:79], 0
	v_mfma_f32_16x16x32_bf16 v[116:119], v[116:119], v[76:79], 0
	v_mfma_f32_16x16x32_bf16 v[120:123], v[120:123], v[76:79], 0
	v_mfma_f32_16x16x32_bf16 v[124:127], v[124:127], v[76:79], 0
	v_mfma_f32_16x16x32_bf16 v[128:131], v[128:131], v[76:79], 0
	v_mfma_f32_16x16x32_bf16 v[132:135], v[132:135], v[76:79], 0
	v_mfma_f32_16x16x32_bf16 v[136:139], v[136:139], v[76:79], 0
	v_mfma_f32_16x16x32_bf16 v[76:79], v[140:143], v[76:79], 0
	s_waitcnt lgkmcnt(0)
	v_mfma_f32_16x16x32_bf16 v[84:87], v[172:175], v[72:75], v[84:87]
	v_mfma_f32_16x16x32_bf16 v[80:83], v[168:171], v[72:75], v[80:83]
	v_mfma_f32_16x16x32_bf16 v[92:95], v[164:167], v[72:75], v[92:95]
	v_mfma_f32_16x16x32_bf16 v[88:91], v[160:163], v[72:75], v[88:91]
	v_mfma_f32_16x16x32_bf16 v[96:99], v[156:159], v[72:75], v[96:99]
	v_mfma_f32_16x16x32_bf16 v[100:103], v[152:155], v[72:75], v[100:103]
	ds_read_b128 v[140:143], v71 offset:33792
	ds_read_b128 v[152:155], v71 offset:35840
	ds_read_b128 v[156:159], v71 offset:37888
	ds_read_b128 v[160:163], v71 offset:39936
	v_mfma_f32_16x16x32_bf16 v[104:107], v[148:151], v[72:75], v[104:107]
	ds_read_b128 v[148:151], v71 offset:41984
	ds_read_b128 v[164:167], v71 offset:44032
	ds_read_b128 v[168:171], v71 offset:46080
	ds_read_b128 v[172:175], v71 offset:48128
	v_mfma_f32_16x16x32_bf16 v[108:111], v[144:147], v[72:75], v[108:111]
	s_waitcnt lgkmcnt(0)
	v_mfma_f32_16x16x32_bf16 v[112:115], v[140:143], v[72:75], v[112:115]
	v_mfma_f32_16x16x32_bf16 v[116:119], v[152:155], v[72:75], v[116:119]
	v_mfma_f32_16x16x32_bf16 v[120:123], v[156:159], v[72:75], v[120:123]
	v_mfma_f32_16x16x32_bf16 v[124:127], v[160:163], v[72:75], v[124:127]
	v_mfma_f32_16x16x32_bf16 v[128:131], v[148:151], v[72:75], v[128:131]
	ds_read_b128 v[140:143], v71 offset:30720
	ds_read_b128 v[144:147], v71 offset:28672
	ds_read_b128 v[148:151], v71 offset:26624
	ds_read_b128 v[152:155], v71 offset:24576
	v_mfma_f32_16x16x32_bf16 v[132:135], v[164:167], v[72:75], v[132:135]
	v_mfma_f32_16x16x32_bf16 v[136:139], v[168:171], v[72:75], v[136:139]
	ds_read_b128 v[156:159], v71 offset:22528
	ds_read_b128 v[160:163], v71 offset:20480
	ds_read_b128 v[164:167], v71 offset:18432
	ds_read_b128 v[168:171], v71 offset:16384
	v_mfma_f32_16x16x32_bf16 v[72:75], v[172:175], v[72:75], v[76:79]
	s_waitcnt lgkmcnt(0)
	v_mfma_f32_16x16x32_bf16 v[76:79], v[168:171], v[52:55], v[84:87]
	v_mfma_f32_16x16x32_bf16 v[80:83], v[164:167], v[52:55], v[80:83]
	v_mfma_f32_16x16x32_bf16 v[84:87], v[160:163], v[52:55], v[92:95]
	v_mfma_f32_16x16x32_bf16 v[88:91], v[156:159], v[52:55], v[88:91]
	v_mfma_f32_16x16x32_bf16 v[92:95], v[152:155], v[52:55], v[96:99]
	v_mfma_f32_16x16x32_bf16 v[96:99], v[148:151], v[52:55], v[100:103]
	s_nop 2
	ds_read_b128 v[100:103], v71 offset:49152
	ds_read_b128 v[148:151], v71 offset:51200
	ds_read_b128 v[152:155], v71 offset:53248
	ds_read_b128 v[156:159], v71 offset:55296
	v_mfma_f32_16x16x32_bf16 v[104:107], v[144:147], v[52:55], v[104:107]
	ds_read_b128 v[144:147], v71 offset:57344
	ds_read_b128 v[160:163], v71 offset:59392
	ds_read_b128 v[164:167], v71 offset:61440
	ds_read_b128 v[168:171], v71 offset:63488
	v_mfma_f32_16x16x32_bf16 v[108:111], v[140:143], v[52:55], v[108:111]
	s_waitcnt lgkmcnt(0)
	v_mfma_f32_16x16x32_bf16 v[100:103], v[100:103], v[52:55], v[112:115]
	v_mfma_f32_16x16x32_bf16 v[112:115], v[148:151], v[52:55], v[116:119]
	v_mfma_f32_16x16x32_bf16 v[116:119], v[152:155], v[52:55], v[120:123]
	v_mfma_f32_16x16x32_bf16 v[120:123], v[156:159], v[52:55], v[124:127]
	v_mfma_f32_16x16x32_bf16 v[124:127], v[144:147], v[52:55], v[128:131]
	v_mfma_f32_16x16x32_bf16 v[128:131], v[160:163], v[52:55], v[132:135]
	s_nop 2
	ds_read_b128 v[132:135], v71 offset:31744
	ds_read_b128 v[140:143], v71 offset:29696
	ds_read_b128 v[144:147], v71 offset:27648
	ds_read_b128 v[148:151], v71 offset:25600
	v_mfma_f32_16x16x32_bf16 v[136:139], v[164:167], v[52:55], v[136:139]
	ds_read_b128 v[152:155], v71 offset:23552
	ds_read_b128 v[156:159], v71 offset:21504
	ds_read_b128 v[160:163], v71 offset:19456
	ds_read_b128 v[164:167], v71 offset:17408
	v_mfma_f32_16x16x32_bf16 v[52:55], v[168:171], v[52:55], v[72:75]
	s_waitcnt lgkmcnt(0)
	v_mfma_f32_16x16x32_bf16 v[72:75], v[164:167], v[48:51], v[76:79]
	v_mfma_f32_16x16x32_bf16 v[76:79], v[160:163], v[48:51], v[80:83]
	v_mfma_f32_16x16x32_bf16 v[80:83], v[156:159], v[48:51], v[84:87]
	v_mfma_f32_16x16x32_bf16 v[84:87], v[152:155], v[48:51], v[88:91]
	v_mfma_f32_16x16x32_bf16 v[88:91], v[148:151], v[48:51], v[92:95]
	v_mfma_f32_16x16x32_bf16 v[92:95], v[144:147], v[48:51], v[96:99]
	s_nop 2
	ds_read_b128 v[96:99], v71 offset:50176
	ds_read_b128 v[144:147], v71 offset:52224
	ds_read_b128 v[148:151], v71 offset:54272
	ds_read_b128 v[152:155], v71 offset:56320
	v_mfma_f32_16x16x32_bf16 v[104:107], v[140:143], v[48:51], v[104:107]
	ds_read_b128 v[140:143], v71 offset:58368
	ds_read_b128 v[156:159], v71 offset:60416
	ds_read_b128 v[160:163], v71 offset:62464
	ds_read_b128 v[164:167], v71 offset:64512
	v_mfma_f32_16x16x32_bf16 v[108:111], v[132:135], v[48:51], v[108:111]
	s_waitcnt lgkmcnt(0)
	v_mfma_f32_16x16x32_bf16 v[96:99], v[96:99], v[48:51], v[100:103]
	v_mfma_f32_16x16x32_bf16 v[100:103], v[144:147], v[48:51], v[112:115]
	v_mfma_f32_16x16x32_bf16 v[112:115], v[148:151], v[48:51], v[116:119]
	v_mfma_f32_16x16x32_bf16 v[116:119], v[152:155], v[48:51], v[120:123]
	v_mfma_f32_16x16x32_bf16 v[120:123], v[140:143], v[48:51], v[124:127]
	v_mfma_f32_16x16x32_bf16 v[124:127], v[156:159], v[48:51], v[128:131]
	v_mfma_f32_16x16x32_bf16 v[128:131], v[160:163], v[48:51], v[136:139]
	v_mfma_f32_16x16x32_bf16 v[50:53], v[164:167], v[48:51], v[52:55]
	s_waitcnt vmcnt(0)
	s_waitcnt vmcnt(0)
	s_barrier
	v_add_u32_e32 v48, 0x10000, v65
	v_mov_b32_e32 v49, v48
	ds_read_b128 v[132:135], v49
	ds_read_b128 v[136:139], v49 offset:2048
	s_waitcnt lgkmcnt(0)
	v_mfma_f32_16x16x32_bf16 v[72:75], v[132:135], v[44:47], v[72:75]
	ds_read_b128 v[132:135], v49 offset:4096
	v_mfma_f32_16x16x32_bf16 v[76:79], v[136:139], v[44:47], v[76:79]
	ds_read_b128 v[136:139], v49 offset:6144
	s_waitcnt lgkmcnt(0)
	v_mfma_f32_16x16x32_bf16 v[80:83], v[132:135], v[44:47], v[80:83]
	ds_read_b128 v[132:135], v49 offset:8192
	v_mfma_f32_16x16x32_bf16 v[84:87], v[136:139], v[44:47], v[84:87]
	ds_read_b128 v[136:139], v49 offset:10240
	s_waitcnt lgkmcnt(0)
	v_mfma_f32_16x16x32_bf16 v[88:91], v[132:135], v[44:47], v[88:91]
	ds_read_b128 v[132:135], v49 offset:12288
	ds_read_b128 v[140:143], v49 offset:14336
	v_mfma_f32_16x16x32_bf16 v[92:95], v[136:139], v[44:47], v[92:95]
	ds_read_b128 v[136:139], v49 offset:32768
	ds_read_b128 v[144:147], v49 offset:34816
	ds_read_b128 v[148:151], v49 offset:36864
	ds_read_b128 v[152:155], v49 offset:38912
	s_waitcnt lgkmcnt(0)
	v_mfma_f32_16x16x32_bf16 v[104:107], v[132:135], v[44:47], v[104:107]
	ds_read_b128 v[132:135], v49 offset:40960
	ds_read_b128 v[156:159], v49 offset:43008
	ds_read_b128 v[160:163], v49 offset:45056
	ds_read_b128 v[164:167], v49 offset:47104
	v_mfma_f32_16x16x32_bf16 v[108:111], v[140:143], v[44:47], v[108:111]
	s_add_u32 s100, s10, 0x11400200
	s_addc_u32 s101, s11, 0
	s_mov_b32 m0, s22
	s_nop 0
	global_load_lds_dwordx4 v240, s[100:101]
	v_mfma_f32_16x16x32_bf16 v[96:99], v[136:139], v[44:47], v[96:99]
	v_mfma_f32_16x16x32_bf16 v[100:103], v[144:147], v[44:47], v[100:103]
	v_mfma_f32_16x16x32_bf16 v[112:115], v[148:151], v[44:47], v[112:115]
	v_mfma_f32_16x16x32_bf16 v[116:119], v[152:155], v[44:47], v[116:119]
	s_waitcnt lgkmcnt(0)
	v_mfma_f32_16x16x32_bf16 v[120:123], v[132:135], v[44:47], v[120:123]
	ds_read_b128 v[132:135], v49 offset:15360
	ds_read_b128 v[136:139], v49 offset:13312
	ds_read_b128 v[140:143], v49 offset:11264
	ds_read_b128 v[144:147], v49 offset:9216
	v_mfma_f32_16x16x32_bf16 v[124:127], v[156:159], v[44:47], v[124:127]
	v_mfma_f32_16x16x32_bf16 v[128:131], v[160:163], v[44:47], v[128:131]
	ds_read_b128 v[148:151], v49 offset:7168
	ds_read_b128 v[152:155], v49 offset:5120
	ds_read_b128 v[156:159], v49 offset:3072
	ds_read_b128 v[160:163], v49 offset:1024
	v_mfma_f32_16x16x32_bf16 v[44:47], v[164:167], v[44:47], v[50:53]
	s_add_u32 s100, s10, 0x11410200
	s_addc_u32 s101, s11, 0
	s_mov_b32 m0, s21
	s_nop 0
	global_load_lds_dwordx4 v240, s[100:101]
	s_waitcnt lgkmcnt(0)
	v_mfma_f32_16x16x32_bf16 v[50:53], v[160:163], v[40:43], v[72:75]
	v_mfma_f32_16x16x32_bf16 v[72:75], v[156:159], v[40:43], v[76:79]
	v_mfma_f32_16x16x32_bf16 v[76:79], v[152:155], v[40:43], v[80:83]
	v_mfma_f32_16x16x32_bf16 v[80:83], v[148:151], v[40:43], v[84:87]
	v_mfma_f32_16x16x32_bf16 v[84:87], v[144:147], v[40:43], v[88:91]
	v_mfma_f32_16x16x32_bf16 v[88:91], v[140:143], v[40:43], v[92:95]
	s_nop 2
	ds_read_b128 v[92:95], v49 offset:33792
	ds_read_b128 v[140:143], v49 offset:35840
	ds_read_b128 v[144:147], v49 offset:37888
	ds_read_b128 v[148:151], v49 offset:39936
	v_mfma_f32_16x16x32_bf16 v[104:107], v[136:139], v[40:43], v[104:107]
	ds_read_b128 v[136:139], v49 offset:41984
	ds_read_b128 v[152:155], v49 offset:44032
	ds_read_b128 v[156:159], v49 offset:46080
	ds_read_b128 v[160:163], v49 offset:48128
	v_mfma_f32_16x16x32_bf16 v[108:111], v[132:135], v[40:43], v[108:111]
	s_add_u32 s100, s10, 0x11400280
	s_addc_u32 s101, s11, 0
	s_mov_b32 m0, s20
	s_nop 0
	global_load_lds_dwordx4 v240, s[100:101]
	s_waitcnt lgkmcnt(0)
	v_mfma_f32_16x16x32_bf16 v[92:95], v[92:95], v[40:43], v[96:99]
	v_mfma_f32_16x16x32_bf16 v[96:99], v[140:143], v[40:43], v[100:103]
	v_mfma_f32_16x16x32_bf16 v[100:103], v[144:147], v[40:43], v[112:115]
	v_mfma_f32_16x16x32_bf16 v[112:115], v[148:151], v[40:43], v[116:119]
	v_mfma_f32_16x16x32_bf16 v[116:119], v[136:139], v[40:43], v[120:123]
	v_mfma_f32_16x16x32_bf16 v[120:123], v[152:155], v[40:43], v[124:127]
	s_nop 2
	ds_read_b128 v[124:127], v49 offset:30720
	ds_read_b128 v[132:135], v49 offset:28672
	ds_read_b128 v[136:139], v49 offset:26624
	ds_read_b128 v[140:143], v49 offset:24576
	v_mfma_f32_16x16x32_bf16 v[128:131], v[156:159], v[40:43], v[128:131]
	ds_read_b128 v[144:147], v49 offset:22528
	ds_read_b128 v[148:151], v49 offset:20480
	ds_read_b128 v[152:155], v49 offset:18432
	ds_read_b128 v[156:159], v49 offset:16384
	v_mfma_f32_16x16x32_bf16 v[40:43], v[160:163], v[40:43], v[44:47]
	s_add_u32 s100, s10, 0x11410280
	s_addc_u32 s101, s11, 0
	s_mov_b32 m0, s23
	s_nop 0
	global_load_lds_dwordx4 v240, s[100:101]
	s_waitcnt lgkmcnt(0)
	v_mfma_f32_16x16x32_bf16 v[44:47], v[156:159], v[36:39], v[50:53]
	v_mfma_f32_16x16x32_bf16 v[50:53], v[152:155], v[36:39], v[72:75]
	v_mfma_f32_16x16x32_bf16 v[72:75], v[148:151], v[36:39], v[76:79]
	v_mfma_f32_16x16x32_bf16 v[76:79], v[144:147], v[36:39], v[80:83]
	v_mfma_f32_16x16x32_bf16 v[80:83], v[140:143], v[36:39], v[84:87]
	v_mfma_f32_16x16x32_bf16 v[84:87], v[136:139], v[36:39], v[88:91]
	s_nop 2
	ds_read_b128 v[88:91], v49 offset:49152
	ds_read_b128 v[136:139], v49 offset:51200
	ds_read_b128 v[140:143], v49 offset:53248
	ds_read_b128 v[144:147], v49 offset:55296
	v_mfma_f32_16x16x32_bf16 v[104:107], v[132:135], v[36:39], v[104:107]
	ds_read_b128 v[132:135], v49 offset:57344
	ds_read_b128 v[148:151], v49 offset:59392
	ds_read_b128 v[152:155], v49 offset:61440
	ds_read_b128 v[156:159], v49 offset:63488
	v_mfma_f32_16x16x32_bf16 v[108:111], v[124:127], v[36:39], v[108:111]
	s_add_u32 s100, s10, 0x11420200
	s_addc_u32 s101, s11, 0
	s_mov_b32 m0, s24
	s_nop 0
	global_load_lds_dwordx4 v240, s[100:101]
	s_waitcnt lgkmcnt(0)
	v_mfma_f32_16x16x32_bf16 v[88:91], v[88:91], v[36:39], v[92:95]
	v_mfma_f32_16x16x32_bf16 v[92:95], v[136:139], v[36:39], v[96:99]
	v_mfma_f32_16x16x32_bf16 v[96:99], v[140:143], v[36:39], v[100:103]
	v_mfma_f32_16x16x32_bf16 v[100:103], v[144:147], v[36:39], v[112:115]
	v_mfma_f32_16x16x32_bf16 v[112:115], v[132:135], v[36:39], v[116:119]
	v_mfma_f32_16x16x32_bf16 v[116:119], v[148:151], v[36:39], v[120:123]
	s_nop 2
	ds_read_b128 v[120:123], v49 offset:31744
	ds_read_b128 v[124:127], v49 offset:29696
	ds_read_b128 v[132:135], v49 offset:27648
	ds_read_b128 v[136:139], v49 offset:25600
	v_mfma_f32_16x16x32_bf16 v[128:131], v[152:155], v[36:39], v[128:131]
	ds_read_b128 v[140:143], v49 offset:23552
	ds_read_b128 v[144:147], v49 offset:21504
	ds_read_b128 v[148:151], v49 offset:19456
	ds_read_b128 v[152:155], v49 offset:17408
	v_mfma_f32_16x16x32_bf16 v[36:39], v[156:159], v[36:39], v[40:43]
	s_add_u32 s100, s10, 0x11430200
	s_addc_u32 s101, s11, 0
	s_mov_b32 m0, s25
	s_nop 0
	global_load_lds_dwordx4 v240, s[100:101]
	s_waitcnt lgkmcnt(0)
	v_mfma_f32_16x16x32_bf16 v[40:43], v[152:155], v[32:35], v[44:47]
	v_mfma_f32_16x16x32_bf16 v[44:47], v[148:151], v[32:35], v[50:53]
	v_mfma_f32_16x16x32_bf16 v[50:53], v[144:147], v[32:35], v[72:75]
	v_mfma_f32_16x16x32_bf16 v[72:75], v[140:143], v[32:35], v[76:79]
	v_mfma_f32_16x16x32_bf16 v[76:79], v[136:139], v[32:35], v[80:83]
	v_mfma_f32_16x16x32_bf16 v[80:83], v[132:135], v[32:35], v[84:87]
	s_nop 2
	ds_read_b128 v[84:87], v49 offset:50176
	ds_read_b128 v[132:135], v49 offset:52224
	ds_read_b128 v[136:139], v49 offset:54272
	ds_read_b128 v[140:143], v49 offset:56320
	v_mfma_f32_16x16x32_bf16 v[104:107], v[124:127], v[32:35], v[104:107]
	ds_read_b128 v[124:127], v49 offset:58368
	ds_read_b128 v[144:147], v49 offset:60416
	ds_read_b128 v[148:151], v49 offset:62464
	ds_read_b128 v[152:155], v49 offset:64512
	v_mfma_f32_16x16x32_bf16 v[108:111], v[120:123], v[32:35], v[108:111]
	s_add_u32 s100, s10, 0x11420280
	s_addc_u32 s101, s11, 0
	s_mov_b32 m0, s26
	s_nop 0
	global_load_lds_dwordx4 v240, s[100:101]
	s_waitcnt lgkmcnt(0)
	v_mfma_f32_16x16x32_bf16 v[84:87], v[84:87], v[32:35], v[88:91]
	v_mfma_f32_16x16x32_bf16 v[88:91], v[132:135], v[32:35], v[92:95]
	v_mfma_f32_16x16x32_bf16 v[92:95], v[136:139], v[32:35], v[96:99]
	v_mfma_f32_16x16x32_bf16 v[96:99], v[140:143], v[32:35], v[100:103]
	v_mfma_f32_16x16x32_bf16 v[100:103], v[124:127], v[32:35], v[112:115]
	v_mfma_f32_16x16x32_bf16 v[112:115], v[144:147], v[32:35], v[116:119]
	v_mfma_f32_16x16x32_bf16 v[116:119], v[148:151], v[32:35], v[128:131]
	v_mfma_f32_16x16x32_bf16 v[32:35], v[152:155], v[32:35], v[36:39]
	s_add_u32 s100, s10, 0x11430280
	s_addc_u32 s101, s11, 0
	s_mov_b32 m0, s27
	s_nop 0
	global_load_lds_dwordx4 v240, s[100:101]
	s_nop 0
	s_waitcnt vmcnt(0)
	s_waitcnt vmcnt(0)
	s_barrier
	v_mov_b32_e32 v49, v65
	ds_read_b128 v[36:39], v49
	ds_read_b128 v[66:69], v49 offset:2048
	s_waitcnt lgkmcnt(0)
	v_mfma_f32_16x16x32_bf16 v[36:39], v[36:39], v[28:31], v[40:43]
	s_nop 2
	ds_read_b128 v[40:43], v49 offset:4096
	v_mfma_f32_16x16x32_bf16 v[44:47], v[66:69], v[28:31], v[44:47]
	ds_read_b128 v[66:69], v49 offset:6144
	s_waitcnt lgkmcnt(0)
	v_mfma_f32_16x16x32_bf16 v[40:43], v[40:43], v[28:31], v[50:53]
	s_nop 2
	ds_read_b128 v[50:53], v49 offset:8192
	v_mfma_f32_16x16x32_bf16 v[66:69], v[66:69], v[28:31], v[72:75]
	s_nop 2
	ds_read_b128 v[72:75], v49 offset:10240
	s_waitcnt lgkmcnt(0)
	v_mfma_f32_16x16x32_bf16 v[50:53], v[50:53], v[28:31], v[76:79]
	s_nop 2
	ds_read_b128 v[76:79], v49 offset:12288
	ds_read_b128 v[120:123], v49 offset:14336
	v_mfma_f32_16x16x32_bf16 v[72:75], v[72:75], v[28:31], v[80:83]
	s_nop 2
	ds_read_b128 v[80:83], v49 offset:32768
	ds_read_b128 v[124:127], v49 offset:34816
	ds_read_b128 v[128:131], v49 offset:36864
	ds_read_b128 v[132:135], v49 offset:38912
	s_waitcnt lgkmcnt(0)
	v_mfma_f32_16x16x32_bf16 v[76:79], v[76:79], v[28:31], v[104:107]
	s_nop 2
	ds_read_b128 v[104:107], v49 offset:40960
	ds_read_b128 v[136:139], v49 offset:43008
	ds_read_b128 v[140:143], v49 offset:45056
	ds_read_b128 v[144:147], v49 offset:47104
	v_mfma_f32_16x16x32_bf16 v[108:111], v[120:123], v[28:31], v[108:111]
	s_add_u32 s100, s10, 0x11400300
	s_addc_u32 s101, s11, 0
	s_mov_b32 m0, s19
	s_nop 0
	global_load_lds_dwordx4 v240, s[100:101]
	v_mfma_f32_16x16x32_bf16 v[80:83], v[80:83], v[28:31], v[84:87]
	v_mfma_f32_16x16x32_bf16 v[84:87], v[124:127], v[28:31], v[88:91]
	v_mfma_f32_16x16x32_bf16 v[88:91], v[128:131], v[28:31], v[92:95]
	v_mfma_f32_16x16x32_bf16 v[92:95], v[132:135], v[28:31], v[96:99]
	s_waitcnt lgkmcnt(0)
	v_mfma_f32_16x16x32_bf16 v[96:99], v[104:107], v[28:31], v[100:103]
	v_mfma_f32_16x16x32_bf16 v[100:103], v[136:139], v[28:31], v[112:115]
	ds_read_b128 v[104:107], v49 offset:15360
	s_nop 1
	ds_read_b128 v[112:115], v49 offset:13312
	ds_read_b128 v[120:123], v49 offset:11264
	ds_read_b128 v[124:127], v49 offset:9216
	v_mfma_f32_16x16x32_bf16 v[116:119], v[140:143], v[28:31], v[116:119]
	ds_read_b128 v[128:131], v49 offset:7168
	ds_read_b128 v[132:135], v49 offset:5120
	ds_read_b128 v[136:139], v49 offset:3072
	ds_read_b128 v[140:143], v49 offset:1024
	v_mfma_f32_16x16x32_bf16 v[28:31], v[144:147], v[28:31], v[32:35]
	s_add_u32 s100, s10, 0x11410300
	s_addc_u32 s101, s11, 0
	s_mov_b32 m0, s13
	s_nop 0
	global_load_lds_dwordx4 v240, s[100:101]
	s_waitcnt lgkmcnt(0)
	v_mfma_f32_16x16x32_bf16 v[32:35], v[140:143], v[24:27], v[36:39]
	v_mfma_f32_16x16x32_bf16 v[36:39], v[136:139], v[24:27], v[44:47]
	v_mfma_f32_16x16x32_bf16 v[40:43], v[132:135], v[24:27], v[40:43]
	v_mfma_f32_16x16x32_bf16 v[44:47], v[128:131], v[24:27], v[66:69]
	v_mfma_f32_16x16x32_bf16 v[50:53], v[124:127], v[24:27], v[50:53]
	v_mfma_f32_16x16x32_bf16 v[66:69], v[120:123], v[24:27], v[72:75]
	s_nop 2
	ds_read_b128 v[72:75], v49 offset:33792
	ds_read_b128 v[120:123], v49 offset:35840
	ds_read_b128 v[124:127], v49 offset:37888
	ds_read_b128 v[128:131], v49 offset:39936
	v_mfma_f32_16x16x32_bf16 v[76:79], v[112:115], v[24:27], v[76:79]
	ds_read_b128 v[112:115], v49 offset:41984
	ds_read_b128 v[132:135], v49 offset:44032
	ds_read_b128 v[136:139], v49 offset:46080
	ds_read_b128 v[140:143], v49 offset:48128
	v_mfma_f32_16x16x32_bf16 v[104:107], v[104:107], v[24:27], v[108:111]
	s_add_u32 s100, s10, 0x11400380
	s_addc_u32 s101, s11, 0
	s_mov_b32 m0, s12
	s_nop 0
	global_load_lds_dwordx4 v240, s[100:101]
	s_waitcnt lgkmcnt(0)
	v_mfma_f32_16x16x32_bf16 v[72:75], v[72:75], v[24:27], v[80:83]
	v_mfma_f32_16x16x32_bf16 v[80:83], v[120:123], v[24:27], v[84:87]
	v_mfma_f32_16x16x32_bf16 v[84:87], v[124:127], v[24:27], v[88:91]
	v_mfma_f32_16x16x32_bf16 v[88:91], v[128:131], v[24:27], v[92:95]
	v_mfma_f32_16x16x32_bf16 v[92:95], v[112:115], v[24:27], v[96:99]
	v_mfma_f32_16x16x32_bf16 v[96:99], v[132:135], v[24:27], v[100:103]
	s_nop 2
	ds_read_b128 v[100:103], v49 offset:30720
	ds_read_b128 v[108:111], v49 offset:28672
	ds_read_b128 v[112:115], v49 offset:26624
	ds_read_b128 v[120:123], v49 offset:24576
	v_mfma_f32_16x16x32_bf16 v[116:119], v[136:139], v[24:27], v[116:119]
	ds_read_b128 v[124:127], v49 offset:22528
	ds_read_b128 v[128:131], v49 offset:20480
	ds_read_b128 v[132:135], v49 offset:18432
	ds_read_b128 v[136:139], v49 offset:16384
	v_mfma_f32_16x16x32_bf16 v[24:27], v[140:143], v[24:27], v[28:31]
	s_add_u32 s100, s10, 0x11410380
	s_addc_u32 s101, s11, 0
	s_mov_b32 m0, s14
	s_nop 0
	global_load_lds_dwordx4 v240, s[100:101]
	s_waitcnt lgkmcnt(0)
	v_mfma_f32_16x16x32_bf16 v[28:31], v[136:139], v[20:23], v[32:35]
	v_mfma_f32_16x16x32_bf16 v[32:35], v[132:135], v[20:23], v[36:39]
	v_mfma_f32_16x16x32_bf16 v[36:39], v[128:131], v[20:23], v[40:43]
	v_mfma_f32_16x16x32_bf16 v[40:43], v[124:127], v[20:23], v[44:47]
	v_mfma_f32_16x16x32_bf16 v[44:47], v[120:123], v[20:23], v[50:53]
	v_mfma_f32_16x16x32_bf16 v[50:53], v[112:115], v[20:23], v[66:69]
	s_nop 2
	ds_read_b128 v[66:69], v49 offset:49152
	ds_read_b128 v[112:115], v49 offset:51200
	ds_read_b128 v[120:123], v49 offset:53248
	ds_read_b128 v[124:127], v49 offset:55296
	v_mfma_f32_16x16x32_bf16 v[76:79], v[108:111], v[20:23], v[76:79]
	ds_read_b128 v[108:111], v49 offset:57344
	ds_read_b128 v[128:131], v49 offset:59392
	ds_read_b128 v[132:135], v49 offset:61440
	ds_read_b128 v[136:139], v49 offset:63488
	v_mfma_f32_16x16x32_bf16 v[100:103], v[100:103], v[20:23], v[104:107]
	s_add_u32 s100, s10, 0x11420300
	s_addc_u32 s101, s11, 0
	s_mov_b32 m0, s15
	s_nop 0
	global_load_lds_dwordx4 v240, s[100:101]
	s_waitcnt lgkmcnt(0)
	v_mfma_f32_16x16x32_bf16 v[66:69], v[66:69], v[20:23], v[72:75]
	v_mfma_f32_16x16x32_bf16 v[72:75], v[112:115], v[20:23], v[80:83]
	v_mfma_f32_16x16x32_bf16 v[80:83], v[120:123], v[20:23], v[84:87]
	v_mfma_f32_16x16x32_bf16 v[84:87], v[124:127], v[20:23], v[88:91]
	v_mfma_f32_16x16x32_bf16 v[88:91], v[108:111], v[20:23], v[92:95]
	v_mfma_f32_16x16x32_bf16 v[92:95], v[128:131], v[20:23], v[96:99]
	s_nop 2
	ds_read_b128 v[96:99], v49 offset:31744
	ds_read_b128 v[104:107], v49 offset:29696
	ds_read_b128 v[108:111], v49 offset:27648
	ds_read_b128 v[112:115], v49 offset:25600
	v_mfma_f32_16x16x32_bf16 v[116:119], v[132:135], v[20:23], v[116:119]
	ds_read_b128 v[120:123], v49 offset:23552
	ds_read_b128 v[124:127], v49 offset:21504
	ds_read_b128 v[128:131], v49 offset:19456
	ds_read_b128 v[132:135], v49 offset:17408
	v_mfma_f32_16x16x32_bf16 v[20:23], v[136:139], v[20:23], v[24:27]
	s_add_u32 s100, s10, 0x11430300
	s_addc_u32 s101, s11, 0
	s_mov_b32 m0, s16
	s_nop 0
	global_load_lds_dwordx4 v240, s[100:101]
	s_waitcnt lgkmcnt(0)
	v_mfma_f32_16x16x32_bf16 v[24:27], v[132:135], v[16:19], v[28:31]
	v_mfma_f32_16x16x32_bf16 v[28:31], v[128:131], v[16:19], v[32:35]
	v_mfma_f32_16x16x32_bf16 v[32:35], v[124:127], v[16:19], v[36:39]
	v_mfma_f32_16x16x32_bf16 v[36:39], v[120:123], v[16:19], v[40:43]
	v_mfma_f32_16x16x32_bf16 v[40:43], v[112:115], v[16:19], v[44:47]
	v_mfma_f32_16x16x32_bf16 v[50:53], v[108:111], v[16:19], v[50:53]
	s_nop 1
	ds_read_b128 v[44:47], v49 offset:50176
	ds_read_b128 v[108:111], v49 offset:52224
	ds_read_b128 v[112:115], v49 offset:54272
	ds_read_b128 v[120:123], v49 offset:56320
	v_mfma_f32_16x16x32_bf16 v[76:79], v[104:107], v[16:19], v[76:79]
	ds_read_b128 v[104:107], v49 offset:58368
	ds_read_b128 v[124:127], v49 offset:60416
	ds_read_b128 v[128:131], v49 offset:62464
	ds_read_b128 v[132:135], v49 offset:64512
	v_mfma_f32_16x16x32_bf16 v[96:99], v[96:99], v[16:19], v[100:103]
	s_add_u32 s100, s10, 0x11420380
	s_addc_u32 s101, s11, 0
	s_mov_b32 m0, s17
	s_nop 0
	global_load_lds_dwordx4 v240, s[100:101]
	s_waitcnt lgkmcnt(0)
	v_mfma_f32_16x16x32_bf16 v[66:69], v[44:47], v[16:19], v[66:69]
	v_mfma_f32_16x16x32_bf16 v[72:75], v[108:111], v[16:19], v[72:75]
	v_mfma_f32_16x16x32_bf16 v[80:83], v[112:115], v[16:19], v[80:83]
	v_mfma_f32_16x16x32_bf16 v[84:87], v[120:123], v[16:19], v[84:87]
	v_mfma_f32_16x16x32_bf16 v[88:91], v[104:107], v[16:19], v[88:91]
	v_mfma_f32_16x16x32_bf16 v[92:95], v[124:127], v[16:19], v[92:95]
	v_mfma_f32_16x16x32_bf16 v[100:103], v[128:131], v[16:19], v[116:119]
	v_mfma_f32_16x16x32_bf16 v[16:19], v[132:135], v[16:19], v[20:23]
	s_add_u32 s100, s10, 0x11430380
	s_addc_u32 s101, s11, 0
	s_mov_b32 m0, s18
	s_nop 0
	global_load_lds_dwordx4 v240, s[100:101]
	s_waitcnt vmcnt(0)
	s_waitcnt vmcnt(0)
	s_barrier
	v_mov_b32_e32 v49, v48
	ds_read_b128 v[20:23], v49
	ds_read_b128 v[104:107], v49 offset:2048
	s_waitcnt lgkmcnt(0)
	v_mfma_f32_16x16x32_bf16 v[20:23], v[20:23], v[12:15], v[24:27]
	s_nop 2
	ds_read_b128 v[24:27], v49 offset:4096
	v_mfma_f32_16x16x32_bf16 v[28:31], v[104:107], v[12:15], v[28:31]
	ds_read_b128 v[104:107], v49 offset:6144
	s_waitcnt lgkmcnt(0)
	v_mfma_f32_16x16x32_bf16 v[24:27], v[24:27], v[12:15], v[32:35]
	s_nop 2
	ds_read_b128 v[32:35], v49 offset:8192
	v_mfma_f32_16x16x32_bf16 v[36:39], v[104:107], v[12:15], v[36:39]
	ds_read_b128 v[104:107], v49 offset:10240
	s_waitcnt lgkmcnt(0)
	v_mfma_f32_16x16x32_bf16 v[32:35], v[32:35], v[12:15], v[40:43]
	s_nop 2
	ds_read_b128 v[40:43], v49 offset:12288
	ds_read_b128 v[108:111], v49 offset:14336
	v_mfma_f32_16x16x32_bf16 v[50:53], v[104:107], v[12:15], v[50:53]
	ds_read_b128 v[104:107], v49 offset:32768
	ds_read_b128 v[112:115], v49 offset:34816
	ds_read_b128 v[116:119], v49 offset:36864
	ds_read_b128 v[120:123], v49 offset:38912
	s_waitcnt lgkmcnt(0)
	v_mfma_f32_16x16x32_bf16 v[40:43], v[40:43], v[12:15], v[76:79]
	s_nop 2
	ds_read_b128 v[76:79], v49 offset:40960
	ds_read_b128 v[124:127], v49 offset:43008
	ds_read_b128 v[128:131], v49 offset:45056
	ds_read_b128 v[132:135], v49 offset:47104
	v_mfma_f32_16x16x32_bf16 v[96:99], v[108:111], v[12:15], v[96:99]
	s_add_u32 s100, s10, 0x11c00000
	s_addc_u32 s101, s11, 0
	s_mov_b32 m0, s22
	s_nop 0
	global_load_lds_dwordx4 v241, s[100:101]
	v_mfma_f32_16x16x32_bf16 v[66:69], v[104:107], v[12:15], v[66:69]
	v_mfma_f32_16x16x32_bf16 v[72:75], v[112:115], v[12:15], v[72:75]
	v_mfma_f32_16x16x32_bf16 v[80:83], v[116:119], v[12:15], v[80:83]
	v_mfma_f32_16x16x32_bf16 v[84:87], v[120:123], v[12:15], v[84:87]
	s_waitcnt lgkmcnt(0)
	v_mfma_f32_16x16x32_bf16 v[76:79], v[76:79], v[12:15], v[88:91]
	v_mfma_f32_16x16x32_bf16 v[88:91], v[124:127], v[12:15], v[92:95]
	s_nop 2
	ds_read_b128 v[92:95], v49 offset:15360
	ds_read_b128 v[104:107], v49 offset:13312
	ds_read_b128 v[108:111], v49 offset:11264
	ds_read_b128 v[112:115], v49 offset:9216
	v_mfma_f32_16x16x32_bf16 v[100:103], v[128:131], v[12:15], v[100:103]
	ds_read_b128 v[116:119], v49 offset:7168
	ds_read_b128 v[120:123], v49 offset:5120
	ds_read_b128 v[124:127], v49 offset:3072
	ds_read_b128 v[128:131], v49 offset:1024
	v_mfma_f32_16x16x32_bf16 v[12:15], v[132:135], v[12:15], v[16:19]
	s_add_u32 s100, s10, 0x11c08000
	s_addc_u32 s101, s11, 0
	s_mov_b32 m0, s21
	s_nop 0
	global_load_lds_dwordx4 v241, s[100:101]
	s_waitcnt lgkmcnt(0)
	v_mfma_f32_16x16x32_bf16 v[16:19], v[128:131], v[8:11], v[20:23]
	v_mfma_f32_16x16x32_bf16 v[20:23], v[124:127], v[8:11], v[28:31]
	v_mfma_f32_16x16x32_bf16 v[24:27], v[120:123], v[8:11], v[24:27]
	v_mfma_f32_16x16x32_bf16 v[28:31], v[116:119], v[8:11], v[36:39]
	v_mfma_f32_16x16x32_bf16 v[32:35], v[112:115], v[8:11], v[32:35]
	v_mfma_f32_16x16x32_bf16 v[36:39], v[108:111], v[8:11], v[50:53]
	s_nop 2
	ds_read_b128 v[50:53], v49 offset:33792
	ds_read_b128 v[108:111], v49 offset:35840
	ds_read_b128 v[112:115], v49 offset:37888
	ds_read_b128 v[116:119], v49 offset:39936
	v_mfma_f32_16x16x32_bf16 v[40:43], v[104:107], v[8:11], v[40:43]
	ds_read_b128 v[104:107], v49 offset:41984
	ds_read_b128 v[120:123], v49 offset:44032
	ds_read_b128 v[124:127], v49 offset:46080
	ds_read_b128 v[128:131], v49 offset:48128
	v_mfma_f32_16x16x32_bf16 v[92:95], v[92:95], v[8:11], v[96:99]
	s_add_u32 s100, s10, 0x11c00080
	s_addc_u32 s101, s11, 0
	s_mov_b32 m0, s20
	s_nop 0
	global_load_lds_dwordx4 v241, s[100:101]
	s_waitcnt lgkmcnt(0)
	v_mfma_f32_16x16x32_bf16 v[50:53], v[50:53], v[8:11], v[66:69]
	v_mfma_f32_16x16x32_bf16 v[66:69], v[108:111], v[8:11], v[72:75]
	v_mfma_f32_16x16x32_bf16 v[72:75], v[112:115], v[8:11], v[80:83]
	v_mfma_f32_16x16x32_bf16 v[80:83], v[116:119], v[8:11], v[84:87]
	v_mfma_f32_16x16x32_bf16 v[76:79], v[104:107], v[8:11], v[76:79]
	v_mfma_f32_16x16x32_bf16 v[84:87], v[120:123], v[8:11], v[88:91]
	s_nop 2
	ds_read_b128 v[88:91], v49 offset:30720
	ds_read_b128 v[96:99], v49 offset:28672
	ds_read_b128 v[104:107], v49 offset:26624
	ds_read_b128 v[108:111], v49 offset:24576
	v_mfma_f32_16x16x32_bf16 v[100:103], v[124:127], v[8:11], v[100:103]
	ds_read_b128 v[112:115], v49 offset:22528
	ds_read_b128 v[116:119], v49 offset:20480
	ds_read_b128 v[120:123], v49 offset:18432
	ds_read_b128 v[124:127], v49 offset:16384
	v_mfma_f32_16x16x32_bf16 v[8:11], v[128:131], v[8:11], v[12:15]
	s_add_u32 s100, s10, 0x11c08080
	s_addc_u32 s101, s11, 0
	s_mov_b32 m0, s23
	s_nop 0
	global_load_lds_dwordx4 v241, s[100:101]
	s_waitcnt lgkmcnt(0)
	v_mfma_f32_16x16x32_bf16 v[12:15], v[124:127], v[4:7], v[16:19]
	v_mfma_f32_16x16x32_bf16 v[16:19], v[120:123], v[4:7], v[20:23]
	v_mfma_f32_16x16x32_bf16 v[20:23], v[116:119], v[4:7], v[24:27]
	v_mfma_f32_16x16x32_bf16 v[24:27], v[112:115], v[4:7], v[28:31]
	v_mfma_f32_16x16x32_bf16 v[28:31], v[108:111], v[4:7], v[32:35]
	v_mfma_f32_16x16x32_bf16 v[32:35], v[104:107], v[4:7], v[36:39]
	s_nop 2
	ds_read_b128 v[36:39], v49 offset:49152
	ds_read_b128 v[104:107], v49 offset:51200
	ds_read_b128 v[108:111], v49 offset:53248
	ds_read_b128 v[112:115], v49 offset:55296
	v_mfma_f32_16x16x32_bf16 v[96:99], v[96:99], v[4:7], v[40:43]
	s_nop 2
	ds_read_b128 v[40:43], v49 offset:57344
	ds_read_b128 v[116:119], v49 offset:59392
	ds_read_b128 v[120:123], v49 offset:61440
	ds_read_b128 v[124:127], v49 offset:63488
	v_mfma_f32_16x16x32_bf16 v[88:91], v[88:91], v[4:7], v[92:95]
	s_add_u32 s100, s10, 0x11c10000
	s_addc_u32 s101, s11, 0
	s_mov_b32 m0, s24
	s_nop 0
	global_load_lds_dwordx4 v241, s[100:101]
	s_waitcnt lgkmcnt(0)
	v_mfma_f32_16x16x32_bf16 v[50:53], v[36:39], v[4:7], v[50:53]
	v_mfma_f32_16x16x32_bf16 v[66:69], v[104:107], v[4:7], v[66:69]
	v_mfma_f32_16x16x32_bf16 v[72:75], v[108:111], v[4:7], v[72:75]
	v_mfma_f32_16x16x32_bf16 v[80:83], v[112:115], v[4:7], v[80:83]
	v_mfma_f32_16x16x32_bf16 v[76:79], v[40:43], v[4:7], v[76:79]
	ds_read_b128 v[92:95], v49 offset:31744
	ds_read_b128 v[36:39], v49 offset:29696
	ds_read_b128 v[40:43], v49 offset:27648
	ds_read_b128 v[104:107], v49 offset:25600
	v_mfma_f32_16x16x32_bf16 v[84:87], v[116:119], v[4:7], v[84:87]
	v_mfma_f32_16x16x32_bf16 v[100:103], v[120:123], v[4:7], v[100:103]
	ds_read_b128 v[108:111], v49 offset:23552
	ds_read_b128 v[112:115], v49 offset:21504
	ds_read_b128 v[116:119], v49 offset:19456
	ds_read_b128 v[120:123], v49 offset:17408
	v_mfma_f32_16x16x32_bf16 v[124:127], v[124:127], v[4:7], v[8:11]
	s_add_u32 s100, s10, 0x11c18000
	s_addc_u32 s101, s11, 0
	s_mov_b32 m0, s25
	s_nop 0
	global_load_lds_dwordx4 v241, s[100:101]
	s_waitcnt lgkmcnt(0)
	v_mfma_f32_16x16x32_bf16 v[120:123], v[120:123], v[0:3], v[12:15]
	v_mfma_f32_16x16x32_bf16 v[116:119], v[116:119], v[0:3], v[16:19]
	ds_read_b128 v[4:7], v49 offset:50176
	ds_read_b128 v[8:11], v49 offset:52224
	ds_read_b128 v[12:15], v49 offset:54272
	ds_read_b128 v[16:19], v49 offset:56320
	v_mfma_f32_16x16x32_bf16 v[36:39], v[36:39], v[0:3], v[96:99]
	s_nop 2
	ds_read_b128 v[96:99], v49 offset:58368
	ds_read_b128 v[128:131], v49 offset:60416
	ds_read_b128 v[132:135], v49 offset:62464
	ds_read_b128 v[136:139], v49 offset:64512
	v_mfma_f32_16x16x32_bf16 v[112:115], v[112:115], v[0:3], v[20:23]
	v_mfma_f32_16x16x32_bf16 v[108:111], v[108:111], v[0:3], v[24:27]
	v_mfma_f32_16x16x32_bf16 v[104:107], v[104:107], v[0:3], v[28:31]
	v_mfma_f32_16x16x32_bf16 v[40:43], v[40:43], v[0:3], v[32:35]
	v_mfma_f32_16x16x32_bf16 v[32:35], v[92:95], v[0:3], v[88:91]
	s_add_u32 s100, s10, 0x11c10080
	s_addc_u32 s101, s11, 0
	s_mov_b32 m0, s26
	s_nop 0
	global_load_lds_dwordx4 v241, s[100:101]
	s_waitcnt lgkmcnt(0)
	v_mfma_f32_16x16x32_bf16 v[28:31], v[4:7], v[0:3], v[50:53]
	v_mfma_f32_16x16x32_bf16 v[24:27], v[8:11], v[0:3], v[66:69]
	v_mfma_f32_16x16x32_bf16 v[20:23], v[12:15], v[0:3], v[72:75]
	v_mfma_f32_16x16x32_bf16 v[16:19], v[16:19], v[0:3], v[80:83]
	v_mfma_f32_16x16x32_bf16 v[12:15], v[96:99], v[0:3], v[76:79]
	v_mfma_f32_16x16x32_bf16 v[8:11], v[128:131], v[0:3], v[84:87]
	v_mfma_f32_16x16x32_bf16 v[4:7], v[132:135], v[0:3], v[100:103]
	v_mfma_f32_16x16x32_bf16 v[0:3], v[136:139], v[0:3], v[124:127]
	s_add_u32 s100, s10, 0x11c18080
	s_addc_u32 s101, s11, 0
	s_mov_b32 m0, s27
	s_nop 0
	global_load_lds_dwordx4 v241, s[100:101]
	v_max_f32_e32 v49, v123, v123
	v_max_f32_e32 v50, v122, v122
	v_max_f32_e32 v49, v50, v49
	v_max_f32_e32 v50, v117, v117
	v_max_f32_e32 v51, v116, v116
	v_max_f32_e32 v50, v51, v50
	v_max_f32_e32 v51, v119, v119
	v_max_f32_e32 v52, v118, v118
	v_max3_f32 v49, v120, v121, v49
	v_max_f32_e32 v51, v52, v51
	v_max3_f32 v49, v49, v50, v51
	v_max_f32_e32 v50, v113, v113
	v_max_f32_e32 v51, v112, v112
	v_max_f32_e32 v50, v51, v50
	v_max_f32_e32 v51, v115, v115
	v_max_f32_e32 v52, v114, v114
	v_max_f32_e32 v51, v52, v51
	v_max3_f32 v49, v49, v50, v51
	v_max_f32_e32 v50, v109, v109
	v_max_f32_e32 v51, v108, v108
	v_max_f32_e32 v50, v51, v50
	v_max_f32_e32 v51, v111, v111
	v_max_f32_e32 v52, v110, v110
	v_max_f32_e32 v51, v52, v51
	v_max3_f32 v49, v49, v50, v51
	v_max_f32_e32 v50, v105, v105
	v_max_f32_e32 v51, v104, v104
	v_max_f32_e32 v50, v51, v50
	v_max_f32_e32 v51, v107, v107
	v_max_f32_e32 v52, v106, v106
	v_max_f32_e32 v51, v52, v51
	v_max3_f32 v49, v49, v50, v51
	v_max_f32_e32 v50, v41, v41
	v_max_f32_e32 v51, v40, v40
	v_max_f32_e32 v50, v51, v50
	v_max_f32_e32 v51, v43, v43
	v_max_f32_e32 v52, v42, v42
	v_max_f32_e32 v51, v52, v51
	v_max3_f32 v49, v49, v50, v51
	v_max_f32_e32 v50, v37, v37
	v_max_f32_e32 v51, v36, v36
	v_max_f32_e32 v50, v51, v50
	v_max_f32_e32 v51, v39, v39
	v_max_f32_e32 v52, v38, v38
	v_max_f32_e32 v51, v52, v51
	v_max3_f32 v49, v49, v50, v51
	v_max_f32_e32 v50, v33, v33
	v_max_f32_e32 v51, v32, v32
	v_max_f32_e32 v50, v51, v50
	v_max_f32_e32 v51, v35, v35
	v_max_f32_e32 v52, v34, v34
	v_max_f32_e32 v51, v52, v51
	v_max3_f32 v49, v49, v50, v51
	v_max_f32_e32 v50, v29, v29
	v_max_f32_e32 v51, v28, v28
	v_max_f32_e32 v50, v51, v50
	v_max_f32_e32 v51, v31, v31
	v_max_f32_e32 v52, v30, v30
	v_max_f32_e32 v51, v52, v51
	v_max3_f32 v49, v49, v50, v51
	v_max_f32_e32 v50, v25, v25
	v_max_f32_e32 v51, v24, v24
	v_max_f32_e32 v50, v51, v50
	v_max_f32_e32 v51, v27, v27
	v_max_f32_e32 v52, v26, v26
	v_max_f32_e32 v51, v52, v51
	v_max3_f32 v49, v49, v50, v51
	v_max_f32_e32 v50, v21, v21
	v_max_f32_e32 v51, v20, v20
	v_max_f32_e32 v50, v51, v50
	v_max_f32_e32 v51, v23, v23
	v_max_f32_e32 v52, v22, v22
	v_max_f32_e32 v51, v52, v51
	v_max3_f32 v49, v49, v50, v51
	v_max_f32_e32 v50, v17, v17
	v_max_f32_e32 v51, v16, v16
	v_max_f32_e32 v50, v51, v50
	v_max_f32_e32 v51, v19, v19
	v_max_f32_e32 v52, v18, v18
	v_max_f32_e32 v51, v52, v51
	v_max3_f32 v49, v49, v50, v51
	v_max_f32_e32 v50, v13, v13
	v_max_f32_e32 v51, v12, v12
	v_max_f32_e32 v50, v51, v50
	v_max_f32_e32 v51, v15, v15
	v_max_f32_e32 v52, v14, v14
	v_max_f32_e32 v51, v52, v51
	v_max3_f32 v49, v49, v50, v51
	v_max_f32_e32 v50, v9, v9
	v_max_f32_e32 v51, v8, v8
	v_max_f32_e32 v50, v51, v50
	v_max_f32_e32 v51, v11, v11
	v_max_f32_e32 v52, v10, v10
	v_max_f32_e32 v51, v52, v51
	v_max3_f32 v49, v49, v50, v51
	v_max_f32_e32 v50, v5, v5
	v_max_f32_e32 v51, v4, v4
	v_max_f32_e32 v50, v51, v50
	v_max_f32_e32 v51, v7, v7
	v_max_f32_e32 v52, v6, v6
	v_max_f32_e32 v51, v52, v51
	v_max3_f32 v49, v49, v50, v51
	v_max_f32_e32 v50, v1, v1
	v_max_f32_e32 v51, v0, v0
	v_max_f32_e32 v50, v51, v50
	v_max_f32_e32 v51, v3, v3
	v_max_f32_e32 v52, v2, v2
	v_max_f32_e32 v51, v52, v51
	v_max3_f32 v49, v49, v50, v51
	v_mbcnt_lo_u32_b32 v50, -1, 0
	v_mbcnt_hi_u32_b32 v50, -1, v50
	v_and_b32_e32 v52, 64, v50
	v_xor_b32_e32 v51, 16, v50
	v_add_u32_e32 v52, 64, v52
	v_cmp_lt_i32_e32 vcc, v51, v52
	s_nop 1
	v_cndmask_b32_e32 v51, v50, v51, vcc
	v_lshlrev_b32_e32 v51, 2, v51
	v_mov_b32_e32 v53, v49
	s_nop 1
	v_permlane16_swap_b32_e32 v53, v49
	s_waitcnt lgkmcnt(0)
	v_max_f32_e32 v53, v53, v53
	v_max_f32_e32 v49, v49, v53
	v_xor_b32_e32 v53, 32, v50
	v_cmp_lt_i32_e32 vcc, v53, v52
	s_nop 1
	v_cndmask_b32_e32 v50, v50, v53, vcc
	v_lshlrev_b32_e32 v50, 2, v50
	v_mov_b32_e32 v52, v49
	s_nop 1
	v_permlane32_swap_b32_e32 v52, v49
	s_waitcnt lgkmcnt(0)
	v_max_f32_e32 v52, v52, v52
	v_max_f32_e32 v49, v49, v52
	v_sub_f32_e32 v52, v120, v49
	v_exp_f32_e32 v52, v52
	v_sub_f32_e32 v53, v121, v49
	v_exp_f32_e32 v53, v53
	v_sub_f32_e32 v54, v122, v49
	v_exp_f32_e32 v54, v54
	v_sub_f32_e32 v55, v123, v49
	v_exp_f32_e32 v55, v55
	v_sub_f32_e32 v59, v116, v49
	v_add_f32_e32 v57, 0, v52
	v_exp_f32_e32 v59, v59
	v_sub_f32_e32 v62, v117, v49
	v_add_f32_e32 v57, v53, v57
	v_exp_f32_e32 v62, v62
	v_sub_f32_e32 v63, v118, v49
	v_add_f32_e32 v57, v54, v57
	v_exp_f32_e32 v63, v63
	v_sub_f32_e32 v64, v119, v49
	v_add_f32_e32 v57, v55, v57
	v_exp_f32_e32 v64, v64
	v_sub_f32_e32 v66, v112, v49
	v_add_f32_e32 v57, v59, v57
	v_exp_f32_e32 v66, v66
	v_sub_f32_e32 v67, v113, v49
	v_add_f32_e32 v57, v62, v57
	v_exp_f32_e32 v67, v67
	v_sub_f32_e32 v68, v114, v49
	v_add_f32_e32 v57, v63, v57
	v_exp_f32_e32 v68, v68
	v_sub_f32_e32 v69, v115, v49
	v_add_f32_e32 v57, v64, v57
	v_exp_f32_e32 v69, v69
	v_sub_f32_e32 v71, v108, v49
	v_add_f32_e32 v57, v66, v57
	v_exp_f32_e32 v71, v71
	v_sub_f32_e32 v72, v109, v49
	v_add_f32_e32 v57, v67, v57
	v_exp_f32_e32 v72, v72
	v_sub_f32_e32 v73, v110, v49
	v_add_f32_e32 v57, v68, v57
	v_exp_f32_e32 v73, v73
	v_sub_f32_e32 v74, v111, v49
	v_add_f32_e32 v57, v69, v57
	v_exp_f32_e32 v74, v74
	v_sub_f32_e32 v75, v104, v49
	v_add_f32_e32 v57, v71, v57
	v_exp_f32_e32 v75, v75
	v_sub_f32_e32 v76, v105, v49
	v_add_f32_e32 v57, v72, v57
	v_exp_f32_e32 v76, v76
	v_sub_f32_e32 v77, v106, v49
	v_add_f32_e32 v57, v73, v57
	v_exp_f32_e32 v77, v77
	v_sub_f32_e32 v78, v107, v49
	v_add_f32_e32 v57, v74, v57
	v_exp_f32_e32 v78, v78
	v_sub_f32_e32 v40, v40, v49
	v_add_f32_e32 v57, v75, v57
	v_exp_f32_e32 v40, v40
	v_sub_f32_e32 v41, v41, v49
	v_add_f32_e32 v57, v76, v57
	v_exp_f32_e32 v41, v41
	v_sub_f32_e32 v42, v42, v49
	v_add_f32_e32 v57, v77, v57
	v_exp_f32_e32 v42, v42
	v_sub_f32_e32 v43, v43, v49
	v_add_f32_e32 v57, v78, v57
	v_exp_f32_e32 v43, v43
	v_sub_f32_e32 v36, v36, v49
	v_add_f32_e32 v57, v40, v57
	v_exp_f32_e32 v36, v36
	v_sub_f32_e32 v37, v37, v49
	v_add_f32_e32 v57, v41, v57
	v_exp_f32_e32 v37, v37
	v_sub_f32_e32 v38, v38, v49
	v_add_f32_e32 v57, v42, v57
	v_exp_f32_e32 v38, v38
	v_sub_f32_e32 v39, v39, v49
	v_add_f32_e32 v57, v43, v57
	v_exp_f32_e32 v39, v39
	v_sub_f32_e32 v32, v32, v49
	v_add_f32_e32 v57, v36, v57
	v_exp_f32_e32 v32, v32
	v_sub_f32_e32 v33, v33, v49
	v_add_f32_e32 v57, v37, v57
	v_exp_f32_e32 v33, v33
	v_sub_f32_e32 v34, v34, v49
	v_add_f32_e32 v57, v38, v57
	v_exp_f32_e32 v34, v34
	v_sub_f32_e32 v35, v35, v49
	v_add_f32_e32 v57, v39, v57
	v_exp_f32_e32 v35, v35
	v_sub_f32_e32 v28, v28, v49
	v_add_f32_e32 v57, v32, v57
	v_exp_f32_e32 v79, v28
	v_sub_f32_e32 v28, v29, v49
	v_add_f32_e32 v57, v33, v57
	v_exp_f32_e32 v80, v28
	v_sub_f32_e32 v28, v30, v49
	v_add_f32_e32 v57, v34, v57
	v_exp_f32_e32 v81, v28
	v_sub_f32_e32 v28, v31, v49
	v_add_f32_e32 v57, v35, v57
	v_exp_f32_e32 v82, v28
	v_sub_f32_e32 v24, v24, v49
	v_add_f32_e32 v28, v79, v57
	v_exp_f32_e32 v57, v24
	v_sub_f32_e32 v24, v25, v49
	v_add_f32_e32 v28, v80, v28
	v_exp_f32_e32 v83, v24
	v_sub_f32_e32 v24, v26, v49
	v_add_f32_e32 v28, v81, v28
	v_exp_f32_e32 v84, v24
	v_sub_f32_e32 v24, v27, v49
	v_add_f32_e32 v28, v82, v28
	v_exp_f32_e32 v85, v24
	v_sub_f32_e32 v20, v20, v49
	v_add_f32_e32 v24, v57, v28
	v_exp_f32_e32 v86, v20
	v_sub_f32_e32 v20, v21, v49
	v_add_f32_e32 v24, v83, v24
	v_exp_f32_e32 v87, v20
	v_sub_f32_e32 v20, v22, v49
	v_add_f32_e32 v24, v84, v24
	v_exp_f32_e32 v88, v20
	v_sub_f32_e32 v20, v23, v49
	v_add_f32_e32 v24, v85, v24
	v_exp_f32_e32 v89, v20
	v_sub_f32_e32 v16, v16, v49
	v_add_f32_e32 v20, v86, v24
	v_exp_f32_e32 v90, v16
	v_sub_f32_e32 v16, v17, v49
	v_add_f32_e32 v20, v87, v20
	v_exp_f32_e32 v91, v16
	v_sub_f32_e32 v16, v18, v49
	v_add_f32_e32 v20, v88, v20
	v_exp_f32_e32 v92, v16
	v_sub_f32_e32 v16, v19, v49
	v_add_f32_e32 v20, v89, v20
	v_exp_f32_e32 v93, v16
	v_sub_f32_e32 v12, v12, v49
	v_add_f32_e32 v16, v90, v20
	v_exp_f32_e32 v94, v12
	v_sub_f32_e32 v12, v13, v49
	v_add_f32_e32 v16, v91, v16
	v_exp_f32_e32 v95, v12
	v_sub_f32_e32 v12, v14, v49
	v_add_f32_e32 v16, v92, v16
	v_exp_f32_e32 v96, v12
	v_sub_f32_e32 v12, v15, v49
	v_add_f32_e32 v16, v93, v16
	v_exp_f32_e32 v97, v12
	v_sub_f32_e32 v8, v8, v49
	v_add_f32_e32 v12, v94, v16
	v_exp_f32_e32 v98, v8
	v_sub_f32_e32 v8, v9, v49
	v_add_f32_e32 v12, v95, v12
	v_exp_f32_e32 v99, v8
	v_sub_f32_e32 v8, v10, v49
	v_add_f32_e32 v12, v96, v12
	v_exp_f32_e32 v100, v8
	v_sub_f32_e32 v8, v11, v49
	v_add_f32_e32 v12, v97, v12
	v_exp_f32_e32 v11, v8
	v_sub_f32_e32 v4, v4, v49
	v_add_f32_e32 v8, v98, v12
	v_exp_f32_e32 v101, v4
	v_sub_f32_e32 v4, v5, v49
	v_add_f32_e32 v8, v99, v8
	v_exp_f32_e32 v102, v4
	v_sub_f32_e32 v4, v6, v49
	v_add_f32_e32 v8, v100, v8
	v_exp_f32_e32 v103, v4
	v_sub_f32_e32 v4, v7, v49
	v_add_f32_e32 v8, v11, v8
	v_exp_f32_e32 v104, v4
	v_sub_f32_e32 v0, v0, v49
	v_add_f32_e32 v4, v101, v8
	v_exp_f32_e32 v105, v0
	v_sub_f32_e32 v0, v1, v49
	v_add_f32_e32 v4, v102, v4
	v_exp_f32_e32 v106, v0
	v_sub_f32_e32 v0, v2, v49
	v_add_f32_e32 v4, v103, v4
	v_exp_f32_e32 v107, v0
	v_sub_f32_e32 v0, v3, v49
	v_add_f32_e32 v4, v104, v4
	v_exp_f32_e32 v3, v0
	v_add_f32_e32 v0, v105, v4
	v_add_f32_e32 v0, v106, v0
	v_add_f32_e32 v0, v107, v0
	v_add_f32_e32 v0, v3, v0
	v_mov_b32_e32 v1, v0
	s_nop 1
	v_permlane16_swap_b32_e32 v1, v0
	v_cvt_pk_bf16_f32 v28, v52, v53
	v_cvt_pk_bf16_f32 v29, v54, v55
	v_cvt_pk_bf16_f32 v30, v59, v62
	v_cvt_pk_bf16_f32 v31, v63, v64
	s_waitcnt lgkmcnt(0)
	v_add_f32_e32 v0, v0, v1
	v_mov_b32_e32 v1, v0
	s_nop 1
	v_permlane32_swap_b32_e32 v1, v0
	v_cvt_pk_bf16_f32 v20, v66, v67
	v_cvt_pk_bf16_f32 v21, v68, v69
	v_cvt_pk_bf16_f32 v22, v71, v72
	v_cvt_pk_bf16_f32 v23, v73, v74
	s_waitcnt lgkmcnt(0)
	v_add_f32_e32 v49, v0, v1
	v_cvt_pk_bf16_f32 v24, v75, v76
	v_cvt_pk_bf16_f32 v25, v77, v78
	v_cvt_pk_bf16_f32 v26, v40, v41
	v_cvt_pk_bf16_f32 v27, v42, v43
	v_cvt_pk_bf16_f32 v16, v36, v37
	v_cvt_pk_bf16_f32 v17, v38, v39
	v_cvt_pk_bf16_f32 v18, v32, v33
	v_cvt_pk_bf16_f32 v19, v34, v35
	v_cvt_pk_bf16_f32 v12, v79, v80
	v_cvt_pk_bf16_f32 v13, v81, v82
	v_cvt_pk_bf16_f32 v14, v57, v83
	v_cvt_pk_bf16_f32 v15, v84, v85
	v_cvt_pk_bf16_f32 v4, v86, v87
	v_cvt_pk_bf16_f32 v5, v88, v89
	v_cvt_pk_bf16_f32 v6, v90, v91
	v_cvt_pk_bf16_f32 v7, v92, v93
	v_cvt_pk_bf16_f32 v8, v94, v95
	v_cvt_pk_bf16_f32 v9, v96, v97
	v_cvt_pk_bf16_f32 v10, v98, v99
	v_cvt_pk_bf16_f32 v11, v100, v11
	v_cvt_pk_bf16_f32 v0, v101, v102
	v_cvt_pk_bf16_f32 v1, v103, v104
	v_cvt_pk_bf16_f32 v2, v105, v106
	v_cvt_pk_bf16_f32 v3, v107, v3
	s_waitcnt vmcnt(0)
	s_waitcnt vmcnt(0)
	s_barrier
	v_mov_b32_e32 v64, v65
	v_div_scale_f32 v62, vcc, 1.0, v49, 1.0
	v_lshlrev_b32_e32 v54, 2, v70
	v_ashrrev_i32_e32 v55, 31, v54
	ds_read_b128 v[32:35], v64
	ds_read_b128 v[36:39], v64 offset:2048
	v_div_scale_f32 v57, s[0:1], v49, v49, 1.0
	v_rcp_f32_e32 v59, v57
	s_waitcnt lgkmcnt(0)
	v_mfma_f32_16x16x32_bf16 v[44:47], v[32:35], v[28:31], 0
	v_fma_f32 v40, -v57, v59, 1.0
	v_fmac_f32_e32 v59, v40, v59
	ds_read_b128 v[40:43], v64 offset:4096
	ds_read_b128 v[32:35], v64 offset:6144
	v_mul_f32_e32 v63, v62, v59
	v_fma_f32 v66, -v57, v63, v62
	v_fmac_f32_e32 v63, v66, v59
	v_mfma_f32_16x16x32_bf16 v[50:53], v[36:39], v[28:31], 0
	v_fma_f32 v36, -v57, v63, v62
	ds_read_b128 v[66:69], v64 offset:8192
	ds_read_b128 v[70:73], v64 offset:10240
	v_div_fmas_f32 v36, v36, v59, v63
	s_waitcnt lgkmcnt(0)
	v_mfma_f32_16x16x32_bf16 v[74:77], v[32:35], v[28:31], 0
	v_lshl_add_u64 v[34:35], v[54:55], 1, v[60:61]
	ds_read_b128 v[60:63], v64 offset:12288
	ds_read_b128 v[78:81], v64 offset:14336
	ds_read_b128 v[82:85], v64 offset:32768
	ds_read_b128 v[86:89], v64 offset:34816
	ds_read_b128 v[90:93], v64 offset:36864
	ds_read_b128 v[94:97], v64 offset:38912
	ds_read_b128 v[98:101], v64 offset:40960
	ds_read_b128 v[102:105], v64 offset:43008
	ds_read_b128 v[106:109], v64 offset:45056
	ds_read_b128 v[110:113], v64 offset:47104
	s_mov_b64 s[0:1], 0x1000000
	v_mfma_f32_16x16x32_bf16 v[38:41], v[40:43], v[28:31], 0
	v_div_fixup_f32 v36, v36, v49, 1.0
	v_lshl_add_u64 v[32:33], v[34:35], 0, s[0:1]
	v_mfma_f32_16x16x32_bf16 v[66:69], v[66:69], v[28:31], 0
	v_mfma_f32_16x16x32_bf16 v[70:73], v[70:73], v[28:31], 0
	s_waitcnt lgkmcnt(0)
	v_mfma_f32_16x16x32_bf16 v[60:63], v[60:63], v[28:31], 0
	v_mfma_f32_16x16x32_bf16 v[78:81], v[78:81], v[28:31], 0
	s_add_u32 s100, s10, 0x11c00100
	s_addc_u32 s101, s11, 0
	s_mov_b32 m0, s19
	s_nop 0
	global_load_lds_dwordx4 v241, s[100:101]
	ds_read_b128 v[114:117], v64 offset:30720
	ds_read_b128 v[118:121], v64 offset:28672
	ds_read_b128 v[122:125], v64 offset:26624
	ds_read_b128 v[126:129], v64 offset:24576
	ds_read_b128 v[130:133], v64 offset:22528
	ds_read_b128 v[134:137], v64 offset:20480
	ds_read_b128 v[138:141], v64 offset:18432
	ds_read_b128 v[142:145], v64 offset:16384
	v_mfma_f32_16x16x32_bf16 v[82:85], v[82:85], v[28:31], 0
	v_mfma_f32_16x16x32_bf16 v[86:89], v[86:89], v[28:31], 0
	v_mfma_f32_16x16x32_bf16 v[90:93], v[90:93], v[28:31], 0
	v_mfma_f32_16x16x32_bf16 v[94:97], v[94:97], v[28:31], 0
	v_mfma_f32_16x16x32_bf16 v[98:101], v[98:101], v[28:31], 0
	v_mfma_f32_16x16x32_bf16 v[102:105], v[102:105], v[28:31], 0
	v_mfma_f32_16x16x32_bf16 v[106:109], v[106:109], v[28:31], 0
	v_mfma_f32_16x16x32_bf16 v[110:113], v[110:113], v[28:31], 0
	s_add_u32 s100, s10, 0x11c08100
	s_addc_u32 s101, s11, 0
	s_mov_b32 m0, s13
	s_nop 0
	global_load_lds_dwordx4 v241, s[100:101]
	s_waitcnt lgkmcnt(0)
	v_mfma_f32_16x16x32_bf16 v[42:45], v[142:145], v[24:27], v[44:47]
	v_mfma_f32_16x16x32_bf16 v[50:53], v[138:141], v[24:27], v[50:53]
	v_mfma_f32_16x16x32_bf16 v[38:41], v[134:137], v[24:27], v[38:41]
	v_mfma_f32_16x16x32_bf16 v[74:77], v[130:133], v[24:27], v[74:77]
	v_mfma_f32_16x16x32_bf16 v[66:69], v[126:129], v[24:27], v[66:69]
	v_mfma_f32_16x16x32_bf16 v[70:73], v[122:125], v[24:27], v[70:73]
	ds_read_b128 v[122:125], v64 offset:49152
	ds_read_b128 v[126:129], v64 offset:51200
	ds_read_b128 v[130:133], v64 offset:53248
	ds_read_b128 v[134:137], v64 offset:55296
	v_mfma_f32_16x16x32_bf16 v[60:63], v[118:121], v[24:27], v[60:63]
	ds_read_b128 v[118:121], v64 offset:57344
	ds_read_b128 v[138:141], v64 offset:59392
	ds_read_b128 v[142:145], v64 offset:61440
	ds_read_b128 v[146:149], v64 offset:63488
	v_mfma_f32_16x16x32_bf16 v[78:81], v[114:117], v[24:27], v[78:81]
	s_add_u32 s100, s10, 0x11c00180
	s_addc_u32 s101, s11, 0
	s_mov_b32 m0, s12
	s_nop 0
	global_load_lds_dwordx4 v241, s[100:101]
	s_waitcnt lgkmcnt(0)
	v_mfma_f32_16x16x32_bf16 v[82:85], v[122:125], v[24:27], v[82:85]
	v_mfma_f32_16x16x32_bf16 v[86:89], v[126:129], v[24:27], v[86:89]
	v_mfma_f32_16x16x32_bf16 v[90:93], v[130:133], v[24:27], v[90:93]
	v_mfma_f32_16x16x32_bf16 v[94:97], v[134:137], v[24:27], v[94:97]
	v_mfma_f32_16x16x32_bf16 v[98:101], v[118:121], v[24:27], v[98:101]
	ds_read_b128 v[114:117], v64 offset:15360
	ds_read_b128 v[118:121], v64 offset:13312
	ds_read_b128 v[122:125], v64 offset:11264
	ds_read_b128 v[126:129], v64 offset:9216
	v_mfma_f32_16x16x32_bf16 v[102:105], v[138:141], v[24:27], v[102:105]
	v_mfma_f32_16x16x32_bf16 v[106:109], v[142:145], v[24:27], v[106:109]
	ds_read_b128 v[130:133], v64 offset:7168
	ds_read_b128 v[134:137], v64 offset:5120
	ds_read_b128 v[138:141], v64 offset:3072
	ds_read_b128 v[142:145], v64 offset:1024
	v_mfma_f32_16x16x32_bf16 v[110:113], v[146:149], v[24:27], v[110:113]
	s_add_u32 s100, s10, 0x11c08180
	s_addc_u32 s101, s11, 0
	s_mov_b32 m0, s14
	s_nop 0
	global_load_lds_dwordx4 v241, s[100:101]
	s_waitcnt lgkmcnt(0)
	v_mfma_f32_16x16x32_bf16 v[42:45], v[142:145], v[20:23], v[42:45]
	v_mfma_f32_16x16x32_bf16 v[50:53], v[138:141], v[20:23], v[50:53]
	v_mfma_f32_16x16x32_bf16 v[38:41], v[134:137], v[20:23], v[38:41]
	v_mfma_f32_16x16x32_bf16 v[74:77], v[130:133], v[20:23], v[74:77]
	v_mfma_f32_16x16x32_bf16 v[66:69], v[126:129], v[20:23], v[66:69]
	v_mfma_f32_16x16x32_bf16 v[70:73], v[122:125], v[20:23], v[70:73]
	ds_read_b128 v[122:125], v64 offset:33792
	ds_read_b128 v[126:129], v64 offset:35840
	ds_read_b128 v[130:133], v64 offset:37888
	ds_read_b128 v[134:137], v64 offset:39936
	v_mfma_f32_16x16x32_bf16 v[60:63], v[118:121], v[20:23], v[60:63]
	ds_read_b128 v[118:121], v64 offset:41984
	ds_read_b128 v[138:141], v64 offset:44032
	ds_read_b128 v[142:145], v64 offset:46080
	ds_read_b128 v[146:149], v64 offset:48128
	v_mfma_f32_16x16x32_bf16 v[78:81], v[114:117], v[20:23], v[78:81]
	s_add_u32 s100, s10, 0x11c10100
	s_addc_u32 s101, s11, 0
	s_mov_b32 m0, s15
	s_nop 0
	global_load_lds_dwordx4 v241, s[100:101]
	s_waitcnt lgkmcnt(0)
	v_mfma_f32_16x16x32_bf16 v[82:85], v[122:125], v[20:23], v[82:85]
	v_mfma_f32_16x16x32_bf16 v[86:89], v[126:129], v[20:23], v[86:89]
	v_mfma_f32_16x16x32_bf16 v[90:93], v[130:133], v[20:23], v[90:93]
	v_mfma_f32_16x16x32_bf16 v[94:97], v[134:137], v[20:23], v[94:97]
	v_mfma_f32_16x16x32_bf16 v[98:101], v[118:121], v[20:23], v[98:101]
	ds_read_b128 v[114:117], v64 offset:31744
	ds_read_b128 v[118:121], v64 offset:29696
	ds_read_b128 v[122:125], v64 offset:27648
	ds_read_b128 v[126:129], v64 offset:25600
	v_mfma_f32_16x16x32_bf16 v[102:105], v[138:141], v[20:23], v[102:105]
	v_mfma_f32_16x16x32_bf16 v[106:109], v[142:145], v[20:23], v[106:109]
	ds_read_b128 v[130:133], v64 offset:23552
	ds_read_b128 v[134:137], v64 offset:21504
	ds_read_b128 v[138:141], v64 offset:19456
	ds_read_b128 v[142:145], v64 offset:17408
	v_mfma_f32_16x16x32_bf16 v[110:113], v[146:149], v[20:23], v[110:113]
	s_add_u32 s100, s10, 0x11c18100
	s_addc_u32 s101, s11, 0
	s_mov_b32 m0, s16
	s_nop 0
	global_load_lds_dwordx4 v241, s[100:101]
	s_waitcnt lgkmcnt(0)
	v_mfma_f32_16x16x32_bf16 v[42:45], v[142:145], v[16:19], v[42:45]
	v_mfma_f32_16x16x32_bf16 v[50:53], v[138:141], v[16:19], v[50:53]
	v_mfma_f32_16x16x32_bf16 v[38:41], v[134:137], v[16:19], v[38:41]
	v_mfma_f32_16x16x32_bf16 v[74:77], v[130:133], v[16:19], v[74:77]
	v_mfma_f32_16x16x32_bf16 v[66:69], v[126:129], v[16:19], v[66:69]
	v_mfma_f32_16x16x32_bf16 v[70:73], v[122:125], v[16:19], v[70:73]
	ds_read_b128 v[122:125], v64 offset:50176
	ds_read_b128 v[126:129], v64 offset:52224
	ds_read_b128 v[130:133], v64 offset:54272
	ds_read_b128 v[134:137], v64 offset:56320
	v_mfma_f32_16x16x32_bf16 v[60:63], v[118:121], v[16:19], v[60:63]
	ds_read_b128 v[118:121], v64 offset:58368
	ds_read_b128 v[138:141], v64 offset:60416
	ds_read_b128 v[142:145], v64 offset:62464
	ds_read_b128 v[146:149], v64 offset:64512
	v_mfma_f32_16x16x32_bf16 v[78:81], v[114:117], v[16:19], v[78:81]
	s_add_u32 s100, s10, 0x11c10180
	s_addc_u32 s101, s11, 0
	s_mov_b32 m0, s17
	s_nop 0
	global_load_lds_dwordx4 v241, s[100:101]
	s_waitcnt lgkmcnt(0)
	v_mfma_f32_16x16x32_bf16 v[82:85], v[122:125], v[16:19], v[82:85]
	v_mfma_f32_16x16x32_bf16 v[86:89], v[126:129], v[16:19], v[86:89]
	v_mfma_f32_16x16x32_bf16 v[90:93], v[130:133], v[16:19], v[90:93]
	v_mfma_f32_16x16x32_bf16 v[94:97], v[134:137], v[16:19], v[94:97]
	v_mfma_f32_16x16x32_bf16 v[98:101], v[118:121], v[16:19], v[98:101]
	v_mfma_f32_16x16x32_bf16 v[102:105], v[138:141], v[16:19], v[102:105]
	v_mfma_f32_16x16x32_bf16 v[106:109], v[142:145], v[16:19], v[106:109]
	v_mfma_f32_16x16x32_bf16 v[110:113], v[146:149], v[16:19], v[110:113]
	s_add_u32 s100, s10, 0x11c18180
	s_addc_u32 s101, s11, 0
	s_mov_b32 m0, s18
	s_nop 0
	global_load_lds_dwordx4 v241, s[100:101]
	s_waitcnt vmcnt(0)
	s_waitcnt vmcnt(0)
	s_barrier
	v_mov_b32_e32 v37, v48
	ds_read_b128 v[114:117], v37
	ds_read_b128 v[118:121], v37 offset:2048
	s_waitcnt lgkmcnt(0)
	v_mfma_f32_16x16x32_bf16 v[42:45], v[114:117], v[12:15], v[42:45]
	ds_read_b128 v[114:117], v37 offset:4096
	v_mfma_f32_16x16x32_bf16 v[50:53], v[118:121], v[12:15], v[50:53]
	ds_read_b128 v[118:121], v37 offset:6144
	s_waitcnt lgkmcnt(0)
	v_mfma_f32_16x16x32_bf16 v[38:41], v[114:117], v[12:15], v[38:41]
	ds_read_b128 v[114:117], v37 offset:8192
	v_mfma_f32_16x16x32_bf16 v[74:77], v[118:121], v[12:15], v[74:77]
	ds_read_b128 v[118:121], v37 offset:10240
	s_waitcnt lgkmcnt(0)
	v_mfma_f32_16x16x32_bf16 v[66:69], v[114:117], v[12:15], v[66:69]
	ds_read_b128 v[114:117], v37 offset:12288
	ds_read_b128 v[122:125], v37 offset:14336
	v_mfma_f32_16x16x32_bf16 v[70:73], v[118:121], v[12:15], v[70:73]
	ds_read_b128 v[118:121], v37 offset:32768
	ds_read_b128 v[126:129], v37 offset:34816
	ds_read_b128 v[130:133], v37 offset:36864
	ds_read_b128 v[134:137], v37 offset:38912
	s_waitcnt lgkmcnt(0)
	v_mfma_f32_16x16x32_bf16 v[60:63], v[114:117], v[12:15], v[60:63]
	ds_read_b128 v[114:117], v37 offset:40960
	ds_read_b128 v[138:141], v37 offset:43008
	ds_read_b128 v[142:145], v37 offset:45056
	ds_read_b128 v[146:149], v37 offset:47104
	v_mfma_f32_16x16x32_bf16 v[78:81], v[122:125], v[12:15], v[78:81]
	s_add_u32 s100, s10, 0x11c20000
	s_addc_u32 s101, s11, 0
	s_mov_b32 m0, s22
	s_nop 0
	global_load_lds_dwordx4 v241, s[100:101]
	v_mfma_f32_16x16x32_bf16 v[82:85], v[118:121], v[12:15], v[82:85]
	v_mfma_f32_16x16x32_bf16 v[86:89], v[126:129], v[12:15], v[86:89]
	v_mfma_f32_16x16x32_bf16 v[90:93], v[130:133], v[12:15], v[90:93]
	v_mfma_f32_16x16x32_bf16 v[94:97], v[134:137], v[12:15], v[94:97]
	s_waitcnt lgkmcnt(0)
	v_mfma_f32_16x16x32_bf16 v[98:101], v[114:117], v[12:15], v[98:101]
	ds_read_b128 v[114:117], v37 offset:30720
	ds_read_b128 v[118:121], v37 offset:28672
	ds_read_b128 v[122:125], v37 offset:26624
	ds_read_b128 v[126:129], v37 offset:24576
	v_mfma_f32_16x16x32_bf16 v[102:105], v[138:141], v[12:15], v[102:105]
	v_mfma_f32_16x16x32_bf16 v[106:109], v[142:145], v[12:15], v[106:109]
	ds_read_b128 v[130:133], v37 offset:22528
	ds_read_b128 v[134:137], v37 offset:20480
	ds_read_b128 v[138:141], v37 offset:18432
	ds_read_b128 v[142:145], v37 offset:16384
	v_mfma_f32_16x16x32_bf16 v[110:113], v[146:149], v[12:15], v[110:113]
	s_add_u32 s100, s10, 0x11c28000
	s_addc_u32 s101, s11, 0
	s_mov_b32 m0, s21
	s_nop 0
	global_load_lds_dwordx4 v241, s[100:101]
	s_waitcnt lgkmcnt(0)
	v_mfma_f32_16x16x32_bf16 v[42:45], v[142:145], v[8:11], v[42:45]
	v_mfma_f32_16x16x32_bf16 v[50:53], v[138:141], v[8:11], v[50:53]
	v_mfma_f32_16x16x32_bf16 v[38:41], v[134:137], v[8:11], v[38:41]
	v_mfma_f32_16x16x32_bf16 v[74:77], v[130:133], v[8:11], v[74:77]
	v_mfma_f32_16x16x32_bf16 v[66:69], v[126:129], v[8:11], v[66:69]
	v_mfma_f32_16x16x32_bf16 v[70:73], v[122:125], v[8:11], v[70:73]
	ds_read_b128 v[122:125], v37 offset:49152
	ds_read_b128 v[126:129], v37 offset:51200
	ds_read_b128 v[130:133], v37 offset:53248
	ds_read_b128 v[134:137], v37 offset:55296
	v_mfma_f32_16x16x32_bf16 v[60:63], v[118:121], v[8:11], v[60:63]
	ds_read_b128 v[118:121], v37 offset:57344
	ds_read_b128 v[138:141], v37 offset:59392
	ds_read_b128 v[142:145], v37 offset:61440
	ds_read_b128 v[146:149], v37 offset:63488
	v_mfma_f32_16x16x32_bf16 v[78:81], v[114:117], v[8:11], v[78:81]
	s_add_u32 s100, s10, 0x11c20080
	s_addc_u32 s101, s11, 0
	s_mov_b32 m0, s20
	s_nop 0
	global_load_lds_dwordx4 v241, s[100:101]
	s_waitcnt lgkmcnt(0)
	v_mfma_f32_16x16x32_bf16 v[82:85], v[122:125], v[8:11], v[82:85]
	v_mfma_f32_16x16x32_bf16 v[86:89], v[126:129], v[8:11], v[86:89]
	v_mfma_f32_16x16x32_bf16 v[90:93], v[130:133], v[8:11], v[90:93]
	v_mfma_f32_16x16x32_bf16 v[94:97], v[134:137], v[8:11], v[94:97]
	v_mfma_f32_16x16x32_bf16 v[98:101], v[118:121], v[8:11], v[98:101]
	ds_read_b128 v[114:117], v37 offset:15360
	ds_read_b128 v[118:121], v37 offset:13312
	ds_read_b128 v[122:125], v37 offset:11264
	ds_read_b128 v[126:129], v37 offset:9216
	v_mfma_f32_16x16x32_bf16 v[102:105], v[138:141], v[8:11], v[102:105]
	v_mfma_f32_16x16x32_bf16 v[106:109], v[142:145], v[8:11], v[106:109]
	ds_read_b128 v[130:133], v37 offset:7168
	ds_read_b128 v[134:137], v37 offset:5120
	ds_read_b128 v[138:141], v37 offset:3072
	ds_read_b128 v[142:145], v37 offset:1024
	v_mfma_f32_16x16x32_bf16 v[110:113], v[146:149], v[8:11], v[110:113]
	s_add_u32 s100, s10, 0x11c28080
	s_addc_u32 s101, s11, 0
	s_mov_b32 m0, s23
	s_nop 0
	global_load_lds_dwordx4 v241, s[100:101]
	s_waitcnt lgkmcnt(0)
	v_mfma_f32_16x16x32_bf16 v[42:45], v[142:145], v[4:7], v[42:45]
	v_mfma_f32_16x16x32_bf16 v[50:53], v[138:141], v[4:7], v[50:53]
	v_mfma_f32_16x16x32_bf16 v[38:41], v[134:137], v[4:7], v[38:41]
	v_mfma_f32_16x16x32_bf16 v[74:77], v[130:133], v[4:7], v[74:77]
	v_mfma_f32_16x16x32_bf16 v[66:69], v[126:129], v[4:7], v[66:69]
	v_mfma_f32_16x16x32_bf16 v[70:73], v[122:125], v[4:7], v[70:73]
	ds_read_b128 v[122:125], v37 offset:33792
	ds_read_b128 v[126:129], v37 offset:35840
	ds_read_b128 v[130:133], v37 offset:37888
	ds_read_b128 v[134:137], v37 offset:39936
	v_mfma_f32_16x16x32_bf16 v[60:63], v[118:121], v[4:7], v[60:63]
	ds_read_b128 v[118:121], v37 offset:41984
	ds_read_b128 v[138:141], v37 offset:44032
	ds_read_b128 v[142:145], v37 offset:46080
	ds_read_b128 v[146:149], v37 offset:48128
	v_mfma_f32_16x16x32_bf16 v[78:81], v[114:117], v[4:7], v[78:81]
	s_add_u32 s100, s10, 0x11c30000
	s_addc_u32 s101, s11, 0
	s_mov_b32 m0, s24
	s_nop 0
	global_load_lds_dwordx4 v241, s[100:101]
	s_waitcnt lgkmcnt(0)
	v_mfma_f32_16x16x32_bf16 v[82:85], v[122:125], v[4:7], v[82:85]
	v_mfma_f32_16x16x32_bf16 v[86:89], v[126:129], v[4:7], v[86:89]
	v_mfma_f32_16x16x32_bf16 v[90:93], v[130:133], v[4:7], v[90:93]
	v_mfma_f32_16x16x32_bf16 v[94:97], v[134:137], v[4:7], v[94:97]
	v_mfma_f32_16x16x32_bf16 v[98:101], v[118:121], v[4:7], v[98:101]
	ds_read_b128 v[114:117], v37 offset:31744
	ds_read_b128 v[118:121], v37 offset:29696
	ds_read_b128 v[122:125], v37 offset:27648
	ds_read_b128 v[126:129], v37 offset:25600
	v_mfma_f32_16x16x32_bf16 v[102:105], v[138:141], v[4:7], v[102:105]
	v_mfma_f32_16x16x32_bf16 v[106:109], v[142:145], v[4:7], v[106:109]
	ds_read_b128 v[130:133], v37 offset:23552
	ds_read_b128 v[134:137], v37 offset:21504
	ds_read_b128 v[138:141], v37 offset:19456
	ds_read_b128 v[142:145], v37 offset:17408
	v_mfma_f32_16x16x32_bf16 v[110:113], v[146:149], v[4:7], v[110:113]
	s_add_u32 s100, s10, 0x11c38000
	s_addc_u32 s101, s11, 0
	s_mov_b32 m0, s25
	s_nop 0
	global_load_lds_dwordx4 v241, s[100:101]
	s_waitcnt lgkmcnt(0)
	v_mfma_f32_16x16x32_bf16 v[42:45], v[142:145], v[0:3], v[42:45]
	v_mfma_f32_16x16x32_bf16 v[50:53], v[138:141], v[0:3], v[50:53]
	v_mfma_f32_16x16x32_bf16 v[38:41], v[134:137], v[0:3], v[38:41]
	v_mfma_f32_16x16x32_bf16 v[74:77], v[130:133], v[0:3], v[74:77]
	v_mfma_f32_16x16x32_bf16 v[66:69], v[126:129], v[0:3], v[66:69]
	v_mfma_f32_16x16x32_bf16 v[70:73], v[122:125], v[0:3], v[70:73]
	ds_read_b128 v[122:125], v37 offset:50176
	ds_read_b128 v[126:129], v37 offset:52224
	ds_read_b128 v[130:133], v37 offset:54272
	ds_read_b128 v[134:137], v37 offset:56320
	v_mfma_f32_16x16x32_bf16 v[60:63], v[118:121], v[0:3], v[60:63]
	ds_read_b128 v[118:121], v37 offset:58368
	ds_read_b128 v[138:141], v37 offset:60416
	ds_read_b128 v[142:145], v37 offset:62464
	ds_read_b128 v[146:149], v37 offset:64512
	v_mfma_f32_16x16x32_bf16 v[78:81], v[114:117], v[0:3], v[78:81]
	s_add_u32 s100, s10, 0x11c30080
	s_addc_u32 s101, s11, 0
	s_mov_b32 m0, s26
	s_nop 0
	global_load_lds_dwordx4 v241, s[100:101]
	s_waitcnt lgkmcnt(0)
	v_mfma_f32_16x16x32_bf16 v[82:85], v[122:125], v[0:3], v[82:85]
	v_mfma_f32_16x16x32_bf16 v[86:89], v[126:129], v[0:3], v[86:89]
	v_mfma_f32_16x16x32_bf16 v[90:93], v[130:133], v[0:3], v[90:93]
	v_mfma_f32_16x16x32_bf16 v[94:97], v[134:137], v[0:3], v[94:97]
	v_mfma_f32_16x16x32_bf16 v[98:101], v[118:121], v[0:3], v[98:101]
	v_mfma_f32_16x16x32_bf16 v[102:105], v[138:141], v[0:3], v[102:105]
	v_mfma_f32_16x16x32_bf16 v[106:109], v[142:145], v[0:3], v[106:109]
	v_mfma_f32_16x16x32_bf16 v[110:113], v[146:149], v[0:3], v[110:113]
	s_add_u32 s100, s10, 0x11c38080
	s_addc_u32 s101, s11, 0
	s_mov_b32 m0, s27
	s_nop 0
	global_load_lds_dwordx4 v241, s[100:101]
	s_mov_b32 s0, 0x1000000
	v_add_co_u32_e32 v34, vcc, s0, v34
	v_addc_co_u32_e32 v35, vcc, 0, v35, vcc
	v_mbcnt_lo_u32_b32 v212, -1, 0
	v_mbcnt_hi_u32_b32 v212, -1, v212
	v_lshrrev_b32_e32 v212, 4, v212
	v_and_b32_e32 v212, 1, v212
	v_mul_u32_u24_e32 v212, 24, v212
	v_mov_b32_e32 v213, 0
	v_lshl_add_u64 v[214:215], v[32:33], 0, v[212:213]
	v_mul_f32_e32 v200, v36, v42
	v_mul_f32_e32 v204, v36, v43
	v_cvt_pk_bf16_f32 v200, v200, v204
	v_mul_f32_e32 v201, v36, v44
	v_mul_f32_e32 v204, v36, v45
	v_cvt_pk_bf16_f32 v201, v201, v204
	v_mul_f32_e32 v202, v36, v50
	v_mul_f32_e32 v204, v36, v51
	v_cvt_pk_bf16_f32 v202, v202, v204
	v_mul_f32_e32 v203, v36, v52
	v_mul_f32_e32 v204, v36, v53
	v_cvt_pk_bf16_f32 v203, v203, v204
	s_nop 1
	v_permlane16_swap_b32_e32 v200, v202
	v_permlane16_swap_b32_e32 v201, v203
	global_store_dwordx4 v[214:215], v[200:203], off offset:0
	v_mul_f32_e32 v206, v36, v38
	v_mul_f32_e32 v210, v36, v39
	v_cvt_pk_bf16_f32 v206, v206, v210
	v_mul_f32_e32 v207, v36, v40
	v_mul_f32_e32 v210, v36, v41
	v_cvt_pk_bf16_f32 v207, v207, v210
	v_mul_f32_e32 v208, v36, v74
	v_mul_f32_e32 v210, v36, v75
	v_cvt_pk_bf16_f32 v208, v208, v210
	v_mul_f32_e32 v209, v36, v76
	v_mul_f32_e32 v210, v36, v77
	v_cvt_pk_bf16_f32 v209, v209, v210
	s_nop 1
	v_permlane16_swap_b32_e32 v206, v208
	v_permlane16_swap_b32_e32 v207, v209
	global_store_dwordx4 v[214:215], v[206:209], off offset:64
	v_mul_f32_e32 v200, v36, v66
	v_mul_f32_e32 v204, v36, v67
	v_cvt_pk_bf16_f32 v200, v200, v204
	v_mul_f32_e32 v201, v36, v68
	v_mul_f32_e32 v204, v36, v69
	v_cvt_pk_bf16_f32 v201, v201, v204
	v_mul_f32_e32 v202, v36, v70
	v_mul_f32_e32 v204, v36, v71
	v_cvt_pk_bf16_f32 v202, v202, v204
	v_mul_f32_e32 v203, v36, v72
	v_mul_f32_e32 v204, v36, v73
	v_cvt_pk_bf16_f32 v203, v203, v204
	s_nop 1
	v_permlane16_swap_b32_e32 v200, v202
	v_permlane16_swap_b32_e32 v201, v203
	global_store_dwordx4 v[214:215], v[200:203], off offset:128
	v_mul_f32_e32 v206, v36, v60
	v_mul_f32_e32 v210, v36, v61
	v_cvt_pk_bf16_f32 v206, v206, v210
	v_mul_f32_e32 v207, v36, v62
	v_mul_f32_e32 v210, v36, v63
	v_cvt_pk_bf16_f32 v207, v207, v210
	v_mul_f32_e32 v208, v36, v78
	v_mul_f32_e32 v210, v36, v79
	v_cvt_pk_bf16_f32 v208, v208, v210
	v_mul_f32_e32 v209, v36, v80
	v_mul_f32_e32 v210, v36, v81
	v_cvt_pk_bf16_f32 v209, v209, v210
	s_nop 1
	v_permlane16_swap_b32_e32 v206, v208
	v_permlane16_swap_b32_e32 v207, v209
	global_store_dwordx4 v[214:215], v[206:209], off offset:192
	v_mul_f32_e32 v200, v36, v82
	v_mul_f32_e32 v204, v36, v83
	v_cvt_pk_bf16_f32 v200, v200, v204
	v_mul_f32_e32 v201, v36, v84
	v_mul_f32_e32 v204, v36, v85
	v_cvt_pk_bf16_f32 v201, v201, v204
	v_mul_f32_e32 v202, v36, v86
	v_mul_f32_e32 v204, v36, v87
	v_cvt_pk_bf16_f32 v202, v202, v204
	v_mul_f32_e32 v203, v36, v88
	v_mul_f32_e32 v204, v36, v89
	v_cvt_pk_bf16_f32 v203, v203, v204
	s_nop 1
	v_permlane16_swap_b32_e32 v200, v202
	v_permlane16_swap_b32_e32 v201, v203
	global_store_dwordx4 v[214:215], v[200:203], off offset:256
	v_mul_f32_e32 v206, v36, v90
	v_mul_f32_e32 v210, v36, v91
	v_cvt_pk_bf16_f32 v206, v206, v210
	v_mul_f32_e32 v207, v36, v92
	v_mul_f32_e32 v210, v36, v93
	v_cvt_pk_bf16_f32 v207, v207, v210
	v_mul_f32_e32 v208, v36, v94
	v_mul_f32_e32 v210, v36, v95
	v_cvt_pk_bf16_f32 v208, v208, v210
	v_mul_f32_e32 v209, v36, v96
	v_mul_f32_e32 v210, v36, v97
	v_cvt_pk_bf16_f32 v209, v209, v210
	s_nop 1
	v_permlane16_swap_b32_e32 v206, v208
	v_permlane16_swap_b32_e32 v207, v209
	global_store_dwordx4 v[214:215], v[206:209], off offset:320
	v_mul_f32_e32 v200, v36, v98
	v_mul_f32_e32 v204, v36, v99
	v_cvt_pk_bf16_f32 v200, v200, v204
	v_mul_f32_e32 v201, v36, v100
	v_mul_f32_e32 v204, v36, v101
	v_cvt_pk_bf16_f32 v201, v201, v204
	v_mul_f32_e32 v202, v36, v102
	v_mul_f32_e32 v204, v36, v103
	v_cvt_pk_bf16_f32 v202, v202, v204
	v_mul_f32_e32 v203, v36, v104
	v_mul_f32_e32 v204, v36, v105
	v_cvt_pk_bf16_f32 v203, v203, v204
	s_nop 1
	v_permlane16_swap_b32_e32 v200, v202
	v_permlane16_swap_b32_e32 v201, v203
	global_store_dwordx4 v[214:215], v[200:203], off offset:384
	v_mul_f32_e32 v206, v36, v106
	v_mul_f32_e32 v210, v36, v107
	v_cvt_pk_bf16_f32 v206, v206, v210
	v_mul_f32_e32 v207, v36, v108
	v_mul_f32_e32 v210, v36, v109
	v_cvt_pk_bf16_f32 v207, v207, v210
	v_mul_f32_e32 v208, v36, v110
	v_mul_f32_e32 v210, v36, v111
	v_cvt_pk_bf16_f32 v208, v208, v210
	v_mul_f32_e32 v209, v36, v112
	v_mul_f32_e32 v210, v36, v113
	v_cvt_pk_bf16_f32 v209, v209, v210
	s_nop 1
	v_permlane16_swap_b32_e32 v206, v208
	v_permlane16_swap_b32_e32 v207, v209
	global_store_dwordx4 v[214:215], v[206:209], off offset:448
	s_waitcnt vmcnt(8)
	s_waitcnt vmcnt(8)
	s_barrier
	ds_read_b128 v[38:41], v65
	ds_read_b128 v[42:45], v65 offset:2048
	ds_read_b128 v[50:53], v65 offset:4096
	ds_read_b128 v[54:57], v65 offset:6144
	ds_read_b128 v[58:61], v65 offset:8192
	ds_read_b128 v[66:69], v65 offset:10240
	ds_read_b128 v[70:73], v65 offset:12288
	ds_read_b128 v[74:77], v65 offset:14336
	ds_read_b128 v[78:81], v65 offset:32768
	ds_read_b128 v[82:85], v65 offset:34816
	ds_read_b128 v[86:89], v65 offset:36864
	ds_read_b128 v[90:93], v65 offset:38912
	ds_read_b128 v[94:97], v65 offset:40960
	ds_read_b128 v[98:101], v65 offset:43008
	ds_read_b128 v[102:105], v65 offset:45056
	ds_read_b128 v[106:109], v65 offset:47104
	s_waitcnt lgkmcnt(0)
	v_mfma_f32_16x16x32_bf16 v[38:41], v[38:41], v[28:31], 0
	v_mfma_f32_16x16x32_bf16 v[42:45], v[42:45], v[28:31], 0
	v_mfma_f32_16x16x32_bf16 v[50:53], v[50:53], v[28:31], 0
	v_mfma_f32_16x16x32_bf16 v[54:57], v[54:57], v[28:31], 0
	v_mfma_f32_16x16x32_bf16 v[58:61], v[58:61], v[28:31], 0
	v_mfma_f32_16x16x32_bf16 v[66:69], v[66:69], v[28:31], 0
	v_mfma_f32_16x16x32_bf16 v[70:73], v[70:73], v[28:31], 0
	v_mfma_f32_16x16x32_bf16 v[74:77], v[74:77], v[28:31], 0
	s_add_u32 s100, s10, 0x11c20100
	s_addc_u32 s101, s11, 0
	s_mov_b32 m0, s19
	s_nop 0
	global_load_lds_dwordx4 v241, s[100:101]
	ds_read_b128 v[110:113], v65 offset:30720
	ds_read_b128 v[114:117], v65 offset:28672
	ds_read_b128 v[118:121], v65 offset:26624
	ds_read_b128 v[122:125], v65 offset:24576
	ds_read_b128 v[126:129], v65 offset:22528
	ds_read_b128 v[130:133], v65 offset:20480
	ds_read_b128 v[134:137], v65 offset:18432
	ds_read_b128 v[138:141], v65 offset:16384
	v_mfma_f32_16x16x32_bf16 v[78:81], v[78:81], v[28:31], 0
	v_mfma_f32_16x16x32_bf16 v[82:85], v[82:85], v[28:31], 0
	v_mfma_f32_16x16x32_bf16 v[86:89], v[86:89], v[28:31], 0
	v_mfma_f32_16x16x32_bf16 v[90:93], v[90:93], v[28:31], 0
	v_mfma_f32_16x16x32_bf16 v[94:97], v[94:97], v[28:31], 0
	v_mfma_f32_16x16x32_bf16 v[98:101], v[98:101], v[28:31], 0
	v_mfma_f32_16x16x32_bf16 v[102:105], v[102:105], v[28:31], 0
	v_mfma_f32_16x16x32_bf16 v[28:31], v[106:109], v[28:31], 0
	s_add_u32 s100, s10, 0x11c28100
	s_addc_u32 s101, s11, 0
	s_mov_b32 m0, s13
	s_nop 0
	global_load_lds_dwordx4 v241, s[100:101]
	s_waitcnt lgkmcnt(0)
	v_mfma_f32_16x16x32_bf16 v[38:41], v[138:141], v[24:27], v[38:41]
	v_mfma_f32_16x16x32_bf16 v[42:45], v[134:137], v[24:27], v[42:45]
	v_mfma_f32_16x16x32_bf16 v[50:53], v[130:133], v[24:27], v[50:53]
	v_mfma_f32_16x16x32_bf16 v[54:57], v[126:129], v[24:27], v[54:57]
	v_mfma_f32_16x16x32_bf16 v[58:61], v[122:125], v[24:27], v[58:61]
	v_mfma_f32_16x16x32_bf16 v[66:69], v[118:121], v[24:27], v[66:69]
	ds_read_b128 v[106:109], v65 offset:49152
	ds_read_b128 v[118:121], v65 offset:51200
	ds_read_b128 v[122:125], v65 offset:53248
	ds_read_b128 v[126:129], v65 offset:55296
	v_mfma_f32_16x16x32_bf16 v[70:73], v[114:117], v[24:27], v[70:73]
	ds_read_b128 v[114:117], v65 offset:57344
	ds_read_b128 v[130:133], v65 offset:59392
	ds_read_b128 v[134:137], v65 offset:61440
	ds_read_b128 v[138:141], v65 offset:63488
	v_mfma_f32_16x16x32_bf16 v[74:77], v[110:113], v[24:27], v[74:77]
	s_add_u32 s100, s10, 0x11c20180
	s_addc_u32 s101, s11, 0
	s_mov_b32 m0, s12
	s_nop 0
	global_load_lds_dwordx4 v241, s[100:101]
	s_waitcnt lgkmcnt(0)
	v_mfma_f32_16x16x32_bf16 v[78:81], v[106:109], v[24:27], v[78:81]
	v_mfma_f32_16x16x32_bf16 v[82:85], v[118:121], v[24:27], v[82:85]
	v_mfma_f32_16x16x32_bf16 v[86:89], v[122:125], v[24:27], v[86:89]
	v_mfma_f32_16x16x32_bf16 v[90:93], v[126:129], v[24:27], v[90:93]
	v_mfma_f32_16x16x32_bf16 v[94:97], v[114:117], v[24:27], v[94:97]
	ds_read_b128 v[106:109], v65 offset:15360
	ds_read_b128 v[110:113], v65 offset:13312
	ds_read_b128 v[114:117], v65 offset:11264
	ds_read_b128 v[118:121], v65 offset:9216
	v_mfma_f32_16x16x32_bf16 v[98:101], v[130:133], v[24:27], v[98:101]
	v_mfma_f32_16x16x32_bf16 v[102:105], v[134:137], v[24:27], v[102:105]
	ds_read_b128 v[122:125], v65 offset:7168
	ds_read_b128 v[126:129], v65 offset:5120
	ds_read_b128 v[130:133], v65 offset:3072
	ds_read_b128 v[134:137], v65 offset:1024
	v_mfma_f32_16x16x32_bf16 v[24:27], v[138:141], v[24:27], v[28:31]
	s_add_u32 s100, s10, 0x11c28180
	s_addc_u32 s101, s11, 0
	s_mov_b32 m0, s14
	s_nop 0
	global_load_lds_dwordx4 v241, s[100:101]
	s_waitcnt lgkmcnt(0)
	v_mfma_f32_16x16x32_bf16 v[28:31], v[134:137], v[20:23], v[38:41]
	v_mfma_f32_16x16x32_bf16 v[38:41], v[130:133], v[20:23], v[42:45]
	v_mfma_f32_16x16x32_bf16 v[42:45], v[126:129], v[20:23], v[50:53]
	v_mfma_f32_16x16x32_bf16 v[50:53], v[122:125], v[20:23], v[54:57]
	v_mfma_f32_16x16x32_bf16 v[54:57], v[118:121], v[20:23], v[58:61]
	v_mfma_f32_16x16x32_bf16 v[58:61], v[114:117], v[20:23], v[66:69]
	s_nop 2
	ds_read_b128 v[66:69], v65 offset:33792
	ds_read_b128 v[114:117], v65 offset:35840
	ds_read_b128 v[118:121], v65 offset:37888
	ds_read_b128 v[122:125], v65 offset:39936
	v_mfma_f32_16x16x32_bf16 v[70:73], v[110:113], v[20:23], v[70:73]
	ds_read_b128 v[110:113], v65 offset:41984
	ds_read_b128 v[126:129], v65 offset:44032
	ds_read_b128 v[130:133], v65 offset:46080
	ds_read_b128 v[134:137], v65 offset:48128
	v_mfma_f32_16x16x32_bf16 v[74:77], v[106:109], v[20:23], v[74:77]
	s_add_u32 s100, s10, 0x11c30100
	s_addc_u32 s101, s11, 0
	s_mov_b32 m0, s15
	s_nop 0
	global_load_lds_dwordx4 v241, s[100:101]
	s_waitcnt lgkmcnt(0)
	v_mfma_f32_16x16x32_bf16 v[66:69], v[66:69], v[20:23], v[78:81]
	v_mfma_f32_16x16x32_bf16 v[78:81], v[114:117], v[20:23], v[82:85]
	v_mfma_f32_16x16x32_bf16 v[82:85], v[118:121], v[20:23], v[86:89]
	v_mfma_f32_16x16x32_bf16 v[86:89], v[122:125], v[20:23], v[90:93]
	v_mfma_f32_16x16x32_bf16 v[90:93], v[110:113], v[20:23], v[94:97]
	v_mfma_f32_16x16x32_bf16 v[94:97], v[126:129], v[20:23], v[98:101]
	s_nop 2
	ds_read_b128 v[98:101], v65 offset:31744
	ds_read_b128 v[106:109], v65 offset:29696
	ds_read_b128 v[110:113], v65 offset:27648
	ds_read_b128 v[114:117], v65 offset:25600
	v_mfma_f32_16x16x32_bf16 v[102:105], v[130:133], v[20:23], v[102:105]
	ds_read_b128 v[118:121], v65 offset:23552
	ds_read_b128 v[122:125], v65 offset:21504
	ds_read_b128 v[126:129], v65 offset:19456
	ds_read_b128 v[130:133], v65 offset:17408
	v_mfma_f32_16x16x32_bf16 v[20:23], v[134:137], v[20:23], v[24:27]
	s_add_u32 s100, s10, 0x11c38100
	s_addc_u32 s101, s11, 0
	s_mov_b32 m0, s16
	s_nop 0
	global_load_lds_dwordx4 v241, s[100:101]
	s_waitcnt lgkmcnt(0)
	v_mfma_f32_16x16x32_bf16 v[24:27], v[130:133], v[16:19], v[28:31]
	v_mfma_f32_16x16x32_bf16 v[28:31], v[126:129], v[16:19], v[38:41]
	v_mfma_f32_16x16x32_bf16 v[38:41], v[122:125], v[16:19], v[42:45]
	v_mfma_f32_16x16x32_bf16 v[42:45], v[118:121], v[16:19], v[50:53]
	v_mfma_f32_16x16x32_bf16 v[50:53], v[114:117], v[16:19], v[54:57]
	v_mfma_f32_16x16x32_bf16 v[54:57], v[110:113], v[16:19], v[58:61]
	s_nop 2
	ds_read_b128 v[58:61], v65 offset:50176
	ds_read_b128 v[110:113], v65 offset:52224
	ds_read_b128 v[114:117], v65 offset:54272
	ds_read_b128 v[118:121], v65 offset:56320
	v_mfma_f32_16x16x32_bf16 v[70:73], v[106:109], v[16:19], v[70:73]
	ds_read_b128 v[106:109], v65 offset:58368
	ds_read_b128 v[122:125], v65 offset:60416
	ds_read_b128 v[126:129], v65 offset:62464
	ds_read_b128 v[62:65], v65 offset:64512
	v_mfma_f32_16x16x32_bf16 v[74:77], v[98:101], v[16:19], v[74:77]
	s_add_u32 s100, s10, 0x11c30180
	s_addc_u32 s101, s11, 0
	s_mov_b32 m0, s17
	s_nop 0
	global_load_lds_dwordx4 v241, s[100:101]
	s_waitcnt lgkmcnt(0)
	v_mfma_f32_16x16x32_bf16 v[58:61], v[58:61], v[16:19], v[66:69]
	v_mfma_f32_16x16x32_bf16 v[66:69], v[110:113], v[16:19], v[78:81]
	v_mfma_f32_16x16x32_bf16 v[78:81], v[114:117], v[16:19], v[82:85]
	v_mfma_f32_16x16x32_bf16 v[82:85], v[118:121], v[16:19], v[86:89]
	v_mfma_f32_16x16x32_bf16 v[86:89], v[106:109], v[16:19], v[90:93]
	v_mfma_f32_16x16x32_bf16 v[90:93], v[122:125], v[16:19], v[94:97]
	v_mfma_f32_16x16x32_bf16 v[94:97], v[126:129], v[16:19], v[102:105]
	v_mfma_f32_16x16x32_bf16 v[16:19], v[62:65], v[16:19], v[20:23]
	s_add_u32 s100, s10, 0x11c38180
	s_addc_u32 s101, s11, 0
	s_mov_b32 m0, s18
	s_nop 0
	global_load_lds_dwordx4 v241, s[100:101]
	s_waitcnt vmcnt(0)
	s_waitcnt vmcnt(0)
	s_barrier
	s_nop 0
	ds_read_b128 v[20:23], v48
	ds_read_b128 v[62:65], v48 offset:2048
	s_waitcnt lgkmcnt(1)
	v_mfma_f32_16x16x32_bf16 v[20:23], v[20:23], v[12:15], v[24:27]
	s_nop 2
	ds_read_b128 v[24:27], v48 offset:4096
	s_waitcnt lgkmcnt(1)
	v_mfma_f32_16x16x32_bf16 v[28:31], v[62:65], v[12:15], v[28:31]
	ds_read_b128 v[62:65], v48 offset:6144
	s_waitcnt lgkmcnt(1)
	v_mfma_f32_16x16x32_bf16 v[24:27], v[24:27], v[12:15], v[38:41]
	s_nop 2
	ds_read_b128 v[38:41], v48 offset:8192
	s_waitcnt lgkmcnt(1)
	v_mfma_f32_16x16x32_bf16 v[42:45], v[62:65], v[12:15], v[42:45]
	ds_read_b128 v[62:65], v48 offset:10240
	s_waitcnt lgkmcnt(1)
	v_mfma_f32_16x16x32_bf16 v[38:41], v[38:41], v[12:15], v[50:53]
	s_nop 2
	ds_read_b128 v[50:53], v48 offset:12288
	ds_read_b128 v[98:101], v48 offset:14336
	s_waitcnt lgkmcnt(2)
	v_mfma_f32_16x16x32_bf16 v[54:57], v[62:65], v[12:15], v[54:57]
	ds_read_b128 v[62:65], v48 offset:32768
	ds_read_b128 v[102:105], v48 offset:34816
	ds_read_b128 v[106:109], v48 offset:36864
	ds_read_b128 v[110:113], v48 offset:38912
	s_waitcnt lgkmcnt(5)
	v_mfma_f32_16x16x32_bf16 v[50:53], v[50:53], v[12:15], v[70:73]
	s_nop 2
	ds_read_b128 v[70:73], v48 offset:40960
	ds_read_b128 v[114:117], v48 offset:43008
	ds_read_b128 v[118:121], v48 offset:45056
	ds_read_b128 v[122:125], v48 offset:47104
	s_waitcnt lgkmcnt(8)
	v_mfma_f32_16x16x32_bf16 v[74:77], v[98:101], v[12:15], v[74:77]
	s_waitcnt lgkmcnt(7)
	v_mfma_f32_16x16x32_bf16 v[58:61], v[62:65], v[12:15], v[58:61]
	s_waitcnt lgkmcnt(6)
	v_mfma_f32_16x16x32_bf16 v[62:65], v[102:105], v[12:15], v[66:69]
	s_waitcnt lgkmcnt(5)
	v_mfma_f32_16x16x32_bf16 v[66:69], v[106:109], v[12:15], v[78:81]
	s_waitcnt lgkmcnt(4)
	v_mfma_f32_16x16x32_bf16 v[78:81], v[110:113], v[12:15], v[82:85]
	s_waitcnt lgkmcnt(3)
	v_mfma_f32_16x16x32_bf16 v[70:73], v[70:73], v[12:15], v[86:89]
	s_waitcnt lgkmcnt(2)
	v_mfma_f32_16x16x32_bf16 v[82:85], v[114:117], v[12:15], v[90:93]
	s_nop 0
	ds_read_b128 v[86:89], v48 offset:30720
	s_nop 0
	ds_read_b128 v[90:93], v48 offset:28672
	ds_read_b128 v[98:101], v48 offset:26624
	ds_read_b128 v[102:105], v48 offset:24576
	s_waitcnt lgkmcnt(5)
	v_mfma_f32_16x16x32_bf16 v[94:97], v[118:121], v[12:15], v[94:97]
	ds_read_b128 v[106:109], v48 offset:22528
	ds_read_b128 v[110:113], v48 offset:20480
	ds_read_b128 v[114:117], v48 offset:18432
	ds_read_b128 v[118:121], v48 offset:16384
	s_waitcnt lgkmcnt(8)
	v_mfma_f32_16x16x32_bf16 v[12:15], v[122:125], v[12:15], v[16:19]
	s_waitcnt lgkmcnt(0)
	v_mfma_f32_16x16x32_bf16 v[16:19], v[118:121], v[8:11], v[20:23]
	v_mfma_f32_16x16x32_bf16 v[20:23], v[114:117], v[8:11], v[28:31]
	v_mfma_f32_16x16x32_bf16 v[24:27], v[110:113], v[8:11], v[24:27]
	v_mfma_f32_16x16x32_bf16 v[28:31], v[106:109], v[8:11], v[42:45]
	v_mfma_f32_16x16x32_bf16 v[38:41], v[102:105], v[8:11], v[38:41]
	v_mfma_f32_16x16x32_bf16 v[42:45], v[98:101], v[8:11], v[54:57]
	s_nop 2
	ds_read_b128 v[54:57], v48 offset:49152
	ds_read_b128 v[98:101], v48 offset:51200
	ds_read_b128 v[102:105], v48 offset:53248
	ds_read_b128 v[106:109], v48 offset:55296
	v_mfma_f32_16x16x32_bf16 v[50:53], v[90:93], v[8:11], v[50:53]
	ds_read_b128 v[90:93], v48 offset:57344
	ds_read_b128 v[110:113], v48 offset:59392
	ds_read_b128 v[114:117], v48 offset:61440
	ds_read_b128 v[118:121], v48 offset:63488
	v_mfma_f32_16x16x32_bf16 v[74:77], v[86:89], v[8:11], v[74:77]
	s_waitcnt lgkmcnt(7)
	v_mfma_f32_16x16x32_bf16 v[54:57], v[54:57], v[8:11], v[58:61]
	s_waitcnt lgkmcnt(6)
	v_mfma_f32_16x16x32_bf16 v[58:61], v[98:101], v[8:11], v[62:65]
	s_waitcnt lgkmcnt(5)
	v_mfma_f32_16x16x32_bf16 v[62:65], v[102:105], v[8:11], v[66:69]
	s_waitcnt lgkmcnt(4)
	v_mfma_f32_16x16x32_bf16 v[66:69], v[106:109], v[8:11], v[78:81]
	s_waitcnt lgkmcnt(3)
	v_mfma_f32_16x16x32_bf16 v[70:73], v[90:93], v[8:11], v[70:73]
	s_waitcnt lgkmcnt(2)
	v_mfma_f32_16x16x32_bf16 v[78:81], v[110:113], v[8:11], v[82:85]
	s_nop 2
	ds_read_b128 v[82:85], v48 offset:15360
	ds_read_b128 v[86:89], v48 offset:13312
	ds_read_b128 v[90:93], v48 offset:11264
	ds_read_b128 v[98:101], v48 offset:9216
	s_waitcnt lgkmcnt(5)
	v_mfma_f32_16x16x32_bf16 v[94:97], v[114:117], v[8:11], v[94:97]
	ds_read_b128 v[102:105], v48 offset:7168
	ds_read_b128 v[106:109], v48 offset:5120
	ds_read_b128 v[110:113], v48 offset:3072
	ds_read_b128 v[114:117], v48 offset:1024
	s_waitcnt lgkmcnt(8)
	v_mfma_f32_16x16x32_bf16 v[8:11], v[118:121], v[8:11], v[12:15]
	s_waitcnt lgkmcnt(0)
	v_mfma_f32_16x16x32_bf16 v[12:15], v[114:117], v[4:7], v[16:19]
	v_mfma_f32_16x16x32_bf16 v[16:19], v[110:113], v[4:7], v[20:23]
	v_mfma_f32_16x16x32_bf16 v[20:23], v[106:109], v[4:7], v[24:27]
	v_mfma_f32_16x16x32_bf16 v[24:27], v[102:105], v[4:7], v[28:31]
	v_mfma_f32_16x16x32_bf16 v[28:31], v[98:101], v[4:7], v[38:41]
	v_mfma_f32_16x16x32_bf16 v[38:41], v[90:93], v[4:7], v[42:45]
	s_nop 2
	ds_read_b128 v[42:45], v48 offset:33792
	ds_read_b128 v[90:93], v48 offset:35840
	ds_read_b128 v[98:101], v48 offset:37888
	ds_read_b128 v[102:105], v48 offset:39936
	v_mfma_f32_16x16x32_bf16 v[50:53], v[86:89], v[4:7], v[50:53]
	ds_read_b128 v[86:89], v48 offset:41984
	ds_read_b128 v[106:109], v48 offset:44032
	ds_read_b128 v[110:113], v48 offset:46080
	ds_read_b128 v[114:117], v48 offset:48128
	v_mfma_f32_16x16x32_bf16 v[74:77], v[82:85], v[4:7], v[74:77]
	s_waitcnt lgkmcnt(7)
	v_mfma_f32_16x16x32_bf16 v[42:45], v[42:45], v[4:7], v[54:57]
	s_waitcnt lgkmcnt(6)
	v_mfma_f32_16x16x32_bf16 v[54:57], v[90:93], v[4:7], v[58:61]
	s_waitcnt lgkmcnt(5)
	v_mfma_f32_16x16x32_bf16 v[58:61], v[98:101], v[4:7], v[62:65]
	s_waitcnt lgkmcnt(4)
	v_mfma_f32_16x16x32_bf16 v[62:65], v[102:105], v[4:7], v[66:69]
	s_waitcnt lgkmcnt(3)
	v_mfma_f32_16x16x32_bf16 v[66:69], v[86:89], v[4:7], v[70:73]
	s_waitcnt lgkmcnt(2)
	v_mfma_f32_16x16x32_bf16 v[70:73], v[106:109], v[4:7], v[78:81]
	s_nop 2
	ds_read_b128 v[78:81], v48 offset:31744
	ds_read_b128 v[82:85], v48 offset:29696
	ds_read_b128 v[86:89], v48 offset:27648
	ds_read_b128 v[90:93], v48 offset:25600
	s_waitcnt lgkmcnt(5)
	v_mfma_f32_16x16x32_bf16 v[94:97], v[110:113], v[4:7], v[94:97]
	ds_read_b128 v[98:101], v48 offset:23552
	ds_read_b128 v[102:105], v48 offset:21504
	ds_read_b128 v[106:109], v48 offset:19456
	ds_read_b128 v[110:113], v48 offset:17408
	s_waitcnt lgkmcnt(8)
	v_mfma_f32_16x16x32_bf16 v[4:7], v[114:117], v[4:7], v[8:11]
	s_waitcnt lgkmcnt(0)
	v_mfma_f32_16x16x32_bf16 v[8:11], v[110:113], v[0:3], v[12:15]
	v_mfma_f32_16x16x32_bf16 v[12:15], v[106:109], v[0:3], v[16:19]
	v_mfma_f32_16x16x32_bf16 v[16:19], v[102:105], v[0:3], v[20:23]
	v_mfma_f32_16x16x32_bf16 v[20:23], v[98:101], v[0:3], v[24:27]
	v_mfma_f32_16x16x32_bf16 v[24:27], v[90:93], v[0:3], v[28:31]
	v_mfma_f32_16x16x32_bf16 v[28:31], v[86:89], v[0:3], v[38:41]
	s_nop 2
	ds_read_b128 v[38:41], v48 offset:50176
	ds_read_b128 v[86:89], v48 offset:52224
	ds_read_b128 v[90:93], v48 offset:54272
	ds_read_b128 v[98:101], v48 offset:56320
	v_mfma_f32_16x16x32_bf16 v[50:53], v[82:85], v[0:3], v[50:53]
	ds_read_b128 v[82:85], v48 offset:58368
	ds_read_b128 v[102:105], v48 offset:60416
	ds_read_b128 v[106:109], v48 offset:62464
	ds_read_b128 v[46:49], v48 offset:64512
	v_mfma_f32_16x16x32_bf16 v[74:77], v[78:81], v[0:3], v[74:77]
	s_waitcnt lgkmcnt(7)
	v_mfma_f32_16x16x32_bf16 v[38:41], v[38:41], v[0:3], v[42:45]
	s_waitcnt lgkmcnt(6)
	v_mfma_f32_16x16x32_bf16 v[42:45], v[86:89], v[0:3], v[54:57]
	s_waitcnt lgkmcnt(5)
	v_mfma_f32_16x16x32_bf16 v[54:57], v[90:93], v[0:3], v[58:61]
	s_waitcnt lgkmcnt(4)
	v_mfma_f32_16x16x32_bf16 v[58:61], v[98:101], v[0:3], v[62:65]
	s_waitcnt lgkmcnt(3)
	v_mfma_f32_16x16x32_bf16 v[62:65], v[82:85], v[0:3], v[66:69]
	s_waitcnt lgkmcnt(2)
	v_mfma_f32_16x16x32_bf16 v[66:69], v[102:105], v[0:3], v[70:73]
	s_waitcnt lgkmcnt(1)
	v_mfma_f32_16x16x32_bf16 v[70:73], v[106:109], v[0:3], v[94:97]
	s_waitcnt lgkmcnt(0)
	v_mfma_f32_16x16x32_bf16 v[0:3], v[46:49], v[0:3], v[4:7]
	s_nop 2
	v_mul_f32_e32 v200, v36, v8
	v_mul_f32_e32 v204, v36, v9
	v_cvt_pk_bf16_f32 v200, v200, v204
	v_mul_f32_e32 v201, v36, v10
	v_mul_f32_e32 v204, v36, v11
	v_cvt_pk_bf16_f32 v201, v201, v204
	v_mul_f32_e32 v202, v36, v12
	v_mul_f32_e32 v204, v36, v13
	v_cvt_pk_bf16_f32 v202, v202, v204
	v_mul_f32_e32 v203, v36, v14
	v_mul_f32_e32 v204, v36, v15
	v_cvt_pk_bf16_f32 v203, v203, v204
	s_nop 1
	v_permlane16_swap_b32_e32 v200, v202
	v_permlane16_swap_b32_e32 v201, v203
	global_store_dwordx4 v[214:215], v[200:203], off offset:512
	v_mul_f32_e32 v206, v36, v16
	v_mul_f32_e32 v210, v36, v17
	v_cvt_pk_bf16_f32 v206, v206, v210
	v_mul_f32_e32 v207, v36, v18
	v_mul_f32_e32 v210, v36, v19
	v_cvt_pk_bf16_f32 v207, v207, v210
	v_mul_f32_e32 v208, v36, v20
	v_mul_f32_e32 v210, v36, v21
	v_cvt_pk_bf16_f32 v208, v208, v210
	v_mul_f32_e32 v209, v36, v22
	v_mul_f32_e32 v210, v36, v23
	v_cvt_pk_bf16_f32 v209, v209, v210
	s_nop 1
	v_permlane16_swap_b32_e32 v206, v208
	v_permlane16_swap_b32_e32 v207, v209
	global_store_dwordx4 v[214:215], v[206:209], off offset:576
	v_mul_f32_e32 v200, v36, v24
	v_mul_f32_e32 v204, v36, v25
	v_cvt_pk_bf16_f32 v200, v200, v204
	v_mul_f32_e32 v201, v36, v26
	v_mul_f32_e32 v204, v36, v27
	v_cvt_pk_bf16_f32 v201, v201, v204
	v_mul_f32_e32 v202, v36, v28
	v_mul_f32_e32 v204, v36, v29
	v_cvt_pk_bf16_f32 v202, v202, v204
	v_mul_f32_e32 v203, v36, v30
	v_mul_f32_e32 v204, v36, v31
	v_cvt_pk_bf16_f32 v203, v203, v204
	s_nop 1
	v_permlane16_swap_b32_e32 v200, v202
	v_permlane16_swap_b32_e32 v201, v203
	global_store_dwordx4 v[214:215], v[200:203], off offset:640
	v_mul_f32_e32 v206, v36, v50
	v_mul_f32_e32 v210, v36, v51
	v_cvt_pk_bf16_f32 v206, v206, v210
	v_mul_f32_e32 v207, v36, v52
	v_mul_f32_e32 v210, v36, v53
	v_cvt_pk_bf16_f32 v207, v207, v210
	v_mul_f32_e32 v208, v36, v74
	v_mul_f32_e32 v210, v36, v75
	v_cvt_pk_bf16_f32 v208, v208, v210
	v_mul_f32_e32 v209, v36, v76
	v_mul_f32_e32 v210, v36, v77
	v_cvt_pk_bf16_f32 v209, v209, v210
	s_nop 1
	v_permlane16_swap_b32_e32 v206, v208
	v_permlane16_swap_b32_e32 v207, v209
	global_store_dwordx4 v[214:215], v[206:209], off offset:704
	v_mul_f32_e32 v200, v36, v38
	v_mul_f32_e32 v204, v36, v39
	v_cvt_pk_bf16_f32 v200, v200, v204
	v_mul_f32_e32 v201, v36, v40
	v_mul_f32_e32 v204, v36, v41
	v_cvt_pk_bf16_f32 v201, v201, v204
	v_mul_f32_e32 v202, v36, v42
	v_mul_f32_e32 v204, v36, v43
	v_cvt_pk_bf16_f32 v202, v202, v204
	v_mul_f32_e32 v203, v36, v44
	v_mul_f32_e32 v204, v36, v45
	v_cvt_pk_bf16_f32 v203, v203, v204
	s_nop 1
	v_permlane16_swap_b32_e32 v200, v202
	v_permlane16_swap_b32_e32 v201, v203
	global_store_dwordx4 v[214:215], v[200:203], off offset:768
	v_mul_f32_e32 v206, v36, v54
	v_mul_f32_e32 v210, v36, v55
	v_cvt_pk_bf16_f32 v206, v206, v210
	v_mul_f32_e32 v207, v36, v56
	v_mul_f32_e32 v210, v36, v57
	v_cvt_pk_bf16_f32 v207, v207, v210
	v_mul_f32_e32 v208, v36, v58
	v_mul_f32_e32 v210, v36, v59
	v_cvt_pk_bf16_f32 v208, v208, v210
	v_mul_f32_e32 v209, v36, v60
	v_mul_f32_e32 v210, v36, v61
	v_cvt_pk_bf16_f32 v209, v209, v210
	s_nop 1
	v_permlane16_swap_b32_e32 v206, v208
	v_permlane16_swap_b32_e32 v207, v209
	global_store_dwordx4 v[214:215], v[206:209], off offset:832
	v_mul_f32_e32 v200, v36, v62
	v_mul_f32_e32 v204, v36, v63
	v_cvt_pk_bf16_f32 v200, v200, v204
	v_mul_f32_e32 v201, v36, v64
	v_mul_f32_e32 v204, v36, v65
	v_cvt_pk_bf16_f32 v201, v201, v204
	v_mul_f32_e32 v202, v36, v66
	v_mul_f32_e32 v204, v36, v67
	v_cvt_pk_bf16_f32 v202, v202, v204
	v_mul_f32_e32 v203, v36, v68
	v_mul_f32_e32 v204, v36, v69
	v_cvt_pk_bf16_f32 v203, v203, v204
	s_nop 1
	v_permlane16_swap_b32_e32 v200, v202
	v_permlane16_swap_b32_e32 v201, v203
	global_store_dwordx4 v[214:215], v[200:203], off offset:896
	v_mul_f32_e32 v206, v36, v70
	v_mul_f32_e32 v210, v36, v71
	v_cvt_pk_bf16_f32 v206, v206, v210
	v_mul_f32_e32 v207, v36, v72
	v_mul_f32_e32 v210, v36, v73
	v_cvt_pk_bf16_f32 v207, v207, v210
	v_mul_f32_e32 v208, v36, v0
	v_mul_f32_e32 v210, v36, v1
	v_cvt_pk_bf16_f32 v208, v208, v210
	v_mul_f32_e32 v209, v36, v2
	v_mul_f32_e32 v210, v36, v3
	v_cvt_pk_bf16_f32 v209, v209, v210
	s_nop 1
	v_permlane16_swap_b32_e32 v206, v208
	v_permlane16_swap_b32_e32 v207, v209
	global_store_dwordx4 v[214:215], v[206:209], off offset:960
	s_waitcnt vmcnt(0)
	s_setprio 0
	s_barrier

.Lat_prio1:
	s_add_i32 s0, 0, 0x23f94
	s_waitcnt vmcnt(0)
	v_mov_b32_e32 v0, s0
	v_mbcnt_lo_u32_b32 v58, -1, 0
	v_mbcnt_hi_u32_b32 v58, -1, v58
	ds_read_b32 v0, v0
	v_lshlrev_b32_e32 v71, 4, v58
	v_and_b32_e32 v59, 15, v58
	s_mov_b32 s1, 0
	v_ashrrev_i32_e32 v70, 4, v58
	s_waitcnt lgkmcnt(0)
	v_readfirstlane_b32 s0, v0
	s_and_b32 s4, s0, 7
	s_mul_i32 s5, s4, 0x1400000
	s_add_u32 s5, s94, s5
	s_addc_u32 s6, s95, 0
	s_lshl_b32 s4, s4, 22
	s_sub_u32 s4, 0, s4
	s_subb_u32 s7, 0, 0
	s_add_u32 s4, s5, s4
	s_addc_u32 s5, s6, s7
	s_lshl_b32 s8, s88, 10
	v_add_u32_e32 v0, s8, v71
	v_ashrrev_i32_e32 v1, 31, v0
	v_lshrrev_b32_e32 v1, 22, v1
	v_add_u32_e32 v1, v0, v1
	v_ashrrev_i32_e32 v1, 10, v1
	v_mul_i32_i24_e32 v2, 0x400, v1
	v_sub_u32_e32 v2, v0, v2
	v_lshrrev_b32_e32 v3, 4, v2
	v_bitop3_b32 v2, v3, v2, 32 bitop3:0x6c
	v_ashrrev_i32_e32 v4, 31, v2
	v_lshrrev_b32_e32 v4, 26, v4
	v_lshlrev_b32_e32 v3, 3, v1
	v_add_u32_e32 v4, v2, v4
	v_and_b32_e32 v3, -16, v3
	v_ashrrev_i32_e32 v5, 6, v4
	v_add_u32_e32 v104, v5, v3
	v_and_b32_e32 v3, 0xc0, v4
	v_lshlrev_b32_e32 v1, 5, v1
	v_sub_u32_e32 v2, v2, v3
	v_mov_b32_e32 v3, 1
	v_and_b32_e32 v1, 32, v1
	v_ashrrev_i16_sdwa v2, v3, sext(v2) dst_sel:DWORD dst_unused:UNUSED_PAD src0_sel:DWORD src1_sel:BYTE_0
	v_add_u32_sdwa v1, v1, sext(v2) dst_sel:DWORD dst_unused:UNUSED_PAD src0_sel:DWORD src1_sel:WORD_0
	v_lshlrev_b32_e32 v2, 10, v104
	v_add_u32_e32 v0, 0x2000, v0
	v_lshl_add_u32 v62, v1, 1, v2
	v_ashrrev_i32_e32 v1, 31, v0
	v_lshrrev_b32_e32 v1, 22, v1
	v_add_u32_e32 v1, v0, v1
	v_ashrrev_i32_e32 v1, 10, v1
	v_mul_i32_i24_e32 v2, 0x400, v1
	v_sub_u32_e32 v0, v0, v2
	v_lshrrev_b32_e32 v2, 4, v0
	s_lshl_b32 s6, s0, 3
	v_bitop3_b32 v0, v2, v0, 32 bitop3:0x6c
	s_and_b32 s6, s6, 56
	s_ashr_i32 s7, s0, 5
	v_ashrrev_i32_e32 v4, 31, v0
	s_add_i32 s9, s6, s7
	v_lshrrev_b32_e32 v4, 26, v4
	s_ashr_i32 s12, s9, 5
	v_lshlrev_b32_e32 v2, 3, v1
	v_add_u32_e32 v4, v0, v4
	s_bfe_u32 s0, s0, 0x20003
	s_lshl_b32 s6, s12, 2
	v_and_b32_e32 v2, -16, v2
	v_ashrrev_i32_e32 v5, 6, v4
	s_or_b32 s6, s6, s0
	v_add_u32_e32 v108, v5, v2
	v_and_b32_e32 v2, 0xffc0, v4
	s_ashr_i32 s7, s6, 31
	v_sub_u32_e32 v0, v0, v2
	s_lshl_b64 s[6:7], s[6:7], 18
	v_lshrrev_b16_e32 v2, 7, v0
	s_add_u32 s10, s94, s6
	v_and_b32_e32 v2, 1, v2
	s_addc_u32 s11, s95, s7
	v_lshlrev_b32_e32 v1, 5, v1
	v_add_u16_e32 v0, v0, v2
	s_add_u32 s6, s10, 0x11600000
	v_and_b32_e32 v1, 32, v1
	v_ashrrev_i16_sdwa v0, v3, sext(v0) dst_sel:DWORD dst_unused:UNUSED_PAD src0_sel:DWORD src1_sel:BYTE_0
	s_addc_u32 s7, s11, 0
	s_lshl_b32 s9, s9, 7
	v_add_u32_sdwa v0, v1, sext(v0) dst_sel:DWORD dst_unused:UNUSED_PAD src0_sel:DWORD src1_sel:WORD_0
	v_lshlrev_b32_e32 v1, 10, v108
	s_lshl_b32 s12, s12, 12
	s_and_b32 s9, s9, 0xf80
	v_lshl_add_u32 v64, v0, 1, v1
	v_lshl_or_b32 v1, s88, 4, v59
	s_or_b32 s9, s12, s9
	v_add_u32_e32 v2, s9, v1
	v_ashrrev_i32_e32 v3, 31, v2
	v_lshlrev_b64 v[2:3], 12, v[2:3]
	s_lshl_b32 s0, s0, 10
	v_lshl_add_u64 v[2:3], s[4:5], 0, v[2:3]
	v_lshlrev_b32_e32 v0, 3, v70
	v_lshl_add_u64 v[2:3], v[2:3], 0, s[0:1]
	s_mov_b64 s[0:1], 0x13000000
	v_ashrrev_i32_e32 v1, 31, v0
	v_lshl_add_u64 v[60:61], v[2:3], 0, s[0:1]
	v_lshl_add_u64 v[0:1], v[0:1], 1, v[60:61]
	s_mov_b64 s[0:1], 0xc00000
	v_lshl_add_u64 v[2:3], v[0:1], 0, s[0:1]
	s_mov_b32 s0, 0xc00000
	v_add_co_u32_e32 v0, vcc, s0, v0
	s_add_i32 s22, s8, 0
	s_nop 0
	v_addc_co_u32_e32 v1, vcc, 0, v1, vcc
	v_mov_b32_e32 v63, 0
	s_mov_b32 m0, s22
	s_add_i32 s21, s22, 0x2000
	global_load_dwordx4 v[72:75], v[2:3], off offset:64
	global_load_dwordx4 v[52:55], v[2:3], off offset:128
	global_load_dwordx4 v[48:51], v[2:3], off offset:192
	global_load_dwordx4 v[76:79], v[0:1], off
	v_mov_b32_e32 v65, v63
	global_load_lds_dwordx4 v62, s[6:7]
	v_mov_b32_e32 v240, v62
	s_mov_b32 m0, s21
	v_lshl_add_u64 v[66:67], s[6:7], 0, v[62:63]
	v_lshl_add_u64 v[68:69], s[6:7], 0, v[64:65]
	global_load_lds_dwordx4 v64, s[6:7]
	s_add_i32 s20, s22, 0x4000
	s_mov_b64 s[6:7], 0x80
	s_add_i32 s23, s22, 0x6000
	v_lshl_add_u64 v[56:57], v[66:67], 0, s[6:7]
	s_mov_b32 m0, s20
	s_add_u32 s0, s10, 0x11620000
	global_load_lds_dwordx4 v[56:57], off
	v_lshl_add_u64 v[56:57], v[68:69], 0, s[6:7]
	s_mov_b32 m0, s23
	s_addc_u32 s1, s11, 0
	s_add_i32 s24, s22, 0x8000
	global_load_lds_dwordx4 v[56:57], off
	s_mov_b32 m0, s24
	s_add_i32 s25, s22, 0xa000
	global_load_lds_dwordx4 v62, s[0:1]
	s_mov_b32 m0, s25
	s_mov_b64 s[4:5], 0x180
	global_load_lds_dwordx4 v64, s[0:1]
	s_add_u32 s0, s10, 0x11620080
	s_addc_u32 s1, s11, 0
	s_add_i32 s26, s22, 0xc000
	s_mov_b32 m0, s26
	s_add_i32 s27, s22, 0xe000
	global_load_lds_dwordx4 v62, s[0:1]
	s_mov_b32 m0, s27
	s_add_u32 s8, s10, 0x11e00000
	global_load_lds_dwordx4 v64, s[0:1]
	s_addc_u32 s9, s11, 0
	s_add_i32 s19, s22, 0x10000
	s_mov_b64 s[0:1], 0x100
	v_lshl_add_u64 v[56:57], v[66:67], 0, s[0:1]
	s_mov_b32 m0, s19
	s_add_i32 s13, s22, 0x12000
	global_load_dwordx4 v[44:47], v[2:3], off offset:256
	global_load_dwordx4 v[40:43], v[2:3], off offset:320
	global_load_dwordx4 v[36:39], v[2:3], off offset:384
	global_load_dwordx4 v[32:35], v[2:3], off offset:448
	global_load_dwordx4 v[28:31], v[2:3], off offset:512
	global_load_dwordx4 v[24:27], v[2:3], off offset:576
	global_load_dwordx4 v[20:23], v[2:3], off offset:640
	global_load_dwordx4 v[16:19], v[2:3], off offset:704
	global_load_dwordx4 v[12:15], v[2:3], off offset:768
	global_load_dwordx4 v[8:11], v[2:3], off offset:832
	global_load_dwordx4 v[4:7], v[2:3], off offset:896
	s_nop 0
	global_load_dwordx4 v[0:3], v[2:3], off offset:960
	s_waitcnt vmcnt(12)
	s_waitcnt vmcnt(12) lgkmcnt(0)
	s_barrier
	global_load_lds_dwordx4 v[56:57], off
	v_lshl_add_u64 v[56:57], v[68:69], 0, s[0:1]
	s_mov_b32 m0, s13
	s_add_i32 s12, s22, 0x14000
	s_add_i32 s14, s22, 0x16000
	global_load_lds_dwordx4 v[56:57], off
	v_lshl_add_u64 v[56:57], v[66:67], 0, s[4:5]
	s_mov_b32 m0, s12
	s_add_u32 s28, s10, 0x11620100
	global_load_lds_dwordx4 v[56:57], off
	v_lshl_add_u64 v[56:57], v[68:69], 0, s[4:5]
	s_mov_b32 m0, s14
	s_addc_u32 s29, s11, 0
	s_add_i32 s15, s22, 0x18000
	global_load_lds_dwordx4 v[56:57], off
	s_mov_b32 m0, s15
	s_add_i32 s16, s22, 0x1a000
	global_load_lds_dwordx4 v62, s[28:29]
	s_mov_b32 m0, s16
	v_and_b32_e32 v57, 48, v58
	global_load_lds_dwordx4 v64, s[28:29]
	s_add_u32 s28, s10, 0x11620180
	s_addc_u32 s29, s11, 0
	s_add_i32 s17, s22, 0x1c000
	s_mov_b32 m0, s17
	s_add_i32 s18, s22, 0x1e000
	global_load_lds_dwordx4 v62, s[28:29]
	s_mov_b32 m0, s18
	v_lshlrev_b32_e32 v58, 2, v58
	global_load_lds_dwordx4 v64, s[28:29]
	v_lshlrev_b32_e32 v56, 6, v59
	v_and_b32_e32 v58, 32, v58
	v_bitop3_b32 v56, v56, v58, v57 bitop3:0x36
	v_and_b32_e32 v57, 0xfffffc00, v71
	v_add3_u32 v65, 0, v56, v57
	v_mov_b32_e32 v71, v65
	ds_read_b128 v[56:59], v71
	ds_read_b128 v[80:83], v71 offset:2048
	s_waitcnt lgkmcnt(0)
	v_mfma_f32_16x16x32_bf16 v[84:87], v[56:59], v[76:79], 0
	ds_read_b128 v[56:59], v71 offset:4096
	ds_read_b128 v[88:91], v71 offset:6144
	ds_read_b128 v[96:99], v71 offset:8192
	ds_read_b128 v[100:103], v71 offset:10240
	s_waitcnt lgkmcnt(0)
	v_mfma_f32_16x16x32_bf16 v[92:95], v[56:59], v[76:79], 0
	v_lshlrev_b32_e32 v56, 9, v104
	ds_read_b128 v[104:107], v71 offset:12288
	v_lshlrev_b32_e32 v57, 9, v108
	ds_read_b128 v[108:111], v71 offset:14336
	ds_read_b128 v[112:115], v71 offset:32768
	ds_read_b128 v[116:119], v71 offset:34816
	ds_read_b128 v[120:123], v71 offset:36864
	ds_read_b128 v[124:127], v71 offset:38912
	ds_read_b128 v[128:131], v71 offset:40960
	ds_read_b128 v[132:135], v71 offset:43008
	ds_read_b128 v[136:139], v71 offset:45056
	ds_read_b128 v[140:143], v71 offset:47104
	v_mfma_f32_16x16x32_bf16 v[80:83], v[80:83], v[76:79], 0
	v_sub_u32_e32 v56, v62, v56
	v_mov_b32_e32 v241, v56
	v_sub_u32_e32 v58, v64, v57
	v_mfma_f32_16x16x32_bf16 v[88:91], v[88:91], v[76:79], 0
	v_mfma_f32_16x16x32_bf16 v[96:99], v[96:99], v[76:79], 0
	v_mfma_f32_16x16x32_bf16 v[100:103], v[100:103], v[76:79], 0
	s_waitcnt lgkmcnt(0)
	v_mfma_f32_16x16x32_bf16 v[104:107], v[104:107], v[76:79], 0
	v_mfma_f32_16x16x32_bf16 v[108:111], v[108:111], v[76:79], 0
	ds_read_b128 v[144:147], v71 offset:15360
	ds_read_b128 v[148:151], v71 offset:13312
	ds_read_b128 v[152:155], v71 offset:11264
	ds_read_b128 v[156:159], v71 offset:9216
	ds_read_b128 v[160:163], v71 offset:7168
	ds_read_b128 v[164:167], v71 offset:5120
	ds_read_b128 v[168:171], v71 offset:3072
	ds_read_b128 v[172:175], v71 offset:1024
	v_mfma_f32_16x16x32_bf16 v[112:115], v[112:115], v[76:79], 0
	v_mfma_f32_16x16x32_bf16 v[116:119], v[116:119], v[76:79], 0
	v_mfma_f32_16x16x32_bf16 v[120:123], v[120:123], v[76:79], 0
	v_mfma_f32_16x16x32_bf16 v[124:127], v[124:127], v[76:79], 0
	v_mfma_f32_16x16x32_bf16 v[128:131], v[128:131], v[76:79], 0
	v_mfma_f32_16x16x32_bf16 v[132:135], v[132:135], v[76:79], 0
	v_mfma_f32_16x16x32_bf16 v[136:139], v[136:139], v[76:79], 0
	v_mfma_f32_16x16x32_bf16 v[76:79], v[140:143], v[76:79], 0
	s_waitcnt lgkmcnt(0)
	v_mfma_f32_16x16x32_bf16 v[84:87], v[172:175], v[72:75], v[84:87]
	v_mfma_f32_16x16x32_bf16 v[80:83], v[168:171], v[72:75], v[80:83]
	v_mfma_f32_16x16x32_bf16 v[92:95], v[164:167], v[72:75], v[92:95]
	v_mfma_f32_16x16x32_bf16 v[88:91], v[160:163], v[72:75], v[88:91]
	v_mfma_f32_16x16x32_bf16 v[96:99], v[156:159], v[72:75], v[96:99]
	v_mfma_f32_16x16x32_bf16 v[100:103], v[152:155], v[72:75], v[100:103]
	ds_read_b128 v[140:143], v71 offset:33792
	ds_read_b128 v[152:155], v71 offset:35840
	ds_read_b128 v[156:159], v71 offset:37888
	ds_read_b128 v[160:163], v71 offset:39936
	v_mfma_f32_16x16x32_bf16 v[104:107], v[148:151], v[72:75], v[104:107]
	ds_read_b128 v[148:151], v71 offset:41984
	ds_read_b128 v[164:167], v71 offset:44032
	ds_read_b128 v[168:171], v71 offset:46080
	ds_read_b128 v[172:175], v71 offset:48128
	v_mfma_f32_16x16x32_bf16 v[108:111], v[144:147], v[72:75], v[108:111]
	s_waitcnt lgkmcnt(0)
	v_mfma_f32_16x16x32_bf16 v[112:115], v[140:143], v[72:75], v[112:115]
	v_mfma_f32_16x16x32_bf16 v[116:119], v[152:155], v[72:75], v[116:119]
	v_mfma_f32_16x16x32_bf16 v[120:123], v[156:159], v[72:75], v[120:123]
	v_mfma_f32_16x16x32_bf16 v[124:127], v[160:163], v[72:75], v[124:127]
	v_mfma_f32_16x16x32_bf16 v[128:131], v[148:151], v[72:75], v[128:131]
	ds_read_b128 v[140:143], v71 offset:30720
	ds_read_b128 v[144:147], v71 offset:28672
	ds_read_b128 v[148:151], v71 offset:26624
	ds_read_b128 v[152:155], v71 offset:24576
	v_mfma_f32_16x16x32_bf16 v[132:135], v[164:167], v[72:75], v[132:135]
	v_mfma_f32_16x16x32_bf16 v[136:139], v[168:171], v[72:75], v[136:139]
	ds_read_b128 v[156:159], v71 offset:22528
	ds_read_b128 v[160:163], v71 offset:20480
	ds_read_b128 v[164:167], v71 offset:18432
	ds_read_b128 v[168:171], v71 offset:16384
	v_mfma_f32_16x16x32_bf16 v[72:75], v[172:175], v[72:75], v[76:79]
	s_waitcnt lgkmcnt(0)
	v_mfma_f32_16x16x32_bf16 v[76:79], v[168:171], v[52:55], v[84:87]
	v_mfma_f32_16x16x32_bf16 v[80:83], v[164:167], v[52:55], v[80:83]
	v_mfma_f32_16x16x32_bf16 v[84:87], v[160:163], v[52:55], v[92:95]
	v_mfma_f32_16x16x32_bf16 v[88:91], v[156:159], v[52:55], v[88:91]
	v_mfma_f32_16x16x32_bf16 v[92:95], v[152:155], v[52:55], v[96:99]
	v_mfma_f32_16x16x32_bf16 v[96:99], v[148:151], v[52:55], v[100:103]
	s_nop 2
	ds_read_b128 v[100:103], v71 offset:49152
	ds_read_b128 v[148:151], v71 offset:51200
	ds_read_b128 v[152:155], v71 offset:53248
	ds_read_b128 v[156:159], v71 offset:55296
	v_mfma_f32_16x16x32_bf16 v[104:107], v[144:147], v[52:55], v[104:107]
	ds_read_b128 v[144:147], v71 offset:57344
	ds_read_b128 v[160:163], v71 offset:59392
	ds_read_b128 v[164:167], v71 offset:61440
	ds_read_b128 v[168:171], v71 offset:63488
	v_mfma_f32_16x16x32_bf16 v[108:111], v[140:143], v[52:55], v[108:111]
	s_waitcnt lgkmcnt(0)
	v_mfma_f32_16x16x32_bf16 v[100:103], v[100:103], v[52:55], v[112:115]
	v_mfma_f32_16x16x32_bf16 v[112:115], v[148:151], v[52:55], v[116:119]
	v_mfma_f32_16x16x32_bf16 v[116:119], v[152:155], v[52:55], v[120:123]
	v_mfma_f32_16x16x32_bf16 v[120:123], v[156:159], v[52:55], v[124:127]
	v_mfma_f32_16x16x32_bf16 v[124:127], v[144:147], v[52:55], v[128:131]
	v_mfma_f32_16x16x32_bf16 v[128:131], v[160:163], v[52:55], v[132:135]
	s_nop 2
	ds_read_b128 v[132:135], v71 offset:31744
	ds_read_b128 v[140:143], v71 offset:29696
	ds_read_b128 v[144:147], v71 offset:27648
	ds_read_b128 v[148:151], v71 offset:25600
	v_mfma_f32_16x16x32_bf16 v[136:139], v[164:167], v[52:55], v[136:139]
	ds_read_b128 v[152:155], v71 offset:23552
	ds_read_b128 v[156:159], v71 offset:21504
	ds_read_b128 v[160:163], v71 offset:19456
	ds_read_b128 v[164:167], v71 offset:17408
	v_mfma_f32_16x16x32_bf16 v[52:55], v[168:171], v[52:55], v[72:75]
	s_waitcnt lgkmcnt(0)
	v_mfma_f32_16x16x32_bf16 v[72:75], v[164:167], v[48:51], v[76:79]
	v_mfma_f32_16x16x32_bf16 v[76:79], v[160:163], v[48:51], v[80:83]
	v_mfma_f32_16x16x32_bf16 v[80:83], v[156:159], v[48:51], v[84:87]
	v_mfma_f32_16x16x32_bf16 v[84:87], v[152:155], v[48:51], v[88:91]
	v_mfma_f32_16x16x32_bf16 v[88:91], v[148:151], v[48:51], v[92:95]
	v_mfma_f32_16x16x32_bf16 v[92:95], v[144:147], v[48:51], v[96:99]
	s_nop 2
	ds_read_b128 v[96:99], v71 offset:50176
	ds_read_b128 v[144:147], v71 offset:52224
	ds_read_b128 v[148:151], v71 offset:54272
	ds_read_b128 v[152:155], v71 offset:56320
	v_mfma_f32_16x16x32_bf16 v[104:107], v[140:143], v[48:51], v[104:107]
	ds_read_b128 v[140:143], v71 offset:58368
	ds_read_b128 v[156:159], v71 offset:60416
	ds_read_b128 v[160:163], v71 offset:62464
	ds_read_b128 v[164:167], v71 offset:64512
	v_mfma_f32_16x16x32_bf16 v[108:111], v[132:135], v[48:51], v[108:111]
	s_waitcnt lgkmcnt(0)
	v_mfma_f32_16x16x32_bf16 v[96:99], v[96:99], v[48:51], v[100:103]
	v_mfma_f32_16x16x32_bf16 v[100:103], v[144:147], v[48:51], v[112:115]
	v_mfma_f32_16x16x32_bf16 v[112:115], v[148:151], v[48:51], v[116:119]
	v_mfma_f32_16x16x32_bf16 v[116:119], v[152:155], v[48:51], v[120:123]
	v_mfma_f32_16x16x32_bf16 v[120:123], v[140:143], v[48:51], v[124:127]
	v_mfma_f32_16x16x32_bf16 v[124:127], v[156:159], v[48:51], v[128:131]
	v_mfma_f32_16x16x32_bf16 v[128:131], v[160:163], v[48:51], v[136:139]
	v_mfma_f32_16x16x32_bf16 v[50:53], v[164:167], v[48:51], v[52:55]
	s_waitcnt vmcnt(0)
	s_waitcnt vmcnt(0)
	s_barrier
	v_add_u32_e32 v48, 0x10000, v65
	v_mov_b32_e32 v49, v48
	ds_read_b128 v[132:135], v49
	ds_read_b128 v[136:139], v49 offset:2048
	s_waitcnt lgkmcnt(0)
	v_mfma_f32_16x16x32_bf16 v[72:75], v[132:135], v[44:47], v[72:75]
	ds_read_b128 v[132:135], v49 offset:4096
	v_mfma_f32_16x16x32_bf16 v[76:79], v[136:139], v[44:47], v[76:79]
	ds_read_b128 v[136:139], v49 offset:6144
	s_waitcnt lgkmcnt(0)
	v_mfma_f32_16x16x32_bf16 v[80:83], v[132:135], v[44:47], v[80:83]
	ds_read_b128 v[132:135], v49 offset:8192
	v_mfma_f32_16x16x32_bf16 v[84:87], v[136:139], v[44:47], v[84:87]
	ds_read_b128 v[136:139], v49 offset:10240
	s_waitcnt lgkmcnt(0)
	v_mfma_f32_16x16x32_bf16 v[88:91], v[132:135], v[44:47], v[88:91]
	ds_read_b128 v[132:135], v49 offset:12288
	ds_read_b128 v[140:143], v49 offset:14336
	v_mfma_f32_16x16x32_bf16 v[92:95], v[136:139], v[44:47], v[92:95]
	ds_read_b128 v[136:139], v49 offset:32768
	ds_read_b128 v[144:147], v49 offset:34816
	ds_read_b128 v[148:151], v49 offset:36864
	ds_read_b128 v[152:155], v49 offset:38912
	s_waitcnt lgkmcnt(0)
	v_mfma_f32_16x16x32_bf16 v[104:107], v[132:135], v[44:47], v[104:107]
	ds_read_b128 v[132:135], v49 offset:40960
	ds_read_b128 v[156:159], v49 offset:43008
	ds_read_b128 v[160:163], v49 offset:45056
	ds_read_b128 v[164:167], v49 offset:47104
	v_mfma_f32_16x16x32_bf16 v[108:111], v[140:143], v[44:47], v[108:111]
	s_add_u32 s100, s10, 0x11600200
	s_addc_u32 s101, s11, 0
	s_mov_b32 m0, s22
	s_nop 0
	global_load_lds_dwordx4 v240, s[100:101]
	v_mfma_f32_16x16x32_bf16 v[96:99], v[136:139], v[44:47], v[96:99]
	v_mfma_f32_16x16x32_bf16 v[100:103], v[144:147], v[44:47], v[100:103]
	v_mfma_f32_16x16x32_bf16 v[112:115], v[148:151], v[44:47], v[112:115]
	v_mfma_f32_16x16x32_bf16 v[116:119], v[152:155], v[44:47], v[116:119]
	s_waitcnt lgkmcnt(0)
	v_mfma_f32_16x16x32_bf16 v[120:123], v[132:135], v[44:47], v[120:123]
	ds_read_b128 v[132:135], v49 offset:15360
	ds_read_b128 v[136:139], v49 offset:13312
	ds_read_b128 v[140:143], v49 offset:11264
	ds_read_b128 v[144:147], v49 offset:9216
	v_mfma_f32_16x16x32_bf16 v[124:127], v[156:159], v[44:47], v[124:127]
	v_mfma_f32_16x16x32_bf16 v[128:131], v[160:163], v[44:47], v[128:131]
	ds_read_b128 v[148:151], v49 offset:7168
	ds_read_b128 v[152:155], v49 offset:5120
	ds_read_b128 v[156:159], v49 offset:3072
	ds_read_b128 v[160:163], v49 offset:1024
	v_mfma_f32_16x16x32_bf16 v[44:47], v[164:167], v[44:47], v[50:53]
	s_add_u32 s100, s10, 0x11610200
	s_addc_u32 s101, s11, 0
	s_mov_b32 m0, s21
	s_nop 0
	global_load_lds_dwordx4 v240, s[100:101]
	s_waitcnt lgkmcnt(0)
	v_mfma_f32_16x16x32_bf16 v[50:53], v[160:163], v[40:43], v[72:75]
	v_mfma_f32_16x16x32_bf16 v[72:75], v[156:159], v[40:43], v[76:79]
	v_mfma_f32_16x16x32_bf16 v[76:79], v[152:155], v[40:43], v[80:83]
	v_mfma_f32_16x16x32_bf16 v[80:83], v[148:151], v[40:43], v[84:87]
	v_mfma_f32_16x16x32_bf16 v[84:87], v[144:147], v[40:43], v[88:91]
	v_mfma_f32_16x16x32_bf16 v[88:91], v[140:143], v[40:43], v[92:95]
	s_nop 2
	ds_read_b128 v[92:95], v49 offset:33792
	ds_read_b128 v[140:143], v49 offset:35840
	ds_read_b128 v[144:147], v49 offset:37888
	ds_read_b128 v[148:151], v49 offset:39936
	v_mfma_f32_16x16x32_bf16 v[104:107], v[136:139], v[40:43], v[104:107]
	ds_read_b128 v[136:139], v49 offset:41984
	ds_read_b128 v[152:155], v49 offset:44032
	ds_read_b128 v[156:159], v49 offset:46080
	ds_read_b128 v[160:163], v49 offset:48128
	v_mfma_f32_16x16x32_bf16 v[108:111], v[132:135], v[40:43], v[108:111]
	s_add_u32 s100, s10, 0x11600280
	s_addc_u32 s101, s11, 0
	s_mov_b32 m0, s20
	s_nop 0
	global_load_lds_dwordx4 v240, s[100:101]
	s_waitcnt lgkmcnt(0)
	v_mfma_f32_16x16x32_bf16 v[92:95], v[92:95], v[40:43], v[96:99]
	v_mfma_f32_16x16x32_bf16 v[96:99], v[140:143], v[40:43], v[100:103]
	v_mfma_f32_16x16x32_bf16 v[100:103], v[144:147], v[40:43], v[112:115]
	v_mfma_f32_16x16x32_bf16 v[112:115], v[148:151], v[40:43], v[116:119]
	v_mfma_f32_16x16x32_bf16 v[116:119], v[136:139], v[40:43], v[120:123]
	v_mfma_f32_16x16x32_bf16 v[120:123], v[152:155], v[40:43], v[124:127]
	s_nop 2
	ds_read_b128 v[124:127], v49 offset:30720
	ds_read_b128 v[132:135], v49 offset:28672
	ds_read_b128 v[136:139], v49 offset:26624
	ds_read_b128 v[140:143], v49 offset:24576
	v_mfma_f32_16x16x32_bf16 v[128:131], v[156:159], v[40:43], v[128:131]
	ds_read_b128 v[144:147], v49 offset:22528
	ds_read_b128 v[148:151], v49 offset:20480
	ds_read_b128 v[152:155], v49 offset:18432
	ds_read_b128 v[156:159], v49 offset:16384
	v_mfma_f32_16x16x32_bf16 v[40:43], v[160:163], v[40:43], v[44:47]
	s_add_u32 s100, s10, 0x11610280
	s_addc_u32 s101, s11, 0
	s_mov_b32 m0, s23
	s_nop 0
	global_load_lds_dwordx4 v240, s[100:101]
	s_waitcnt lgkmcnt(0)
	v_mfma_f32_16x16x32_bf16 v[44:47], v[156:159], v[36:39], v[50:53]
	v_mfma_f32_16x16x32_bf16 v[50:53], v[152:155], v[36:39], v[72:75]
	v_mfma_f32_16x16x32_bf16 v[72:75], v[148:151], v[36:39], v[76:79]
	v_mfma_f32_16x16x32_bf16 v[76:79], v[144:147], v[36:39], v[80:83]
	v_mfma_f32_16x16x32_bf16 v[80:83], v[140:143], v[36:39], v[84:87]
	v_mfma_f32_16x16x32_bf16 v[84:87], v[136:139], v[36:39], v[88:91]
	s_nop 2
	ds_read_b128 v[88:91], v49 offset:49152
	ds_read_b128 v[136:139], v49 offset:51200
	ds_read_b128 v[140:143], v49 offset:53248
	ds_read_b128 v[144:147], v49 offset:55296
	v_mfma_f32_16x16x32_bf16 v[104:107], v[132:135], v[36:39], v[104:107]
	ds_read_b128 v[132:135], v49 offset:57344
	ds_read_b128 v[148:151], v49 offset:59392
	ds_read_b128 v[152:155], v49 offset:61440
	ds_read_b128 v[156:159], v49 offset:63488
	v_mfma_f32_16x16x32_bf16 v[108:111], v[124:127], v[36:39], v[108:111]
	s_add_u32 s100, s10, 0x11620200
	s_addc_u32 s101, s11, 0
	s_mov_b32 m0, s24
	s_nop 0
	global_load_lds_dwordx4 v240, s[100:101]
	s_waitcnt lgkmcnt(0)
	v_mfma_f32_16x16x32_bf16 v[88:91], v[88:91], v[36:39], v[92:95]
	v_mfma_f32_16x16x32_bf16 v[92:95], v[136:139], v[36:39], v[96:99]
	v_mfma_f32_16x16x32_bf16 v[96:99], v[140:143], v[36:39], v[100:103]
	v_mfma_f32_16x16x32_bf16 v[100:103], v[144:147], v[36:39], v[112:115]
	v_mfma_f32_16x16x32_bf16 v[112:115], v[132:135], v[36:39], v[116:119]
	v_mfma_f32_16x16x32_bf16 v[116:119], v[148:151], v[36:39], v[120:123]
	s_nop 2
	ds_read_b128 v[120:123], v49 offset:31744
	ds_read_b128 v[124:127], v49 offset:29696
	ds_read_b128 v[132:135], v49 offset:27648
	ds_read_b128 v[136:139], v49 offset:25600
	v_mfma_f32_16x16x32_bf16 v[128:131], v[152:155], v[36:39], v[128:131]
	ds_read_b128 v[140:143], v49 offset:23552
	ds_read_b128 v[144:147], v49 offset:21504
	ds_read_b128 v[148:151], v49 offset:19456
	ds_read_b128 v[152:155], v49 offset:17408
	v_mfma_f32_16x16x32_bf16 v[36:39], v[156:159], v[36:39], v[40:43]
	s_add_u32 s100, s10, 0x11630200
	s_addc_u32 s101, s11, 0
	s_mov_b32 m0, s25
	s_nop 0
	global_load_lds_dwordx4 v240, s[100:101]
	s_waitcnt lgkmcnt(0)
	v_mfma_f32_16x16x32_bf16 v[40:43], v[152:155], v[32:35], v[44:47]
	v_mfma_f32_16x16x32_bf16 v[44:47], v[148:151], v[32:35], v[50:53]
	v_mfma_f32_16x16x32_bf16 v[50:53], v[144:147], v[32:35], v[72:75]
	v_mfma_f32_16x16x32_bf16 v[72:75], v[140:143], v[32:35], v[76:79]
	v_mfma_f32_16x16x32_bf16 v[76:79], v[136:139], v[32:35], v[80:83]
	v_mfma_f32_16x16x32_bf16 v[80:83], v[132:135], v[32:35], v[84:87]
	s_nop 2
	ds_read_b128 v[84:87], v49 offset:50176
	ds_read_b128 v[132:135], v49 offset:52224
	ds_read_b128 v[136:139], v49 offset:54272
	ds_read_b128 v[140:143], v49 offset:56320
	v_mfma_f32_16x16x32_bf16 v[104:107], v[124:127], v[32:35], v[104:107]
	ds_read_b128 v[124:127], v49 offset:58368
	ds_read_b128 v[144:147], v49 offset:60416
	ds_read_b128 v[148:151], v49 offset:62464
	ds_read_b128 v[152:155], v49 offset:64512
	v_mfma_f32_16x16x32_bf16 v[108:111], v[120:123], v[32:35], v[108:111]
	s_add_u32 s100, s10, 0x11620280
	s_addc_u32 s101, s11, 0
	s_mov_b32 m0, s26
	s_nop 0
	global_load_lds_dwordx4 v240, s[100:101]
	s_waitcnt lgkmcnt(0)
	v_mfma_f32_16x16x32_bf16 v[84:87], v[84:87], v[32:35], v[88:91]
	v_mfma_f32_16x16x32_bf16 v[88:91], v[132:135], v[32:35], v[92:95]
	v_mfma_f32_16x16x32_bf16 v[92:95], v[136:139], v[32:35], v[96:99]
	v_mfma_f32_16x16x32_bf16 v[96:99], v[140:143], v[32:35], v[100:103]
	v_mfma_f32_16x16x32_bf16 v[100:103], v[124:127], v[32:35], v[112:115]
	v_mfma_f32_16x16x32_bf16 v[112:115], v[144:147], v[32:35], v[116:119]
	v_mfma_f32_16x16x32_bf16 v[116:119], v[148:151], v[32:35], v[128:131]
	v_mfma_f32_16x16x32_bf16 v[32:35], v[152:155], v[32:35], v[36:39]
	s_add_u32 s100, s10, 0x11630280
	s_addc_u32 s101, s11, 0
	s_mov_b32 m0, s27
	s_nop 0
	global_load_lds_dwordx4 v240, s[100:101]
	s_nop 0
	s_waitcnt vmcnt(0)
	s_waitcnt vmcnt(0)
	s_barrier
	v_mov_b32_e32 v49, v65
	ds_read_b128 v[36:39], v49
	ds_read_b128 v[66:69], v49 offset:2048
	s_waitcnt lgkmcnt(0)
	v_mfma_f32_16x16x32_bf16 v[36:39], v[36:39], v[28:31], v[40:43]
	s_nop 2
	ds_read_b128 v[40:43], v49 offset:4096
	v_mfma_f32_16x16x32_bf16 v[44:47], v[66:69], v[28:31], v[44:47]
	ds_read_b128 v[66:69], v49 offset:6144
	s_waitcnt lgkmcnt(0)
	v_mfma_f32_16x16x32_bf16 v[40:43], v[40:43], v[28:31], v[50:53]
	s_nop 2
	ds_read_b128 v[50:53], v49 offset:8192
	v_mfma_f32_16x16x32_bf16 v[66:69], v[66:69], v[28:31], v[72:75]
	s_nop 2
	ds_read_b128 v[72:75], v49 offset:10240
	s_waitcnt lgkmcnt(0)
	v_mfma_f32_16x16x32_bf16 v[50:53], v[50:53], v[28:31], v[76:79]
	s_nop 2
	ds_read_b128 v[76:79], v49 offset:12288
	ds_read_b128 v[120:123], v49 offset:14336
	v_mfma_f32_16x16x32_bf16 v[72:75], v[72:75], v[28:31], v[80:83]
	s_nop 2
	ds_read_b128 v[80:83], v49 offset:32768
	ds_read_b128 v[124:127], v49 offset:34816
	ds_read_b128 v[128:131], v49 offset:36864
	ds_read_b128 v[132:135], v49 offset:38912
	s_waitcnt lgkmcnt(0)
	v_mfma_f32_16x16x32_bf16 v[76:79], v[76:79], v[28:31], v[104:107]
	s_nop 2
	ds_read_b128 v[104:107], v49 offset:40960
	ds_read_b128 v[136:139], v49 offset:43008
	ds_read_b128 v[140:143], v49 offset:45056
	ds_read_b128 v[144:147], v49 offset:47104
	v_mfma_f32_16x16x32_bf16 v[108:111], v[120:123], v[28:31], v[108:111]
	s_add_u32 s100, s10, 0x11600300
	s_addc_u32 s101, s11, 0
	s_mov_b32 m0, s19
	s_nop 0
	global_load_lds_dwordx4 v240, s[100:101]
	v_mfma_f32_16x16x32_bf16 v[80:83], v[80:83], v[28:31], v[84:87]
	v_mfma_f32_16x16x32_bf16 v[84:87], v[124:127], v[28:31], v[88:91]
	v_mfma_f32_16x16x32_bf16 v[88:91], v[128:131], v[28:31], v[92:95]
	v_mfma_f32_16x16x32_bf16 v[92:95], v[132:135], v[28:31], v[96:99]
	s_waitcnt lgkmcnt(0)
	v_mfma_f32_16x16x32_bf16 v[96:99], v[104:107], v[28:31], v[100:103]
	v_mfma_f32_16x16x32_bf16 v[100:103], v[136:139], v[28:31], v[112:115]
	ds_read_b128 v[104:107], v49 offset:15360
	s_nop 1
	ds_read_b128 v[112:115], v49 offset:13312
	ds_read_b128 v[120:123], v49 offset:11264
	ds_read_b128 v[124:127], v49 offset:9216
	v_mfma_f32_16x16x32_bf16 v[116:119], v[140:143], v[28:31], v[116:119]
	ds_read_b128 v[128:131], v49 offset:7168
	ds_read_b128 v[132:135], v49 offset:5120
	ds_read_b128 v[136:139], v49 offset:3072
	ds_read_b128 v[140:143], v49 offset:1024
	v_mfma_f32_16x16x32_bf16 v[28:31], v[144:147], v[28:31], v[32:35]
	s_add_u32 s100, s10, 0x11610300
	s_addc_u32 s101, s11, 0
	s_mov_b32 m0, s13
	s_nop 0
	global_load_lds_dwordx4 v240, s[100:101]
	s_waitcnt lgkmcnt(0)
	v_mfma_f32_16x16x32_bf16 v[32:35], v[140:143], v[24:27], v[36:39]
	v_mfma_f32_16x16x32_bf16 v[36:39], v[136:139], v[24:27], v[44:47]
	v_mfma_f32_16x16x32_bf16 v[40:43], v[132:135], v[24:27], v[40:43]
	v_mfma_f32_16x16x32_bf16 v[44:47], v[128:131], v[24:27], v[66:69]
	v_mfma_f32_16x16x32_bf16 v[50:53], v[124:127], v[24:27], v[50:53]
	v_mfma_f32_16x16x32_bf16 v[66:69], v[120:123], v[24:27], v[72:75]
	s_nop 2
	ds_read_b128 v[72:75], v49 offset:33792
	ds_read_b128 v[120:123], v49 offset:35840
	ds_read_b128 v[124:127], v49 offset:37888
	ds_read_b128 v[128:131], v49 offset:39936
	v_mfma_f32_16x16x32_bf16 v[76:79], v[112:115], v[24:27], v[76:79]
	ds_read_b128 v[112:115], v49 offset:41984
	ds_read_b128 v[132:135], v49 offset:44032
	ds_read_b128 v[136:139], v49 offset:46080
	ds_read_b128 v[140:143], v49 offset:48128
	v_mfma_f32_16x16x32_bf16 v[104:107], v[104:107], v[24:27], v[108:111]
	s_add_u32 s100, s10, 0x11600380
	s_addc_u32 s101, s11, 0
	s_mov_b32 m0, s12
	s_nop 0
	global_load_lds_dwordx4 v240, s[100:101]
	s_waitcnt lgkmcnt(0)
	v_mfma_f32_16x16x32_bf16 v[72:75], v[72:75], v[24:27], v[80:83]
	v_mfma_f32_16x16x32_bf16 v[80:83], v[120:123], v[24:27], v[84:87]
	v_mfma_f32_16x16x32_bf16 v[84:87], v[124:127], v[24:27], v[88:91]
	v_mfma_f32_16x16x32_bf16 v[88:91], v[128:131], v[24:27], v[92:95]
	v_mfma_f32_16x16x32_bf16 v[92:95], v[112:115], v[24:27], v[96:99]
	v_mfma_f32_16x16x32_bf16 v[96:99], v[132:135], v[24:27], v[100:103]
	s_nop 2
	ds_read_b128 v[100:103], v49 offset:30720
	ds_read_b128 v[108:111], v49 offset:28672
	ds_read_b128 v[112:115], v49 offset:26624
	ds_read_b128 v[120:123], v49 offset:24576
	v_mfma_f32_16x16x32_bf16 v[116:119], v[136:139], v[24:27], v[116:119]
	ds_read_b128 v[124:127], v49 offset:22528
	ds_read_b128 v[128:131], v49 offset:20480
	ds_read_b128 v[132:135], v49 offset:18432
	ds_read_b128 v[136:139], v49 offset:16384
	v_mfma_f32_16x16x32_bf16 v[24:27], v[140:143], v[24:27], v[28:31]
	s_add_u32 s100, s10, 0x11610380
	s_addc_u32 s101, s11, 0
	s_mov_b32 m0, s14
	s_nop 0
	global_load_lds_dwordx4 v240, s[100:101]
	s_waitcnt lgkmcnt(0)
	v_mfma_f32_16x16x32_bf16 v[28:31], v[136:139], v[20:23], v[32:35]
	v_mfma_f32_16x16x32_bf16 v[32:35], v[132:135], v[20:23], v[36:39]
	v_mfma_f32_16x16x32_bf16 v[36:39], v[128:131], v[20:23], v[40:43]
	v_mfma_f32_16x16x32_bf16 v[40:43], v[124:127], v[20:23], v[44:47]
	v_mfma_f32_16x16x32_bf16 v[44:47], v[120:123], v[20:23], v[50:53]
	v_mfma_f32_16x16x32_bf16 v[50:53], v[112:115], v[20:23], v[66:69]
	s_nop 2
	ds_read_b128 v[66:69], v49 offset:49152
	ds_read_b128 v[112:115], v49 offset:51200
	ds_read_b128 v[120:123], v49 offset:53248
	ds_read_b128 v[124:127], v49 offset:55296
	v_mfma_f32_16x16x32_bf16 v[76:79], v[108:111], v[20:23], v[76:79]
	ds_read_b128 v[108:111], v49 offset:57344
	ds_read_b128 v[128:131], v49 offset:59392
	ds_read_b128 v[132:135], v49 offset:61440
	ds_read_b128 v[136:139], v49 offset:63488
	v_mfma_f32_16x16x32_bf16 v[100:103], v[100:103], v[20:23], v[104:107]
	s_add_u32 s100, s10, 0x11620300
	s_addc_u32 s101, s11, 0
	s_mov_b32 m0, s15
	s_nop 0
	global_load_lds_dwordx4 v240, s[100:101]
	s_waitcnt lgkmcnt(0)
	v_mfma_f32_16x16x32_bf16 v[66:69], v[66:69], v[20:23], v[72:75]
	v_mfma_f32_16x16x32_bf16 v[72:75], v[112:115], v[20:23], v[80:83]
	v_mfma_f32_16x16x32_bf16 v[80:83], v[120:123], v[20:23], v[84:87]
	v_mfma_f32_16x16x32_bf16 v[84:87], v[124:127], v[20:23], v[88:91]
	v_mfma_f32_16x16x32_bf16 v[88:91], v[108:111], v[20:23], v[92:95]
	v_mfma_f32_16x16x32_bf16 v[92:95], v[128:131], v[20:23], v[96:99]
	s_nop 2
	ds_read_b128 v[96:99], v49 offset:31744
	ds_read_b128 v[104:107], v49 offset:29696
	ds_read_b128 v[108:111], v49 offset:27648
	ds_read_b128 v[112:115], v49 offset:25600
	v_mfma_f32_16x16x32_bf16 v[116:119], v[132:135], v[20:23], v[116:119]
	ds_read_b128 v[120:123], v49 offset:23552
	ds_read_b128 v[124:127], v49 offset:21504
	ds_read_b128 v[128:131], v49 offset:19456
	ds_read_b128 v[132:135], v49 offset:17408
	v_mfma_f32_16x16x32_bf16 v[20:23], v[136:139], v[20:23], v[24:27]
	s_add_u32 s100, s10, 0x11630300
	s_addc_u32 s101, s11, 0
	s_mov_b32 m0, s16
	s_nop 0
	global_load_lds_dwordx4 v240, s[100:101]
	s_waitcnt lgkmcnt(0)
	v_mfma_f32_16x16x32_bf16 v[24:27], v[132:135], v[16:19], v[28:31]
	v_mfma_f32_16x16x32_bf16 v[28:31], v[128:131], v[16:19], v[32:35]
	v_mfma_f32_16x16x32_bf16 v[32:35], v[124:127], v[16:19], v[36:39]
	v_mfma_f32_16x16x32_bf16 v[36:39], v[120:123], v[16:19], v[40:43]
	v_mfma_f32_16x16x32_bf16 v[40:43], v[112:115], v[16:19], v[44:47]
	v_mfma_f32_16x16x32_bf16 v[50:53], v[108:111], v[16:19], v[50:53]
	s_nop 1
	ds_read_b128 v[44:47], v49 offset:50176
	ds_read_b128 v[108:111], v49 offset:52224
	ds_read_b128 v[112:115], v49 offset:54272
	ds_read_b128 v[120:123], v49 offset:56320
	v_mfma_f32_16x16x32_bf16 v[76:79], v[104:107], v[16:19], v[76:79]
	ds_read_b128 v[104:107], v49 offset:58368
	ds_read_b128 v[124:127], v49 offset:60416
	ds_read_b128 v[128:131], v49 offset:62464
	ds_read_b128 v[132:135], v49 offset:64512
	v_mfma_f32_16x16x32_bf16 v[96:99], v[96:99], v[16:19], v[100:103]
	s_add_u32 s100, s10, 0x11620380
	s_addc_u32 s101, s11, 0
	s_mov_b32 m0, s17
	s_nop 0
	global_load_lds_dwordx4 v240, s[100:101]
	s_waitcnt lgkmcnt(0)
	v_mfma_f32_16x16x32_bf16 v[66:69], v[44:47], v[16:19], v[66:69]
	v_mfma_f32_16x16x32_bf16 v[72:75], v[108:111], v[16:19], v[72:75]
	v_mfma_f32_16x16x32_bf16 v[80:83], v[112:115], v[16:19], v[80:83]
	v_mfma_f32_16x16x32_bf16 v[84:87], v[120:123], v[16:19], v[84:87]
	v_mfma_f32_16x16x32_bf16 v[88:91], v[104:107], v[16:19], v[88:91]
	v_mfma_f32_16x16x32_bf16 v[92:95], v[124:127], v[16:19], v[92:95]
	v_mfma_f32_16x16x32_bf16 v[100:103], v[128:131], v[16:19], v[116:119]
	v_mfma_f32_16x16x32_bf16 v[16:19], v[132:135], v[16:19], v[20:23]
	s_add_u32 s100, s10, 0x11630380
	s_addc_u32 s101, s11, 0
	s_mov_b32 m0, s18
	s_nop 0
	global_load_lds_dwordx4 v240, s[100:101]
	s_waitcnt vmcnt(0)
	s_waitcnt vmcnt(0)
	s_barrier
	v_mov_b32_e32 v49, v48
	ds_read_b128 v[20:23], v49
	ds_read_b128 v[104:107], v49 offset:2048
	s_waitcnt lgkmcnt(0)
	v_mfma_f32_16x16x32_bf16 v[20:23], v[20:23], v[12:15], v[24:27]
	s_nop 2
	ds_read_b128 v[24:27], v49 offset:4096
	v_mfma_f32_16x16x32_bf16 v[28:31], v[104:107], v[12:15], v[28:31]
	ds_read_b128 v[104:107], v49 offset:6144
	s_waitcnt lgkmcnt(0)
	v_mfma_f32_16x16x32_bf16 v[24:27], v[24:27], v[12:15], v[32:35]
	s_nop 2
	ds_read_b128 v[32:35], v49 offset:8192
	v_mfma_f32_16x16x32_bf16 v[36:39], v[104:107], v[12:15], v[36:39]
	ds_read_b128 v[104:107], v49 offset:10240
	s_waitcnt lgkmcnt(0)
	v_mfma_f32_16x16x32_bf16 v[32:35], v[32:35], v[12:15], v[40:43]
	s_nop 2
	ds_read_b128 v[40:43], v49 offset:12288
	ds_read_b128 v[108:111], v49 offset:14336
	v_mfma_f32_16x16x32_bf16 v[50:53], v[104:107], v[12:15], v[50:53]
	ds_read_b128 v[104:107], v49 offset:32768
	ds_read_b128 v[112:115], v49 offset:34816
	ds_read_b128 v[116:119], v49 offset:36864
	ds_read_b128 v[120:123], v49 offset:38912
	s_waitcnt lgkmcnt(0)
	v_mfma_f32_16x16x32_bf16 v[40:43], v[40:43], v[12:15], v[76:79]
	s_nop 2
	ds_read_b128 v[76:79], v49 offset:40960
	ds_read_b128 v[124:127], v49 offset:43008
	ds_read_b128 v[128:131], v49 offset:45056
	ds_read_b128 v[132:135], v49 offset:47104
	v_mfma_f32_16x16x32_bf16 v[96:99], v[108:111], v[12:15], v[96:99]
	s_add_u32 s100, s10, 0x11e00000
	s_addc_u32 s101, s11, 0
	s_mov_b32 m0, s22
	s_nop 0
	global_load_lds_dwordx4 v241, s[100:101]
	v_mfma_f32_16x16x32_bf16 v[66:69], v[104:107], v[12:15], v[66:69]
	v_mfma_f32_16x16x32_bf16 v[72:75], v[112:115], v[12:15], v[72:75]
	v_mfma_f32_16x16x32_bf16 v[80:83], v[116:119], v[12:15], v[80:83]
	v_mfma_f32_16x16x32_bf16 v[84:87], v[120:123], v[12:15], v[84:87]
	s_waitcnt lgkmcnt(0)
	v_mfma_f32_16x16x32_bf16 v[76:79], v[76:79], v[12:15], v[88:91]
	v_mfma_f32_16x16x32_bf16 v[88:91], v[124:127], v[12:15], v[92:95]
	s_nop 2
	ds_read_b128 v[92:95], v49 offset:15360
	ds_read_b128 v[104:107], v49 offset:13312
	ds_read_b128 v[108:111], v49 offset:11264
	ds_read_b128 v[112:115], v49 offset:9216
	v_mfma_f32_16x16x32_bf16 v[100:103], v[128:131], v[12:15], v[100:103]
	ds_read_b128 v[116:119], v49 offset:7168
	ds_read_b128 v[120:123], v49 offset:5120
	ds_read_b128 v[124:127], v49 offset:3072
	ds_read_b128 v[128:131], v49 offset:1024
	v_mfma_f32_16x16x32_bf16 v[12:15], v[132:135], v[12:15], v[16:19]
	s_add_u32 s100, s10, 0x11e08000
	s_addc_u32 s101, s11, 0
	s_mov_b32 m0, s21
	s_nop 0
	global_load_lds_dwordx4 v241, s[100:101]
	s_waitcnt lgkmcnt(0)
	v_mfma_f32_16x16x32_bf16 v[16:19], v[128:131], v[8:11], v[20:23]
	v_mfma_f32_16x16x32_bf16 v[20:23], v[124:127], v[8:11], v[28:31]
	v_mfma_f32_16x16x32_bf16 v[24:27], v[120:123], v[8:11], v[24:27]
	v_mfma_f32_16x16x32_bf16 v[28:31], v[116:119], v[8:11], v[36:39]
	v_mfma_f32_16x16x32_bf16 v[32:35], v[112:115], v[8:11], v[32:35]
	v_mfma_f32_16x16x32_bf16 v[36:39], v[108:111], v[8:11], v[50:53]
	s_nop 2
	ds_read_b128 v[50:53], v49 offset:33792
	ds_read_b128 v[108:111], v49 offset:35840
	ds_read_b128 v[112:115], v49 offset:37888
	ds_read_b128 v[116:119], v49 offset:39936
	v_mfma_f32_16x16x32_bf16 v[40:43], v[104:107], v[8:11], v[40:43]
	ds_read_b128 v[104:107], v49 offset:41984
	ds_read_b128 v[120:123], v49 offset:44032
	ds_read_b128 v[124:127], v49 offset:46080
	ds_read_b128 v[128:131], v49 offset:48128
	v_mfma_f32_16x16x32_bf16 v[92:95], v[92:95], v[8:11], v[96:99]
	s_add_u32 s100, s10, 0x11e00080
	s_addc_u32 s101, s11, 0
	s_mov_b32 m0, s20
	s_nop 0
	global_load_lds_dwordx4 v241, s[100:101]
	s_waitcnt lgkmcnt(0)
	v_mfma_f32_16x16x32_bf16 v[50:53], v[50:53], v[8:11], v[66:69]
	v_mfma_f32_16x16x32_bf16 v[66:69], v[108:111], v[8:11], v[72:75]
	v_mfma_f32_16x16x32_bf16 v[72:75], v[112:115], v[8:11], v[80:83]
	v_mfma_f32_16x16x32_bf16 v[80:83], v[116:119], v[8:11], v[84:87]
	v_mfma_f32_16x16x32_bf16 v[76:79], v[104:107], v[8:11], v[76:79]
	v_mfma_f32_16x16x32_bf16 v[84:87], v[120:123], v[8:11], v[88:91]
	s_nop 2
	ds_read_b128 v[88:91], v49 offset:30720
	ds_read_b128 v[96:99], v49 offset:28672
	ds_read_b128 v[104:107], v49 offset:26624
	ds_read_b128 v[108:111], v49 offset:24576
	v_mfma_f32_16x16x32_bf16 v[100:103], v[124:127], v[8:11], v[100:103]
	ds_read_b128 v[112:115], v49 offset:22528
	ds_read_b128 v[116:119], v49 offset:20480
	ds_read_b128 v[120:123], v49 offset:18432
	ds_read_b128 v[124:127], v49 offset:16384
	v_mfma_f32_16x16x32_bf16 v[8:11], v[128:131], v[8:11], v[12:15]
	s_add_u32 s100, s10, 0x11e08080
	s_addc_u32 s101, s11, 0
	s_mov_b32 m0, s23
	s_nop 0
	global_load_lds_dwordx4 v241, s[100:101]
	s_waitcnt lgkmcnt(0)
	v_mfma_f32_16x16x32_bf16 v[12:15], v[124:127], v[4:7], v[16:19]
	v_mfma_f32_16x16x32_bf16 v[16:19], v[120:123], v[4:7], v[20:23]
	v_mfma_f32_16x16x32_bf16 v[20:23], v[116:119], v[4:7], v[24:27]
	v_mfma_f32_16x16x32_bf16 v[24:27], v[112:115], v[4:7], v[28:31]
	v_mfma_f32_16x16x32_bf16 v[28:31], v[108:111], v[4:7], v[32:35]
	v_mfma_f32_16x16x32_bf16 v[32:35], v[104:107], v[4:7], v[36:39]
	s_nop 2
	ds_read_b128 v[36:39], v49 offset:49152
	ds_read_b128 v[104:107], v49 offset:51200
	ds_read_b128 v[108:111], v49 offset:53248
	ds_read_b128 v[112:115], v49 offset:55296
	v_mfma_f32_16x16x32_bf16 v[96:99], v[96:99], v[4:7], v[40:43]
	s_nop 2
	ds_read_b128 v[40:43], v49 offset:57344
	ds_read_b128 v[116:119], v49 offset:59392
	ds_read_b128 v[120:123], v49 offset:61440
	ds_read_b128 v[124:127], v49 offset:63488
	v_mfma_f32_16x16x32_bf16 v[88:91], v[88:91], v[4:7], v[92:95]
	s_add_u32 s100, s10, 0x11e10000
	s_addc_u32 s101, s11, 0
	s_mov_b32 m0, s24
	s_nop 0
	global_load_lds_dwordx4 v241, s[100:101]
	s_waitcnt lgkmcnt(0)
	v_mfma_f32_16x16x32_bf16 v[50:53], v[36:39], v[4:7], v[50:53]
	v_mfma_f32_16x16x32_bf16 v[66:69], v[104:107], v[4:7], v[66:69]
	v_mfma_f32_16x16x32_bf16 v[72:75], v[108:111], v[4:7], v[72:75]
	v_mfma_f32_16x16x32_bf16 v[80:83], v[112:115], v[4:7], v[80:83]
	v_mfma_f32_16x16x32_bf16 v[76:79], v[40:43], v[4:7], v[76:79]
	ds_read_b128 v[92:95], v49 offset:31744
	ds_read_b128 v[36:39], v49 offset:29696
	ds_read_b128 v[40:43], v49 offset:27648
	ds_read_b128 v[104:107], v49 offset:25600
	v_mfma_f32_16x16x32_bf16 v[84:87], v[116:119], v[4:7], v[84:87]
	v_mfma_f32_16x16x32_bf16 v[100:103], v[120:123], v[4:7], v[100:103]
	ds_read_b128 v[108:111], v49 offset:23552
	ds_read_b128 v[112:115], v49 offset:21504
	ds_read_b128 v[116:119], v49 offset:19456
	ds_read_b128 v[120:123], v49 offset:17408
	v_mfma_f32_16x16x32_bf16 v[124:127], v[124:127], v[4:7], v[8:11]
	s_add_u32 s100, s10, 0x11e18000
	s_addc_u32 s101, s11, 0
	s_mov_b32 m0, s25
	s_nop 0
	global_load_lds_dwordx4 v241, s[100:101]
	s_waitcnt lgkmcnt(0)
	v_mfma_f32_16x16x32_bf16 v[120:123], v[120:123], v[0:3], v[12:15]
	v_mfma_f32_16x16x32_bf16 v[116:119], v[116:119], v[0:3], v[16:19]
	ds_read_b128 v[4:7], v49 offset:50176
	ds_read_b128 v[8:11], v49 offset:52224
	ds_read_b128 v[12:15], v49 offset:54272
	ds_read_b128 v[16:19], v49 offset:56320
	v_mfma_f32_16x16x32_bf16 v[36:39], v[36:39], v[0:3], v[96:99]
	s_nop 2
	ds_read_b128 v[96:99], v49 offset:58368
	ds_read_b128 v[128:131], v49 offset:60416
	ds_read_b128 v[132:135], v49 offset:62464
	ds_read_b128 v[136:139], v49 offset:64512
	v_mfma_f32_16x16x32_bf16 v[112:115], v[112:115], v[0:3], v[20:23]
	v_mfma_f32_16x16x32_bf16 v[108:111], v[108:111], v[0:3], v[24:27]
	v_mfma_f32_16x16x32_bf16 v[104:107], v[104:107], v[0:3], v[28:31]
	v_mfma_f32_16x16x32_bf16 v[40:43], v[40:43], v[0:3], v[32:35]
	v_mfma_f32_16x16x32_bf16 v[32:35], v[92:95], v[0:3], v[88:91]
	s_add_u32 s100, s10, 0x11e10080
	s_addc_u32 s101, s11, 0
	s_mov_b32 m0, s26
	s_nop 0
	global_load_lds_dwordx4 v241, s[100:101]
	s_waitcnt lgkmcnt(0)
	v_mfma_f32_16x16x32_bf16 v[28:31], v[4:7], v[0:3], v[50:53]
	v_mfma_f32_16x16x32_bf16 v[24:27], v[8:11], v[0:3], v[66:69]
	v_mfma_f32_16x16x32_bf16 v[20:23], v[12:15], v[0:3], v[72:75]
	v_mfma_f32_16x16x32_bf16 v[16:19], v[16:19], v[0:3], v[80:83]
	v_mfma_f32_16x16x32_bf16 v[12:15], v[96:99], v[0:3], v[76:79]
	v_mfma_f32_16x16x32_bf16 v[8:11], v[128:131], v[0:3], v[84:87]
	v_mfma_f32_16x16x32_bf16 v[4:7], v[132:135], v[0:3], v[100:103]
	v_mfma_f32_16x16x32_bf16 v[0:3], v[136:139], v[0:3], v[124:127]
	s_add_u32 s100, s10, 0x11e18080
	s_addc_u32 s101, s11, 0
	s_mov_b32 m0, s27
	s_nop 0
	global_load_lds_dwordx4 v241, s[100:101]
	v_max_f32_e32 v49, v123, v123
	v_max_f32_e32 v50, v122, v122
	v_max_f32_e32 v49, v50, v49
	v_max_f32_e32 v50, v117, v117
	v_max_f32_e32 v51, v116, v116
	v_max_f32_e32 v50, v51, v50
	v_max_f32_e32 v51, v119, v119
	v_max_f32_e32 v52, v118, v118
	v_max3_f32 v49, v120, v121, v49
	v_max_f32_e32 v51, v52, v51
	v_max3_f32 v49, v49, v50, v51
	v_max_f32_e32 v50, v113, v113
	v_max_f32_e32 v51, v112, v112
	v_max_f32_e32 v50, v51, v50
	v_max_f32_e32 v51, v115, v115
	v_max_f32_e32 v52, v114, v114
	v_max_f32_e32 v51, v52, v51
	v_max3_f32 v49, v49, v50, v51
	v_max_f32_e32 v50, v109, v109
	v_max_f32_e32 v51, v108, v108
	v_max_f32_e32 v50, v51, v50
	v_max_f32_e32 v51, v111, v111
	v_max_f32_e32 v52, v110, v110
	v_max_f32_e32 v51, v52, v51
	v_max3_f32 v49, v49, v50, v51
	v_max_f32_e32 v50, v105, v105
	v_max_f32_e32 v51, v104, v104
	v_max_f32_e32 v50, v51, v50
	v_max_f32_e32 v51, v107, v107
	v_max_f32_e32 v52, v106, v106
	v_max_f32_e32 v51, v52, v51
	v_max3_f32 v49, v49, v50, v51
	v_max_f32_e32 v50, v41, v41
	v_max_f32_e32 v51, v40, v40
	v_max_f32_e32 v50, v51, v50
	v_max_f32_e32 v51, v43, v43
	v_max_f32_e32 v52, v42, v42
	v_max_f32_e32 v51, v52, v51
	v_max3_f32 v49, v49, v50, v51
	v_max_f32_e32 v50, v37, v37
	v_max_f32_e32 v51, v36, v36
	v_max_f32_e32 v50, v51, v50
	v_max_f32_e32 v51, v39, v39
	v_max_f32_e32 v52, v38, v38
	v_max_f32_e32 v51, v52, v51
	v_max3_f32 v49, v49, v50, v51
	v_max_f32_e32 v50, v33, v33
	v_max_f32_e32 v51, v32, v32
	v_max_f32_e32 v50, v51, v50
	v_max_f32_e32 v51, v35, v35
	v_max_f32_e32 v52, v34, v34
	v_max_f32_e32 v51, v52, v51
	v_max3_f32 v49, v49, v50, v51
	v_max_f32_e32 v50, v29, v29
	v_max_f32_e32 v51, v28, v28
	v_max_f32_e32 v50, v51, v50
	v_max_f32_e32 v51, v31, v31
	v_max_f32_e32 v52, v30, v30
	v_max_f32_e32 v51, v52, v51
	v_max3_f32 v49, v49, v50, v51
	v_max_f32_e32 v50, v25, v25
	v_max_f32_e32 v51, v24, v24
	v_max_f32_e32 v50, v51, v50
	v_max_f32_e32 v51, v27, v27
	v_max_f32_e32 v52, v26, v26
	v_max_f32_e32 v51, v52, v51
	v_max3_f32 v49, v49, v50, v51
	v_max_f32_e32 v50, v21, v21
	v_max_f32_e32 v51, v20, v20
	v_max_f32_e32 v50, v51, v50
	v_max_f32_e32 v51, v23, v23
	v_max_f32_e32 v52, v22, v22
	v_max_f32_e32 v51, v52, v51
	v_max3_f32 v49, v49, v50, v51
	v_max_f32_e32 v50, v17, v17
	v_max_f32_e32 v51, v16, v16
	v_max_f32_e32 v50, v51, v50
	v_max_f32_e32 v51, v19, v19
	v_max_f32_e32 v52, v18, v18
	v_max_f32_e32 v51, v52, v51
	v_max3_f32 v49, v49, v50, v51
	v_max_f32_e32 v50, v13, v13
	v_max_f32_e32 v51, v12, v12
	v_max_f32_e32 v50, v51, v50
	v_max_f32_e32 v51, v15, v15
	v_max_f32_e32 v52, v14, v14
	v_max_f32_e32 v51, v52, v51
	v_max3_f32 v49, v49, v50, v51
	v_max_f32_e32 v50, v9, v9
	v_max_f32_e32 v51, v8, v8
	v_max_f32_e32 v50, v51, v50
	v_max_f32_e32 v51, v11, v11
	v_max_f32_e32 v52, v10, v10
	v_max_f32_e32 v51, v52, v51
	v_max3_f32 v49, v49, v50, v51
	v_max_f32_e32 v50, v5, v5
	v_max_f32_e32 v51, v4, v4
	v_max_f32_e32 v50, v51, v50
	v_max_f32_e32 v51, v7, v7
	v_max_f32_e32 v52, v6, v6
	v_max_f32_e32 v51, v52, v51
	v_max3_f32 v49, v49, v50, v51
	v_max_f32_e32 v50, v1, v1
	v_max_f32_e32 v51, v0, v0
	v_max_f32_e32 v50, v51, v50
	v_max_f32_e32 v51, v3, v3
	v_max_f32_e32 v52, v2, v2
	v_max_f32_e32 v51, v52, v51
	v_max3_f32 v49, v49, v50, v51
	v_mbcnt_lo_u32_b32 v50, -1, 0
	v_mbcnt_hi_u32_b32 v50, -1, v50
	v_and_b32_e32 v52, 64, v50
	v_xor_b32_e32 v51, 16, v50
	v_add_u32_e32 v52, 64, v52
	v_cmp_lt_i32_e32 vcc, v51, v52
	s_nop 1
	v_cndmask_b32_e32 v51, v50, v51, vcc
	v_lshlrev_b32_e32 v51, 2, v51
	v_mov_b32_e32 v53, v49
	s_nop 1
	v_permlane16_swap_b32_e32 v53, v49
	s_waitcnt lgkmcnt(0)
	v_max_f32_e32 v53, v53, v53
	v_max_f32_e32 v49, v49, v53
	v_xor_b32_e32 v53, 32, v50
	v_cmp_lt_i32_e32 vcc, v53, v52
	s_nop 1
	v_cndmask_b32_e32 v50, v50, v53, vcc
	v_lshlrev_b32_e32 v50, 2, v50
	v_mov_b32_e32 v52, v49
	s_nop 1
	v_permlane32_swap_b32_e32 v52, v49
	s_waitcnt lgkmcnt(0)
	v_max_f32_e32 v52, v52, v52
	v_max_f32_e32 v49, v49, v52
	v_sub_f32_e32 v52, v120, v49
	v_exp_f32_e32 v52, v52
	v_sub_f32_e32 v53, v121, v49
	v_exp_f32_e32 v53, v53
	v_sub_f32_e32 v54, v122, v49
	v_exp_f32_e32 v54, v54
	v_sub_f32_e32 v55, v123, v49
	v_exp_f32_e32 v55, v55
	v_sub_f32_e32 v59, v116, v49
	v_add_f32_e32 v57, 0, v52
	v_exp_f32_e32 v59, v59
	v_sub_f32_e32 v62, v117, v49
	v_add_f32_e32 v57, v53, v57
	v_exp_f32_e32 v62, v62
	v_sub_f32_e32 v63, v118, v49
	v_add_f32_e32 v57, v54, v57
	v_exp_f32_e32 v63, v63
	v_sub_f32_e32 v64, v119, v49
	v_add_f32_e32 v57, v55, v57
	v_exp_f32_e32 v64, v64
	v_sub_f32_e32 v66, v112, v49
	v_add_f32_e32 v57, v59, v57
	v_exp_f32_e32 v66, v66
	v_sub_f32_e32 v67, v113, v49
	v_add_f32_e32 v57, v62, v57
	v_exp_f32_e32 v67, v67
	v_sub_f32_e32 v68, v114, v49
	v_add_f32_e32 v57, v63, v57
	v_exp_f32_e32 v68, v68
	v_sub_f32_e32 v69, v115, v49
	v_add_f32_e32 v57, v64, v57
	v_exp_f32_e32 v69, v69
	v_sub_f32_e32 v71, v108, v49
	v_add_f32_e32 v57, v66, v57
	v_exp_f32_e32 v71, v71
	v_sub_f32_e32 v72, v109, v49
	v_add_f32_e32 v57, v67, v57
	v_exp_f32_e32 v72, v72
	v_sub_f32_e32 v73, v110, v49
	v_add_f32_e32 v57, v68, v57
	v_exp_f32_e32 v73, v73
	v_sub_f32_e32 v74, v111, v49
	v_add_f32_e32 v57, v69, v57
	v_exp_f32_e32 v74, v74
	v_sub_f32_e32 v75, v104, v49
	v_add_f32_e32 v57, v71, v57
	v_exp_f32_e32 v75, v75
	v_sub_f32_e32 v76, v105, v49
	v_add_f32_e32 v57, v72, v57
	v_exp_f32_e32 v76, v76
	v_sub_f32_e32 v77, v106, v49
	v_add_f32_e32 v57, v73, v57
	v_exp_f32_e32 v77, v77
	v_sub_f32_e32 v78, v107, v49
	v_add_f32_e32 v57, v74, v57
	v_exp_f32_e32 v78, v78
	v_sub_f32_e32 v40, v40, v49
	v_add_f32_e32 v57, v75, v57
	v_exp_f32_e32 v40, v40
	v_sub_f32_e32 v41, v41, v49
	v_add_f32_e32 v57, v76, v57
	v_exp_f32_e32 v41, v41
	v_sub_f32_e32 v42, v42, v49
	v_add_f32_e32 v57, v77, v57
	v_exp_f32_e32 v42, v42
	v_sub_f32_e32 v43, v43, v49
	v_add_f32_e32 v57, v78, v57
	v_exp_f32_e32 v43, v43
	v_sub_f32_e32 v36, v36, v49
	v_add_f32_e32 v57, v40, v57
	v_exp_f32_e32 v36, v36
	v_sub_f32_e32 v37, v37, v49
	v_add_f32_e32 v57, v41, v57
	v_exp_f32_e32 v37, v37
	v_sub_f32_e32 v38, v38, v49
	v_add_f32_e32 v57, v42, v57
	v_exp_f32_e32 v38, v38
	v_sub_f32_e32 v39, v39, v49
	v_add_f32_e32 v57, v43, v57
	v_exp_f32_e32 v39, v39
	v_sub_f32_e32 v32, v32, v49
	v_add_f32_e32 v57, v36, v57
	v_exp_f32_e32 v32, v32
	v_sub_f32_e32 v33, v33, v49
	v_add_f32_e32 v57, v37, v57
	v_exp_f32_e32 v33, v33
	v_sub_f32_e32 v34, v34, v49
	v_add_f32_e32 v57, v38, v57
	v_exp_f32_e32 v34, v34
	v_sub_f32_e32 v35, v35, v49
	v_add_f32_e32 v57, v39, v57
	v_exp_f32_e32 v35, v35
	v_sub_f32_e32 v28, v28, v49
	v_add_f32_e32 v57, v32, v57
	v_exp_f32_e32 v79, v28
	v_sub_f32_e32 v28, v29, v49
	v_add_f32_e32 v57, v33, v57
	v_exp_f32_e32 v80, v28
	v_sub_f32_e32 v28, v30, v49
	v_add_f32_e32 v57, v34, v57
	v_exp_f32_e32 v81, v28
	v_sub_f32_e32 v28, v31, v49
	v_add_f32_e32 v57, v35, v57
	v_exp_f32_e32 v82, v28
	v_sub_f32_e32 v24, v24, v49
	v_add_f32_e32 v28, v79, v57
	v_exp_f32_e32 v57, v24
	v_sub_f32_e32 v24, v25, v49
	v_add_f32_e32 v28, v80, v28
	v_exp_f32_e32 v83, v24
	v_sub_f32_e32 v24, v26, v49
	v_add_f32_e32 v28, v81, v28
	v_exp_f32_e32 v84, v24
	v_sub_f32_e32 v24, v27, v49
	v_add_f32_e32 v28, v82, v28
	v_exp_f32_e32 v85, v24
	v_sub_f32_e32 v20, v20, v49
	v_add_f32_e32 v24, v57, v28
	v_exp_f32_e32 v86, v20
	v_sub_f32_e32 v20, v21, v49
	v_add_f32_e32 v24, v83, v24
	v_exp_f32_e32 v87, v20
	v_sub_f32_e32 v20, v22, v49
	v_add_f32_e32 v24, v84, v24
	v_exp_f32_e32 v88, v20
	v_sub_f32_e32 v20, v23, v49
	v_add_f32_e32 v24, v85, v24
	v_exp_f32_e32 v89, v20
	v_sub_f32_e32 v16, v16, v49
	v_add_f32_e32 v20, v86, v24
	v_exp_f32_e32 v90, v16
	v_sub_f32_e32 v16, v17, v49
	v_add_f32_e32 v20, v87, v20
	v_exp_f32_e32 v91, v16
	v_sub_f32_e32 v16, v18, v49
	v_add_f32_e32 v20, v88, v20
	v_exp_f32_e32 v92, v16
	v_sub_f32_e32 v16, v19, v49
	v_add_f32_e32 v20, v89, v20
	v_exp_f32_e32 v93, v16
	v_sub_f32_e32 v12, v12, v49
	v_add_f32_e32 v16, v90, v20
	v_exp_f32_e32 v94, v12
	v_sub_f32_e32 v12, v13, v49
	v_add_f32_e32 v16, v91, v16
	v_exp_f32_e32 v95, v12
	v_sub_f32_e32 v12, v14, v49
	v_add_f32_e32 v16, v92, v16
	v_exp_f32_e32 v96, v12
	v_sub_f32_e32 v12, v15, v49
	v_add_f32_e32 v16, v93, v16
	v_exp_f32_e32 v97, v12
	v_sub_f32_e32 v8, v8, v49
	v_add_f32_e32 v12, v94, v16
	v_exp_f32_e32 v98, v8
	v_sub_f32_e32 v8, v9, v49
	v_add_f32_e32 v12, v95, v12
	v_exp_f32_e32 v99, v8
	v_sub_f32_e32 v8, v10, v49
	v_add_f32_e32 v12, v96, v12
	v_exp_f32_e32 v100, v8
	v_sub_f32_e32 v8, v11, v49
	v_add_f32_e32 v12, v97, v12
	v_exp_f32_e32 v11, v8
	v_sub_f32_e32 v4, v4, v49
	v_add_f32_e32 v8, v98, v12
	v_exp_f32_e32 v101, v4
	v_sub_f32_e32 v4, v5, v49
	v_add_f32_e32 v8, v99, v8
	v_exp_f32_e32 v102, v4
	v_sub_f32_e32 v4, v6, v49
	v_add_f32_e32 v8, v100, v8
	v_exp_f32_e32 v103, v4
	v_sub_f32_e32 v4, v7, v49
	v_add_f32_e32 v8, v11, v8
	v_exp_f32_e32 v104, v4
	v_sub_f32_e32 v0, v0, v49
	v_add_f32_e32 v4, v101, v8
	v_exp_f32_e32 v105, v0
	v_sub_f32_e32 v0, v1, v49
	v_add_f32_e32 v4, v102, v4
	v_exp_f32_e32 v106, v0
	v_sub_f32_e32 v0, v2, v49
	v_add_f32_e32 v4, v103, v4
	v_exp_f32_e32 v107, v0
	v_sub_f32_e32 v0, v3, v49
	v_add_f32_e32 v4, v104, v4
	v_exp_f32_e32 v3, v0
	v_add_f32_e32 v0, v105, v4
	v_add_f32_e32 v0, v106, v0
	v_add_f32_e32 v0, v107, v0
	v_add_f32_e32 v0, v3, v0
	v_mov_b32_e32 v1, v0
	s_nop 1
	v_permlane16_swap_b32_e32 v1, v0
	v_cvt_pk_bf16_f32 v28, v52, v53
	v_cvt_pk_bf16_f32 v29, v54, v55
	v_cvt_pk_bf16_f32 v30, v59, v62
	v_cvt_pk_bf16_f32 v31, v63, v64
	s_waitcnt lgkmcnt(0)
	v_add_f32_e32 v0, v0, v1
	v_mov_b32_e32 v1, v0
	s_nop 1
	v_permlane32_swap_b32_e32 v1, v0
	v_cvt_pk_bf16_f32 v20, v66, v67
	v_cvt_pk_bf16_f32 v21, v68, v69
	v_cvt_pk_bf16_f32 v22, v71, v72
	v_cvt_pk_bf16_f32 v23, v73, v74
	s_waitcnt lgkmcnt(0)
	v_add_f32_e32 v49, v0, v1
	v_cvt_pk_bf16_f32 v24, v75, v76
	v_cvt_pk_bf16_f32 v25, v77, v78
	v_cvt_pk_bf16_f32 v26, v40, v41
	v_cvt_pk_bf16_f32 v27, v42, v43
	v_cvt_pk_bf16_f32 v16, v36, v37
	v_cvt_pk_bf16_f32 v17, v38, v39
	v_cvt_pk_bf16_f32 v18, v32, v33
	v_cvt_pk_bf16_f32 v19, v34, v35
	v_cvt_pk_bf16_f32 v12, v79, v80
	v_cvt_pk_bf16_f32 v13, v81, v82
	v_cvt_pk_bf16_f32 v14, v57, v83
	v_cvt_pk_bf16_f32 v15, v84, v85
	v_cvt_pk_bf16_f32 v4, v86, v87
	v_cvt_pk_bf16_f32 v5, v88, v89
	v_cvt_pk_bf16_f32 v6, v90, v91
	v_cvt_pk_bf16_f32 v7, v92, v93
	v_cvt_pk_bf16_f32 v8, v94, v95
	v_cvt_pk_bf16_f32 v9, v96, v97
	v_cvt_pk_bf16_f32 v10, v98, v99
	v_cvt_pk_bf16_f32 v11, v100, v11
	v_cvt_pk_bf16_f32 v0, v101, v102
	v_cvt_pk_bf16_f32 v1, v103, v104
	v_cvt_pk_bf16_f32 v2, v105, v106
	v_cvt_pk_bf16_f32 v3, v107, v3
	s_waitcnt vmcnt(0)
	s_waitcnt vmcnt(0)
	s_barrier
	v_mov_b32_e32 v64, v65
	v_div_scale_f32 v62, vcc, 1.0, v49, 1.0
	v_lshlrev_b32_e32 v54, 2, v70
	v_ashrrev_i32_e32 v55, 31, v54
	ds_read_b128 v[32:35], v64
	ds_read_b128 v[36:39], v64 offset:2048
	v_div_scale_f32 v57, s[0:1], v49, v49, 1.0
	v_rcp_f32_e32 v59, v57
	s_waitcnt lgkmcnt(0)
	v_mfma_f32_16x16x32_bf16 v[44:47], v[32:35], v[28:31], 0
	v_fma_f32 v40, -v57, v59, 1.0
	v_fmac_f32_e32 v59, v40, v59
	ds_read_b128 v[40:43], v64 offset:4096
	ds_read_b128 v[32:35], v64 offset:6144
	v_mul_f32_e32 v63, v62, v59
	v_fma_f32 v66, -v57, v63, v62
	v_fmac_f32_e32 v63, v66, v59
	v_mfma_f32_16x16x32_bf16 v[50:53], v[36:39], v[28:31], 0
	v_fma_f32 v36, -v57, v63, v62
	ds_read_b128 v[66:69], v64 offset:8192
	ds_read_b128 v[70:73], v64 offset:10240
	v_div_fmas_f32 v36, v36, v59, v63
	s_waitcnt lgkmcnt(0)
	v_mfma_f32_16x16x32_bf16 v[74:77], v[32:35], v[28:31], 0
	v_lshl_add_u64 v[34:35], v[54:55], 1, v[60:61]
	ds_read_b128 v[60:63], v64 offset:12288
	ds_read_b128 v[78:81], v64 offset:14336
	ds_read_b128 v[82:85], v64 offset:32768
	ds_read_b128 v[86:89], v64 offset:34816
	ds_read_b128 v[90:93], v64 offset:36864
	ds_read_b128 v[94:97], v64 offset:38912
	ds_read_b128 v[98:101], v64 offset:40960
	ds_read_b128 v[102:105], v64 offset:43008
	ds_read_b128 v[106:109], v64 offset:45056
	ds_read_b128 v[110:113], v64 offset:47104
	s_mov_b64 s[0:1], 0x1000000
	v_mfma_f32_16x16x32_bf16 v[38:41], v[40:43], v[28:31], 0
	v_div_fixup_f32 v36, v36, v49, 1.0
	v_lshl_add_u64 v[32:33], v[34:35], 0, s[0:1]
	v_mfma_f32_16x16x32_bf16 v[66:69], v[66:69], v[28:31], 0
	v_mfma_f32_16x16x32_bf16 v[70:73], v[70:73], v[28:31], 0
	s_waitcnt lgkmcnt(0)
	v_mfma_f32_16x16x32_bf16 v[60:63], v[60:63], v[28:31], 0
	v_mfma_f32_16x16x32_bf16 v[78:81], v[78:81], v[28:31], 0
	s_add_u32 s100, s10, 0x11e00100
	s_addc_u32 s101, s11, 0
	s_mov_b32 m0, s19
	s_nop 0
	global_load_lds_dwordx4 v241, s[100:101]
	ds_read_b128 v[114:117], v64 offset:30720
	ds_read_b128 v[118:121], v64 offset:28672
	ds_read_b128 v[122:125], v64 offset:26624
	ds_read_b128 v[126:129], v64 offset:24576
	ds_read_b128 v[130:133], v64 offset:22528
	ds_read_b128 v[134:137], v64 offset:20480
	ds_read_b128 v[138:141], v64 offset:18432
	ds_read_b128 v[142:145], v64 offset:16384
	v_mfma_f32_16x16x32_bf16 v[82:85], v[82:85], v[28:31], 0
	v_mfma_f32_16x16x32_bf16 v[86:89], v[86:89], v[28:31], 0
	v_mfma_f32_16x16x32_bf16 v[90:93], v[90:93], v[28:31], 0
	v_mfma_f32_16x16x32_bf16 v[94:97], v[94:97], v[28:31], 0
	v_mfma_f32_16x16x32_bf16 v[98:101], v[98:101], v[28:31], 0
	v_mfma_f32_16x16x32_bf16 v[102:105], v[102:105], v[28:31], 0
	v_mfma_f32_16x16x32_bf16 v[106:109], v[106:109], v[28:31], 0
	v_mfma_f32_16x16x32_bf16 v[110:113], v[110:113], v[28:31], 0
	s_add_u32 s100, s10, 0x11e08100
	s_addc_u32 s101, s11, 0
	s_mov_b32 m0, s13
	s_nop 0
	global_load_lds_dwordx4 v241, s[100:101]
	s_waitcnt lgkmcnt(0)
	v_mfma_f32_16x16x32_bf16 v[42:45], v[142:145], v[24:27], v[44:47]
	v_mfma_f32_16x16x32_bf16 v[50:53], v[138:141], v[24:27], v[50:53]
	v_mfma_f32_16x16x32_bf16 v[38:41], v[134:137], v[24:27], v[38:41]
	v_mfma_f32_16x16x32_bf16 v[74:77], v[130:133], v[24:27], v[74:77]
	v_mfma_f32_16x16x32_bf16 v[66:69], v[126:129], v[24:27], v[66:69]
	v_mfma_f32_16x16x32_bf16 v[70:73], v[122:125], v[24:27], v[70:73]
	ds_read_b128 v[122:125], v64 offset:49152
	ds_read_b128 v[126:129], v64 offset:51200
	ds_read_b128 v[130:133], v64 offset:53248
	ds_read_b128 v[134:137], v64 offset:55296
	v_mfma_f32_16x16x32_bf16 v[60:63], v[118:121], v[24:27], v[60:63]
	ds_read_b128 v[118:121], v64 offset:57344
	ds_read_b128 v[138:141], v64 offset:59392
	ds_read_b128 v[142:145], v64 offset:61440
	ds_read_b128 v[146:149], v64 offset:63488
	v_mfma_f32_16x16x32_bf16 v[78:81], v[114:117], v[24:27], v[78:81]
	s_add_u32 s100, s10, 0x11e00180
	s_addc_u32 s101, s11, 0
	s_mov_b32 m0, s12
	s_nop 0
	global_load_lds_dwordx4 v241, s[100:101]
	s_waitcnt lgkmcnt(0)
	v_mfma_f32_16x16x32_bf16 v[82:85], v[122:125], v[24:27], v[82:85]
	v_mfma_f32_16x16x32_bf16 v[86:89], v[126:129], v[24:27], v[86:89]
	v_mfma_f32_16x16x32_bf16 v[90:93], v[130:133], v[24:27], v[90:93]
	v_mfma_f32_16x16x32_bf16 v[94:97], v[134:137], v[24:27], v[94:97]
	v_mfma_f32_16x16x32_bf16 v[98:101], v[118:121], v[24:27], v[98:101]
	ds_read_b128 v[114:117], v64 offset:15360
	ds_read_b128 v[118:121], v64 offset:13312
	ds_read_b128 v[122:125], v64 offset:11264
	ds_read_b128 v[126:129], v64 offset:9216
	v_mfma_f32_16x16x32_bf16 v[102:105], v[138:141], v[24:27], v[102:105]
	v_mfma_f32_16x16x32_bf16 v[106:109], v[142:145], v[24:27], v[106:109]
	ds_read_b128 v[130:133], v64 offset:7168
	ds_read_b128 v[134:137], v64 offset:5120
	ds_read_b128 v[138:141], v64 offset:3072
	ds_read_b128 v[142:145], v64 offset:1024
	v_mfma_f32_16x16x32_bf16 v[110:113], v[146:149], v[24:27], v[110:113]
	s_add_u32 s100, s10, 0x11e08180
	s_addc_u32 s101, s11, 0
	s_mov_b32 m0, s14
	s_nop 0
	global_load_lds_dwordx4 v241, s[100:101]
	s_waitcnt lgkmcnt(0)
	v_mfma_f32_16x16x32_bf16 v[42:45], v[142:145], v[20:23], v[42:45]
	v_mfma_f32_16x16x32_bf16 v[50:53], v[138:141], v[20:23], v[50:53]
	v_mfma_f32_16x16x32_bf16 v[38:41], v[134:137], v[20:23], v[38:41]
	v_mfma_f32_16x16x32_bf16 v[74:77], v[130:133], v[20:23], v[74:77]
	v_mfma_f32_16x16x32_bf16 v[66:69], v[126:129], v[20:23], v[66:69]
	v_mfma_f32_16x16x32_bf16 v[70:73], v[122:125], v[20:23], v[70:73]
	ds_read_b128 v[122:125], v64 offset:33792
	ds_read_b128 v[126:129], v64 offset:35840
	ds_read_b128 v[130:133], v64 offset:37888
	ds_read_b128 v[134:137], v64 offset:39936
	v_mfma_f32_16x16x32_bf16 v[60:63], v[118:121], v[20:23], v[60:63]
	ds_read_b128 v[118:121], v64 offset:41984
	ds_read_b128 v[138:141], v64 offset:44032
	ds_read_b128 v[142:145], v64 offset:46080
	ds_read_b128 v[146:149], v64 offset:48128
	v_mfma_f32_16x16x32_bf16 v[78:81], v[114:117], v[20:23], v[78:81]
	s_add_u32 s100, s10, 0x11e10100
	s_addc_u32 s101, s11, 0
	s_mov_b32 m0, s15
	s_nop 0
	global_load_lds_dwordx4 v241, s[100:101]
	s_waitcnt lgkmcnt(0)
	v_mfma_f32_16x16x32_bf16 v[82:85], v[122:125], v[20:23], v[82:85]
	v_mfma_f32_16x16x32_bf16 v[86:89], v[126:129], v[20:23], v[86:89]
	v_mfma_f32_16x16x32_bf16 v[90:93], v[130:133], v[20:23], v[90:93]
	v_mfma_f32_16x16x32_bf16 v[94:97], v[134:137], v[20:23], v[94:97]
	v_mfma_f32_16x16x32_bf16 v[98:101], v[118:121], v[20:23], v[98:101]
	ds_read_b128 v[114:117], v64 offset:31744
	ds_read_b128 v[118:121], v64 offset:29696
	ds_read_b128 v[122:125], v64 offset:27648
	ds_read_b128 v[126:129], v64 offset:25600
	v_mfma_f32_16x16x32_bf16 v[102:105], v[138:141], v[20:23], v[102:105]
	v_mfma_f32_16x16x32_bf16 v[106:109], v[142:145], v[20:23], v[106:109]
	ds_read_b128 v[130:133], v64 offset:23552
	ds_read_b128 v[134:137], v64 offset:21504
	ds_read_b128 v[138:141], v64 offset:19456
	ds_read_b128 v[142:145], v64 offset:17408
	v_mfma_f32_16x16x32_bf16 v[110:113], v[146:149], v[20:23], v[110:113]
	s_add_u32 s100, s10, 0x11e18100
	s_addc_u32 s101, s11, 0
	s_mov_b32 m0, s16
	s_nop 0
	global_load_lds_dwordx4 v241, s[100:101]
	s_waitcnt lgkmcnt(0)
	v_mfma_f32_16x16x32_bf16 v[42:45], v[142:145], v[16:19], v[42:45]
	v_mfma_f32_16x16x32_bf16 v[50:53], v[138:141], v[16:19], v[50:53]
	v_mfma_f32_16x16x32_bf16 v[38:41], v[134:137], v[16:19], v[38:41]
	v_mfma_f32_16x16x32_bf16 v[74:77], v[130:133], v[16:19], v[74:77]
	v_mfma_f32_16x16x32_bf16 v[66:69], v[126:129], v[16:19], v[66:69]
	v_mfma_f32_16x16x32_bf16 v[70:73], v[122:125], v[16:19], v[70:73]
	ds_read_b128 v[122:125], v64 offset:50176
	ds_read_b128 v[126:129], v64 offset:52224
	ds_read_b128 v[130:133], v64 offset:54272
	ds_read_b128 v[134:137], v64 offset:56320
	v_mfma_f32_16x16x32_bf16 v[60:63], v[118:121], v[16:19], v[60:63]
	ds_read_b128 v[118:121], v64 offset:58368
	ds_read_b128 v[138:141], v64 offset:60416
	ds_read_b128 v[142:145], v64 offset:62464
	ds_read_b128 v[146:149], v64 offset:64512
	v_mfma_f32_16x16x32_bf16 v[78:81], v[114:117], v[16:19], v[78:81]
	s_add_u32 s100, s10, 0x11e10180
	s_addc_u32 s101, s11, 0
	s_mov_b32 m0, s17
	s_nop 0
	global_load_lds_dwordx4 v241, s[100:101]
	s_waitcnt lgkmcnt(0)
	v_mfma_f32_16x16x32_bf16 v[82:85], v[122:125], v[16:19], v[82:85]
	v_mfma_f32_16x16x32_bf16 v[86:89], v[126:129], v[16:19], v[86:89]
	v_mfma_f32_16x16x32_bf16 v[90:93], v[130:133], v[16:19], v[90:93]
	v_mfma_f32_16x16x32_bf16 v[94:97], v[134:137], v[16:19], v[94:97]
	v_mfma_f32_16x16x32_bf16 v[98:101], v[118:121], v[16:19], v[98:101]
	v_mfma_f32_16x16x32_bf16 v[102:105], v[138:141], v[16:19], v[102:105]
	v_mfma_f32_16x16x32_bf16 v[106:109], v[142:145], v[16:19], v[106:109]
	v_mfma_f32_16x16x32_bf16 v[110:113], v[146:149], v[16:19], v[110:113]
	s_add_u32 s100, s10, 0x11e18180
	s_addc_u32 s101, s11, 0
	s_mov_b32 m0, s18
	s_nop 0
	global_load_lds_dwordx4 v241, s[100:101]
	s_waitcnt vmcnt(0)
	s_waitcnt vmcnt(0)
	s_barrier
	v_mov_b32_e32 v37, v48
	ds_read_b128 v[114:117], v37
	ds_read_b128 v[118:121], v37 offset:2048
	s_waitcnt lgkmcnt(0)
	v_mfma_f32_16x16x32_bf16 v[42:45], v[114:117], v[12:15], v[42:45]
	ds_read_b128 v[114:117], v37 offset:4096
	v_mfma_f32_16x16x32_bf16 v[50:53], v[118:121], v[12:15], v[50:53]
	ds_read_b128 v[118:121], v37 offset:6144
	s_waitcnt lgkmcnt(0)
	v_mfma_f32_16x16x32_bf16 v[38:41], v[114:117], v[12:15], v[38:41]
	ds_read_b128 v[114:117], v37 offset:8192
	v_mfma_f32_16x16x32_bf16 v[74:77], v[118:121], v[12:15], v[74:77]
	ds_read_b128 v[118:121], v37 offset:10240
	s_waitcnt lgkmcnt(0)
	v_mfma_f32_16x16x32_bf16 v[66:69], v[114:117], v[12:15], v[66:69]
	ds_read_b128 v[114:117], v37 offset:12288
	ds_read_b128 v[122:125], v37 offset:14336
	v_mfma_f32_16x16x32_bf16 v[70:73], v[118:121], v[12:15], v[70:73]
	ds_read_b128 v[118:121], v37 offset:32768
	ds_read_b128 v[126:129], v37 offset:34816
	ds_read_b128 v[130:133], v37 offset:36864
	ds_read_b128 v[134:137], v37 offset:38912
	s_waitcnt lgkmcnt(0)
	v_mfma_f32_16x16x32_bf16 v[60:63], v[114:117], v[12:15], v[60:63]
	ds_read_b128 v[114:117], v37 offset:40960
	ds_read_b128 v[138:141], v37 offset:43008
	ds_read_b128 v[142:145], v37 offset:45056
	ds_read_b128 v[146:149], v37 offset:47104
	v_mfma_f32_16x16x32_bf16 v[78:81], v[122:125], v[12:15], v[78:81]
	s_add_u32 s100, s10, 0x11e20000
	s_addc_u32 s101, s11, 0
	s_mov_b32 m0, s22
	s_nop 0
	global_load_lds_dwordx4 v241, s[100:101]
	v_mfma_f32_16x16x32_bf16 v[82:85], v[118:121], v[12:15], v[82:85]
	v_mfma_f32_16x16x32_bf16 v[86:89], v[126:129], v[12:15], v[86:89]
	v_mfma_f32_16x16x32_bf16 v[90:93], v[130:133], v[12:15], v[90:93]
	v_mfma_f32_16x16x32_bf16 v[94:97], v[134:137], v[12:15], v[94:97]
	s_waitcnt lgkmcnt(0)
	v_mfma_f32_16x16x32_bf16 v[98:101], v[114:117], v[12:15], v[98:101]
	ds_read_b128 v[114:117], v37 offset:30720
	ds_read_b128 v[118:121], v37 offset:28672
	ds_read_b128 v[122:125], v37 offset:26624
	ds_read_b128 v[126:129], v37 offset:24576
	v_mfma_f32_16x16x32_bf16 v[102:105], v[138:141], v[12:15], v[102:105]
	v_mfma_f32_16x16x32_bf16 v[106:109], v[142:145], v[12:15], v[106:109]
	ds_read_b128 v[130:133], v37 offset:22528
	ds_read_b128 v[134:137], v37 offset:20480
	ds_read_b128 v[138:141], v37 offset:18432
	ds_read_b128 v[142:145], v37 offset:16384
	v_mfma_f32_16x16x32_bf16 v[110:113], v[146:149], v[12:15], v[110:113]
	s_add_u32 s100, s10, 0x11e28000
	s_addc_u32 s101, s11, 0
	s_mov_b32 m0, s21
	s_nop 0
	global_load_lds_dwordx4 v241, s[100:101]
	s_waitcnt lgkmcnt(0)
	v_mfma_f32_16x16x32_bf16 v[42:45], v[142:145], v[8:11], v[42:45]
	v_mfma_f32_16x16x32_bf16 v[50:53], v[138:141], v[8:11], v[50:53]
	v_mfma_f32_16x16x32_bf16 v[38:41], v[134:137], v[8:11], v[38:41]
	v_mfma_f32_16x16x32_bf16 v[74:77], v[130:133], v[8:11], v[74:77]
	v_mfma_f32_16x16x32_bf16 v[66:69], v[126:129], v[8:11], v[66:69]
	v_mfma_f32_16x16x32_bf16 v[70:73], v[122:125], v[8:11], v[70:73]
	ds_read_b128 v[122:125], v37 offset:49152
	ds_read_b128 v[126:129], v37 offset:51200
	ds_read_b128 v[130:133], v37 offset:53248
	ds_read_b128 v[134:137], v37 offset:55296
	v_mfma_f32_16x16x32_bf16 v[60:63], v[118:121], v[8:11], v[60:63]
	ds_read_b128 v[118:121], v37 offset:57344
	ds_read_b128 v[138:141], v37 offset:59392
	ds_read_b128 v[142:145], v37 offset:61440
	ds_read_b128 v[146:149], v37 offset:63488
	v_mfma_f32_16x16x32_bf16 v[78:81], v[114:117], v[8:11], v[78:81]
	s_add_u32 s100, s10, 0x11e20080
	s_addc_u32 s101, s11, 0
	s_mov_b32 m0, s20
	s_nop 0
	global_load_lds_dwordx4 v241, s[100:101]
	s_waitcnt lgkmcnt(0)
	v_mfma_f32_16x16x32_bf16 v[82:85], v[122:125], v[8:11], v[82:85]
	v_mfma_f32_16x16x32_bf16 v[86:89], v[126:129], v[8:11], v[86:89]
	v_mfma_f32_16x16x32_bf16 v[90:93], v[130:133], v[8:11], v[90:93]
	v_mfma_f32_16x16x32_bf16 v[94:97], v[134:137], v[8:11], v[94:97]
	v_mfma_f32_16x16x32_bf16 v[98:101], v[118:121], v[8:11], v[98:101]
	ds_read_b128 v[114:117], v37 offset:15360
	ds_read_b128 v[118:121], v37 offset:13312
	ds_read_b128 v[122:125], v37 offset:11264
	ds_read_b128 v[126:129], v37 offset:9216
	v_mfma_f32_16x16x32_bf16 v[102:105], v[138:141], v[8:11], v[102:105]
	v_mfma_f32_16x16x32_bf16 v[106:109], v[142:145], v[8:11], v[106:109]
	ds_read_b128 v[130:133], v37 offset:7168
	ds_read_b128 v[134:137], v37 offset:5120
	ds_read_b128 v[138:141], v37 offset:3072
	ds_read_b128 v[142:145], v37 offset:1024
	v_mfma_f32_16x16x32_bf16 v[110:113], v[146:149], v[8:11], v[110:113]
	s_add_u32 s100, s10, 0x11e28080
	s_addc_u32 s101, s11, 0
	s_mov_b32 m0, s23
	s_nop 0
	global_load_lds_dwordx4 v241, s[100:101]
	s_waitcnt lgkmcnt(0)
	v_mfma_f32_16x16x32_bf16 v[42:45], v[142:145], v[4:7], v[42:45]
	v_mfma_f32_16x16x32_bf16 v[50:53], v[138:141], v[4:7], v[50:53]
	v_mfma_f32_16x16x32_bf16 v[38:41], v[134:137], v[4:7], v[38:41]
	v_mfma_f32_16x16x32_bf16 v[74:77], v[130:133], v[4:7], v[74:77]
	v_mfma_f32_16x16x32_bf16 v[66:69], v[126:129], v[4:7], v[66:69]
	v_mfma_f32_16x16x32_bf16 v[70:73], v[122:125], v[4:7], v[70:73]
	ds_read_b128 v[122:125], v37 offset:33792
	ds_read_b128 v[126:129], v37 offset:35840
	ds_read_b128 v[130:133], v37 offset:37888
	ds_read_b128 v[134:137], v37 offset:39936
	v_mfma_f32_16x16x32_bf16 v[60:63], v[118:121], v[4:7], v[60:63]
	ds_read_b128 v[118:121], v37 offset:41984
	ds_read_b128 v[138:141], v37 offset:44032
	ds_read_b128 v[142:145], v37 offset:46080
	ds_read_b128 v[146:149], v37 offset:48128
	v_mfma_f32_16x16x32_bf16 v[78:81], v[114:117], v[4:7], v[78:81]
	s_add_u32 s100, s10, 0x11e30000
	s_addc_u32 s101, s11, 0
	s_mov_b32 m0, s24
	s_nop 0
	global_load_lds_dwordx4 v241, s[100:101]
	s_waitcnt lgkmcnt(0)
	v_mfma_f32_16x16x32_bf16 v[82:85], v[122:125], v[4:7], v[82:85]
	v_mfma_f32_16x16x32_bf16 v[86:89], v[126:129], v[4:7], v[86:89]
	v_mfma_f32_16x16x32_bf16 v[90:93], v[130:133], v[4:7], v[90:93]
	v_mfma_f32_16x16x32_bf16 v[94:97], v[134:137], v[4:7], v[94:97]
	v_mfma_f32_16x16x32_bf16 v[98:101], v[118:121], v[4:7], v[98:101]
	ds_read_b128 v[114:117], v37 offset:31744
	ds_read_b128 v[118:121], v37 offset:29696
	ds_read_b128 v[122:125], v37 offset:27648
	ds_read_b128 v[126:129], v37 offset:25600
	v_mfma_f32_16x16x32_bf16 v[102:105], v[138:141], v[4:7], v[102:105]
	v_mfma_f32_16x16x32_bf16 v[106:109], v[142:145], v[4:7], v[106:109]
	ds_read_b128 v[130:133], v37 offset:23552
	ds_read_b128 v[134:137], v37 offset:21504
	ds_read_b128 v[138:141], v37 offset:19456
	ds_read_b128 v[142:145], v37 offset:17408
	v_mfma_f32_16x16x32_bf16 v[110:113], v[146:149], v[4:7], v[110:113]
	s_add_u32 s100, s10, 0x11e38000
	s_addc_u32 s101, s11, 0
	s_mov_b32 m0, s25
	s_nop 0
	global_load_lds_dwordx4 v241, s[100:101]
	s_waitcnt lgkmcnt(0)
	v_mfma_f32_16x16x32_bf16 v[42:45], v[142:145], v[0:3], v[42:45]
	v_mfma_f32_16x16x32_bf16 v[50:53], v[138:141], v[0:3], v[50:53]
	v_mfma_f32_16x16x32_bf16 v[38:41], v[134:137], v[0:3], v[38:41]
	v_mfma_f32_16x16x32_bf16 v[74:77], v[130:133], v[0:3], v[74:77]
	v_mfma_f32_16x16x32_bf16 v[66:69], v[126:129], v[0:3], v[66:69]
	v_mfma_f32_16x16x32_bf16 v[70:73], v[122:125], v[0:3], v[70:73]
	ds_read_b128 v[122:125], v37 offset:50176
	ds_read_b128 v[126:129], v37 offset:52224
	ds_read_b128 v[130:133], v37 offset:54272
	ds_read_b128 v[134:137], v37 offset:56320
	v_mfma_f32_16x16x32_bf16 v[60:63], v[118:121], v[0:3], v[60:63]
	ds_read_b128 v[118:121], v37 offset:58368
	ds_read_b128 v[138:141], v37 offset:60416
	ds_read_b128 v[142:145], v37 offset:62464
	ds_read_b128 v[146:149], v37 offset:64512
	v_mfma_f32_16x16x32_bf16 v[78:81], v[114:117], v[0:3], v[78:81]
	s_add_u32 s100, s10, 0x11e30080
	s_addc_u32 s101, s11, 0
	s_mov_b32 m0, s26
	s_nop 0
	global_load_lds_dwordx4 v241, s[100:101]
	s_waitcnt lgkmcnt(0)
	v_mfma_f32_16x16x32_bf16 v[82:85], v[122:125], v[0:3], v[82:85]
	v_mfma_f32_16x16x32_bf16 v[86:89], v[126:129], v[0:3], v[86:89]
	v_mfma_f32_16x16x32_bf16 v[90:93], v[130:133], v[0:3], v[90:93]
	v_mfma_f32_16x16x32_bf16 v[94:97], v[134:137], v[0:3], v[94:97]
	v_mfma_f32_16x16x32_bf16 v[98:101], v[118:121], v[0:3], v[98:101]
	v_mfma_f32_16x16x32_bf16 v[102:105], v[138:141], v[0:3], v[102:105]
	v_mfma_f32_16x16x32_bf16 v[106:109], v[142:145], v[0:3], v[106:109]
	v_mfma_f32_16x16x32_bf16 v[110:113], v[146:149], v[0:3], v[110:113]
	s_add_u32 s100, s10, 0x11e38080
	s_addc_u32 s101, s11, 0
	s_mov_b32 m0, s27
	s_nop 0
	global_load_lds_dwordx4 v241, s[100:101]
	s_mov_b32 s0, 0x1000000
	v_add_co_u32_e32 v34, vcc, s0, v34
	v_addc_co_u32_e32 v35, vcc, 0, v35, vcc
	v_mbcnt_lo_u32_b32 v212, -1, 0
	v_mbcnt_hi_u32_b32 v212, -1, v212
	v_lshrrev_b32_e32 v212, 4, v212
	v_and_b32_e32 v212, 1, v212
	v_mul_u32_u24_e32 v212, 24, v212
	v_mov_b32_e32 v213, 0
	v_lshl_add_u64 v[214:215], v[32:33], 0, v[212:213]
	v_mul_f32_e32 v200, v36, v42
	v_mul_f32_e32 v204, v36, v43
	v_cvt_pk_bf16_f32 v200, v200, v204
	v_mul_f32_e32 v201, v36, v44
	v_mul_f32_e32 v204, v36, v45
	v_cvt_pk_bf16_f32 v201, v201, v204
	v_mul_f32_e32 v202, v36, v50
	v_mul_f32_e32 v204, v36, v51
	v_cvt_pk_bf16_f32 v202, v202, v204
	v_mul_f32_e32 v203, v36, v52
	v_mul_f32_e32 v204, v36, v53
	v_cvt_pk_bf16_f32 v203, v203, v204
	s_nop 1
	v_permlane16_swap_b32_e32 v200, v202
	v_permlane16_swap_b32_e32 v201, v203
	global_store_dwordx4 v[214:215], v[200:203], off offset:0
	v_mul_f32_e32 v206, v36, v38
	v_mul_f32_e32 v210, v36, v39
	v_cvt_pk_bf16_f32 v206, v206, v210
	v_mul_f32_e32 v207, v36, v40
	v_mul_f32_e32 v210, v36, v41
	v_cvt_pk_bf16_f32 v207, v207, v210
	v_mul_f32_e32 v208, v36, v74
	v_mul_f32_e32 v210, v36, v75
	v_cvt_pk_bf16_f32 v208, v208, v210
	v_mul_f32_e32 v209, v36, v76
	v_mul_f32_e32 v210, v36, v77
	v_cvt_pk_bf16_f32 v209, v209, v210
	s_nop 1
	v_permlane16_swap_b32_e32 v206, v208
	v_permlane16_swap_b32_e32 v207, v209
	global_store_dwordx4 v[214:215], v[206:209], off offset:64
	v_mul_f32_e32 v200, v36, v66
	v_mul_f32_e32 v204, v36, v67
	v_cvt_pk_bf16_f32 v200, v200, v204
	v_mul_f32_e32 v201, v36, v68
	v_mul_f32_e32 v204, v36, v69
	v_cvt_pk_bf16_f32 v201, v201, v204
	v_mul_f32_e32 v202, v36, v70
	v_mul_f32_e32 v204, v36, v71
	v_cvt_pk_bf16_f32 v202, v202, v204
	v_mul_f32_e32 v203, v36, v72
	v_mul_f32_e32 v204, v36, v73
	v_cvt_pk_bf16_f32 v203, v203, v204
	s_nop 1
	v_permlane16_swap_b32_e32 v200, v202
	v_permlane16_swap_b32_e32 v201, v203
	global_store_dwordx4 v[214:215], v[200:203], off offset:128
	v_mul_f32_e32 v206, v36, v60
	v_mul_f32_e32 v210, v36, v61
	v_cvt_pk_bf16_f32 v206, v206, v210
	v_mul_f32_e32 v207, v36, v62
	v_mul_f32_e32 v210, v36, v63
	v_cvt_pk_bf16_f32 v207, v207, v210
	v_mul_f32_e32 v208, v36, v78
	v_mul_f32_e32 v210, v36, v79
	v_cvt_pk_bf16_f32 v208, v208, v210
	v_mul_f32_e32 v209, v36, v80
	v_mul_f32_e32 v210, v36, v81
	v_cvt_pk_bf16_f32 v209, v209, v210
	s_nop 1
	v_permlane16_swap_b32_e32 v206, v208
	v_permlane16_swap_b32_e32 v207, v209
	global_store_dwordx4 v[214:215], v[206:209], off offset:192
	v_mul_f32_e32 v200, v36, v82
	v_mul_f32_e32 v204, v36, v83
	v_cvt_pk_bf16_f32 v200, v200, v204
	v_mul_f32_e32 v201, v36, v84
	v_mul_f32_e32 v204, v36, v85
	v_cvt_pk_bf16_f32 v201, v201, v204
	v_mul_f32_e32 v202, v36, v86
	v_mul_f32_e32 v204, v36, v87
	v_cvt_pk_bf16_f32 v202, v202, v204
	v_mul_f32_e32 v203, v36, v88
	v_mul_f32_e32 v204, v36, v89
	v_cvt_pk_bf16_f32 v203, v203, v204
	s_nop 1
	v_permlane16_swap_b32_e32 v200, v202
	v_permlane16_swap_b32_e32 v201, v203
	global_store_dwordx4 v[214:215], v[200:203], off offset:256
	v_mul_f32_e32 v206, v36, v90
	v_mul_f32_e32 v210, v36, v91
	v_cvt_pk_bf16_f32 v206, v206, v210
	v_mul_f32_e32 v207, v36, v92
	v_mul_f32_e32 v210, v36, v93
	v_cvt_pk_bf16_f32 v207, v207, v210
	v_mul_f32_e32 v208, v36, v94
	v_mul_f32_e32 v210, v36, v95
	v_cvt_pk_bf16_f32 v208, v208, v210
	v_mul_f32_e32 v209, v36, v96
	v_mul_f32_e32 v210, v36, v97
	v_cvt_pk_bf16_f32 v209, v209, v210
	s_nop 1
	v_permlane16_swap_b32_e32 v206, v208
	v_permlane16_swap_b32_e32 v207, v209
	global_store_dwordx4 v[214:215], v[206:209], off offset:320
	v_mul_f32_e32 v200, v36, v98
	v_mul_f32_e32 v204, v36, v99
	v_cvt_pk_bf16_f32 v200, v200, v204
	v_mul_f32_e32 v201, v36, v100
	v_mul_f32_e32 v204, v36, v101
	v_cvt_pk_bf16_f32 v201, v201, v204
	v_mul_f32_e32 v202, v36, v102
	v_mul_f32_e32 v204, v36, v103
	v_cvt_pk_bf16_f32 v202, v202, v204
	v_mul_f32_e32 v203, v36, v104
	v_mul_f32_e32 v204, v36, v105
	v_cvt_pk_bf16_f32 v203, v203, v204
	s_nop 1
	v_permlane16_swap_b32_e32 v200, v202
	v_permlane16_swap_b32_e32 v201, v203
	global_store_dwordx4 v[214:215], v[200:203], off offset:384
	v_mul_f32_e32 v206, v36, v106
	v_mul_f32_e32 v210, v36, v107
	v_cvt_pk_bf16_f32 v206, v206, v210
	v_mul_f32_e32 v207, v36, v108
	v_mul_f32_e32 v210, v36, v109
	v_cvt_pk_bf16_f32 v207, v207, v210
	v_mul_f32_e32 v208, v36, v110
	v_mul_f32_e32 v210, v36, v111
	v_cvt_pk_bf16_f32 v208, v208, v210
	v_mul_f32_e32 v209, v36, v112
	v_mul_f32_e32 v210, v36, v113
	v_cvt_pk_bf16_f32 v209, v209, v210
	s_nop 1
	v_permlane16_swap_b32_e32 v206, v208
	v_permlane16_swap_b32_e32 v207, v209
	global_store_dwordx4 v[214:215], v[206:209], off offset:448
	s_waitcnt vmcnt(8)
	s_waitcnt vmcnt(8)
	s_barrier
	ds_read_b128 v[38:41], v65
	ds_read_b128 v[42:45], v65 offset:2048
	ds_read_b128 v[50:53], v65 offset:4096
	ds_read_b128 v[54:57], v65 offset:6144
	ds_read_b128 v[58:61], v65 offset:8192
	ds_read_b128 v[66:69], v65 offset:10240
	ds_read_b128 v[70:73], v65 offset:12288
	ds_read_b128 v[74:77], v65 offset:14336
	ds_read_b128 v[78:81], v65 offset:32768
	ds_read_b128 v[82:85], v65 offset:34816
	ds_read_b128 v[86:89], v65 offset:36864
	ds_read_b128 v[90:93], v65 offset:38912
	ds_read_b128 v[94:97], v65 offset:40960
	ds_read_b128 v[98:101], v65 offset:43008
	ds_read_b128 v[102:105], v65 offset:45056
	ds_read_b128 v[106:109], v65 offset:47104
	s_waitcnt lgkmcnt(0)
	v_mfma_f32_16x16x32_bf16 v[38:41], v[38:41], v[28:31], 0
	v_mfma_f32_16x16x32_bf16 v[42:45], v[42:45], v[28:31], 0
	v_mfma_f32_16x16x32_bf16 v[50:53], v[50:53], v[28:31], 0
	v_mfma_f32_16x16x32_bf16 v[54:57], v[54:57], v[28:31], 0
	v_mfma_f32_16x16x32_bf16 v[58:61], v[58:61], v[28:31], 0
	v_mfma_f32_16x16x32_bf16 v[66:69], v[66:69], v[28:31], 0
	v_mfma_f32_16x16x32_bf16 v[70:73], v[70:73], v[28:31], 0
	v_mfma_f32_16x16x32_bf16 v[74:77], v[74:77], v[28:31], 0
	s_add_u32 s100, s10, 0x11e20100
	s_addc_u32 s101, s11, 0
	s_mov_b32 m0, s19
	s_nop 0
	global_load_lds_dwordx4 v241, s[100:101]
	ds_read_b128 v[110:113], v65 offset:30720
	ds_read_b128 v[114:117], v65 offset:28672
	ds_read_b128 v[118:121], v65 offset:26624
	ds_read_b128 v[122:125], v65 offset:24576
	ds_read_b128 v[126:129], v65 offset:22528
	ds_read_b128 v[130:133], v65 offset:20480
	ds_read_b128 v[134:137], v65 offset:18432
	ds_read_b128 v[138:141], v65 offset:16384
	v_mfma_f32_16x16x32_bf16 v[78:81], v[78:81], v[28:31], 0
	v_mfma_f32_16x16x32_bf16 v[82:85], v[82:85], v[28:31], 0
	v_mfma_f32_16x16x32_bf16 v[86:89], v[86:89], v[28:31], 0
	v_mfma_f32_16x16x32_bf16 v[90:93], v[90:93], v[28:31], 0
	v_mfma_f32_16x16x32_bf16 v[94:97], v[94:97], v[28:31], 0
	v_mfma_f32_16x16x32_bf16 v[98:101], v[98:101], v[28:31], 0
	v_mfma_f32_16x16x32_bf16 v[102:105], v[102:105], v[28:31], 0
	v_mfma_f32_16x16x32_bf16 v[28:31], v[106:109], v[28:31], 0
	s_add_u32 s100, s10, 0x11e28100
	s_addc_u32 s101, s11, 0
	s_mov_b32 m0, s13
	s_nop 0
	global_load_lds_dwordx4 v241, s[100:101]
	s_waitcnt lgkmcnt(0)
	v_mfma_f32_16x16x32_bf16 v[38:41], v[138:141], v[24:27], v[38:41]
	v_mfma_f32_16x16x32_bf16 v[42:45], v[134:137], v[24:27], v[42:45]
	v_mfma_f32_16x16x32_bf16 v[50:53], v[130:133], v[24:27], v[50:53]
	v_mfma_f32_16x16x32_bf16 v[54:57], v[126:129], v[24:27], v[54:57]
	v_mfma_f32_16x16x32_bf16 v[58:61], v[122:125], v[24:27], v[58:61]
	v_mfma_f32_16x16x32_bf16 v[66:69], v[118:121], v[24:27], v[66:69]
	ds_read_b128 v[106:109], v65 offset:49152
	ds_read_b128 v[118:121], v65 offset:51200
	ds_read_b128 v[122:125], v65 offset:53248
	ds_read_b128 v[126:129], v65 offset:55296
	v_mfma_f32_16x16x32_bf16 v[70:73], v[114:117], v[24:27], v[70:73]
	ds_read_b128 v[114:117], v65 offset:57344
	ds_read_b128 v[130:133], v65 offset:59392
	ds_read_b128 v[134:137], v65 offset:61440
	ds_read_b128 v[138:141], v65 offset:63488
	v_mfma_f32_16x16x32_bf16 v[74:77], v[110:113], v[24:27], v[74:77]
	s_add_u32 s100, s10, 0x11e20180
	s_addc_u32 s101, s11, 0
	s_mov_b32 m0, s12
	s_nop 0
	global_load_lds_dwordx4 v241, s[100:101]
	s_waitcnt lgkmcnt(0)
	v_mfma_f32_16x16x32_bf16 v[78:81], v[106:109], v[24:27], v[78:81]
	v_mfma_f32_16x16x32_bf16 v[82:85], v[118:121], v[24:27], v[82:85]
	v_mfma_f32_16x16x32_bf16 v[86:89], v[122:125], v[24:27], v[86:89]
	v_mfma_f32_16x16x32_bf16 v[90:93], v[126:129], v[24:27], v[90:93]
	v_mfma_f32_16x16x32_bf16 v[94:97], v[114:117], v[24:27], v[94:97]
	ds_read_b128 v[106:109], v65 offset:15360
	ds_read_b128 v[110:113], v65 offset:13312
	ds_read_b128 v[114:117], v65 offset:11264
	ds_read_b128 v[118:121], v65 offset:9216
	v_mfma_f32_16x16x32_bf16 v[98:101], v[130:133], v[24:27], v[98:101]
	v_mfma_f32_16x16x32_bf16 v[102:105], v[134:137], v[24:27], v[102:105]
	ds_read_b128 v[122:125], v65 offset:7168
	ds_read_b128 v[126:129], v65 offset:5120
	ds_read_b128 v[130:133], v65 offset:3072
	ds_read_b128 v[134:137], v65 offset:1024
	v_mfma_f32_16x16x32_bf16 v[24:27], v[138:141], v[24:27], v[28:31]
	s_add_u32 s100, s10, 0x11e28180
	s_addc_u32 s101, s11, 0
	s_mov_b32 m0, s14
	s_nop 0
	global_load_lds_dwordx4 v241, s[100:101]
	s_waitcnt lgkmcnt(0)
	v_mfma_f32_16x16x32_bf16 v[28:31], v[134:137], v[20:23], v[38:41]
	v_mfma_f32_16x16x32_bf16 v[38:41], v[130:133], v[20:23], v[42:45]
	v_mfma_f32_16x16x32_bf16 v[42:45], v[126:129], v[20:23], v[50:53]
	v_mfma_f32_16x16x32_bf16 v[50:53], v[122:125], v[20:23], v[54:57]
	v_mfma_f32_16x16x32_bf16 v[54:57], v[118:121], v[20:23], v[58:61]
	v_mfma_f32_16x16x32_bf16 v[58:61], v[114:117], v[20:23], v[66:69]
	s_nop 2
	ds_read_b128 v[66:69], v65 offset:33792
	ds_read_b128 v[114:117], v65 offset:35840
	ds_read_b128 v[118:121], v65 offset:37888
	ds_read_b128 v[122:125], v65 offset:39936
	v_mfma_f32_16x16x32_bf16 v[70:73], v[110:113], v[20:23], v[70:73]
	ds_read_b128 v[110:113], v65 offset:41984
	ds_read_b128 v[126:129], v65 offset:44032
	ds_read_b128 v[130:133], v65 offset:46080
	ds_read_b128 v[134:137], v65 offset:48128
	v_mfma_f32_16x16x32_bf16 v[74:77], v[106:109], v[20:23], v[74:77]
	s_add_u32 s100, s10, 0x11e30100
	s_addc_u32 s101, s11, 0
	s_mov_b32 m0, s15
	s_nop 0
	global_load_lds_dwordx4 v241, s[100:101]
	s_waitcnt lgkmcnt(0)
	v_mfma_f32_16x16x32_bf16 v[66:69], v[66:69], v[20:23], v[78:81]
	v_mfma_f32_16x16x32_bf16 v[78:81], v[114:117], v[20:23], v[82:85]
	v_mfma_f32_16x16x32_bf16 v[82:85], v[118:121], v[20:23], v[86:89]
	v_mfma_f32_16x16x32_bf16 v[86:89], v[122:125], v[20:23], v[90:93]
	v_mfma_f32_16x16x32_bf16 v[90:93], v[110:113], v[20:23], v[94:97]
	v_mfma_f32_16x16x32_bf16 v[94:97], v[126:129], v[20:23], v[98:101]
	s_nop 2
	ds_read_b128 v[98:101], v65 offset:31744
	ds_read_b128 v[106:109], v65 offset:29696
	ds_read_b128 v[110:113], v65 offset:27648
	ds_read_b128 v[114:117], v65 offset:25600
	v_mfma_f32_16x16x32_bf16 v[102:105], v[130:133], v[20:23], v[102:105]
	ds_read_b128 v[118:121], v65 offset:23552
	ds_read_b128 v[122:125], v65 offset:21504
	ds_read_b128 v[126:129], v65 offset:19456
	ds_read_b128 v[130:133], v65 offset:17408
	v_mfma_f32_16x16x32_bf16 v[20:23], v[134:137], v[20:23], v[24:27]
	s_add_u32 s100, s10, 0x11e38100
	s_addc_u32 s101, s11, 0
	s_mov_b32 m0, s16
	s_nop 0
	global_load_lds_dwordx4 v241, s[100:101]
	s_waitcnt lgkmcnt(0)
	v_mfma_f32_16x16x32_bf16 v[24:27], v[130:133], v[16:19], v[28:31]
	v_mfma_f32_16x16x32_bf16 v[28:31], v[126:129], v[16:19], v[38:41]
	v_mfma_f32_16x16x32_bf16 v[38:41], v[122:125], v[16:19], v[42:45]
	v_mfma_f32_16x16x32_bf16 v[42:45], v[118:121], v[16:19], v[50:53]
	v_mfma_f32_16x16x32_bf16 v[50:53], v[114:117], v[16:19], v[54:57]
	v_mfma_f32_16x16x32_bf16 v[54:57], v[110:113], v[16:19], v[58:61]
	s_nop 2
	ds_read_b128 v[58:61], v65 offset:50176
	ds_read_b128 v[110:113], v65 offset:52224
	ds_read_b128 v[114:117], v65 offset:54272
	ds_read_b128 v[118:121], v65 offset:56320
	v_mfma_f32_16x16x32_bf16 v[70:73], v[106:109], v[16:19], v[70:73]
	ds_read_b128 v[106:109], v65 offset:58368
	ds_read_b128 v[122:125], v65 offset:60416
	ds_read_b128 v[126:129], v65 offset:62464
	ds_read_b128 v[62:65], v65 offset:64512
	v_mfma_f32_16x16x32_bf16 v[74:77], v[98:101], v[16:19], v[74:77]
	s_add_u32 s100, s10, 0x11e30180
	s_addc_u32 s101, s11, 0
	s_mov_b32 m0, s17
	s_nop 0
	global_load_lds_dwordx4 v241, s[100:101]
	s_waitcnt lgkmcnt(0)
	v_mfma_f32_16x16x32_bf16 v[58:61], v[58:61], v[16:19], v[66:69]
	v_mfma_f32_16x16x32_bf16 v[66:69], v[110:113], v[16:19], v[78:81]
	v_mfma_f32_16x16x32_bf16 v[78:81], v[114:117], v[16:19], v[82:85]
	v_mfma_f32_16x16x32_bf16 v[82:85], v[118:121], v[16:19], v[86:89]
	v_mfma_f32_16x16x32_bf16 v[86:89], v[106:109], v[16:19], v[90:93]
	v_mfma_f32_16x16x32_bf16 v[90:93], v[122:125], v[16:19], v[94:97]
	v_mfma_f32_16x16x32_bf16 v[94:97], v[126:129], v[16:19], v[102:105]
	v_mfma_f32_16x16x32_bf16 v[16:19], v[62:65], v[16:19], v[20:23]
	s_add_u32 s100, s10, 0x11e38180
	s_addc_u32 s101, s11, 0
	s_mov_b32 m0, s18
	s_nop 0
	global_load_lds_dwordx4 v241, s[100:101]
	s_waitcnt vmcnt(0)
	s_waitcnt vmcnt(0)
	s_barrier
	s_nop 0
	ds_read_b128 v[20:23], v48
	ds_read_b128 v[62:65], v48 offset:2048
	s_waitcnt lgkmcnt(1)
	v_mfma_f32_16x16x32_bf16 v[20:23], v[20:23], v[12:15], v[24:27]
	s_nop 2
	ds_read_b128 v[24:27], v48 offset:4096
	s_waitcnt lgkmcnt(1)
	v_mfma_f32_16x16x32_bf16 v[28:31], v[62:65], v[12:15], v[28:31]
	ds_read_b128 v[62:65], v48 offset:6144
	s_waitcnt lgkmcnt(1)
	v_mfma_f32_16x16x32_bf16 v[24:27], v[24:27], v[12:15], v[38:41]
	s_nop 2
	ds_read_b128 v[38:41], v48 offset:8192
	s_waitcnt lgkmcnt(1)
	v_mfma_f32_16x16x32_bf16 v[42:45], v[62:65], v[12:15], v[42:45]
	ds_read_b128 v[62:65], v48 offset:10240
	s_waitcnt lgkmcnt(1)
	v_mfma_f32_16x16x32_bf16 v[38:41], v[38:41], v[12:15], v[50:53]
	s_nop 2
	ds_read_b128 v[50:53], v48 offset:12288
	ds_read_b128 v[98:101], v48 offset:14336
	s_waitcnt lgkmcnt(2)
	v_mfma_f32_16x16x32_bf16 v[54:57], v[62:65], v[12:15], v[54:57]
	ds_read_b128 v[62:65], v48 offset:32768
	ds_read_b128 v[102:105], v48 offset:34816
	ds_read_b128 v[106:109], v48 offset:36864
	ds_read_b128 v[110:113], v48 offset:38912
	s_waitcnt lgkmcnt(5)
	v_mfma_f32_16x16x32_bf16 v[50:53], v[50:53], v[12:15], v[70:73]
	s_nop 2
	ds_read_b128 v[70:73], v48 offset:40960
	ds_read_b128 v[114:117], v48 offset:43008
	ds_read_b128 v[118:121], v48 offset:45056
	ds_read_b128 v[122:125], v48 offset:47104
	s_waitcnt lgkmcnt(8)
	v_mfma_f32_16x16x32_bf16 v[74:77], v[98:101], v[12:15], v[74:77]
	s_waitcnt lgkmcnt(7)
	v_mfma_f32_16x16x32_bf16 v[58:61], v[62:65], v[12:15], v[58:61]
	s_waitcnt lgkmcnt(6)
	v_mfma_f32_16x16x32_bf16 v[62:65], v[102:105], v[12:15], v[66:69]
	s_waitcnt lgkmcnt(5)
	v_mfma_f32_16x16x32_bf16 v[66:69], v[106:109], v[12:15], v[78:81]
	s_waitcnt lgkmcnt(4)
	v_mfma_f32_16x16x32_bf16 v[78:81], v[110:113], v[12:15], v[82:85]
	s_waitcnt lgkmcnt(3)
	v_mfma_f32_16x16x32_bf16 v[70:73], v[70:73], v[12:15], v[86:89]
	s_waitcnt lgkmcnt(2)
	v_mfma_f32_16x16x32_bf16 v[82:85], v[114:117], v[12:15], v[90:93]
	s_nop 0
	ds_read_b128 v[86:89], v48 offset:30720
	s_nop 0
	ds_read_b128 v[90:93], v48 offset:28672
	ds_read_b128 v[98:101], v48 offset:26624
	ds_read_b128 v[102:105], v48 offset:24576
	s_waitcnt lgkmcnt(5)
	v_mfma_f32_16x16x32_bf16 v[94:97], v[118:121], v[12:15], v[94:97]
	ds_read_b128 v[106:109], v48 offset:22528
	ds_read_b128 v[110:113], v48 offset:20480
	ds_read_b128 v[114:117], v48 offset:18432
	ds_read_b128 v[118:121], v48 offset:16384
	s_waitcnt lgkmcnt(8)
	v_mfma_f32_16x16x32_bf16 v[12:15], v[122:125], v[12:15], v[16:19]
	s_waitcnt lgkmcnt(0)
	v_mfma_f32_16x16x32_bf16 v[16:19], v[118:121], v[8:11], v[20:23]
	v_mfma_f32_16x16x32_bf16 v[20:23], v[114:117], v[8:11], v[28:31]
	v_mfma_f32_16x16x32_bf16 v[24:27], v[110:113], v[8:11], v[24:27]
	v_mfma_f32_16x16x32_bf16 v[28:31], v[106:109], v[8:11], v[42:45]
	v_mfma_f32_16x16x32_bf16 v[38:41], v[102:105], v[8:11], v[38:41]
	v_mfma_f32_16x16x32_bf16 v[42:45], v[98:101], v[8:11], v[54:57]
	s_nop 2
	ds_read_b128 v[54:57], v48 offset:49152
	ds_read_b128 v[98:101], v48 offset:51200
	ds_read_b128 v[102:105], v48 offset:53248
	ds_read_b128 v[106:109], v48 offset:55296
	v_mfma_f32_16x16x32_bf16 v[50:53], v[90:93], v[8:11], v[50:53]
	ds_read_b128 v[90:93], v48 offset:57344
	ds_read_b128 v[110:113], v48 offset:59392
	ds_read_b128 v[114:117], v48 offset:61440
	ds_read_b128 v[118:121], v48 offset:63488
	v_mfma_f32_16x16x32_bf16 v[74:77], v[86:89], v[8:11], v[74:77]
	s_waitcnt lgkmcnt(7)
	v_mfma_f32_16x16x32_bf16 v[54:57], v[54:57], v[8:11], v[58:61]
	s_waitcnt lgkmcnt(6)
	v_mfma_f32_16x16x32_bf16 v[58:61], v[98:101], v[8:11], v[62:65]
	s_waitcnt lgkmcnt(5)
	v_mfma_f32_16x16x32_bf16 v[62:65], v[102:105], v[8:11], v[66:69]
	s_waitcnt lgkmcnt(4)
	v_mfma_f32_16x16x32_bf16 v[66:69], v[106:109], v[8:11], v[78:81]
	s_waitcnt lgkmcnt(3)
	v_mfma_f32_16x16x32_bf16 v[70:73], v[90:93], v[8:11], v[70:73]
	s_waitcnt lgkmcnt(2)
	v_mfma_f32_16x16x32_bf16 v[78:81], v[110:113], v[8:11], v[82:85]
	s_nop 2
	ds_read_b128 v[82:85], v48 offset:15360
	ds_read_b128 v[86:89], v48 offset:13312
	ds_read_b128 v[90:93], v48 offset:11264
	ds_read_b128 v[98:101], v48 offset:9216
	s_waitcnt lgkmcnt(5)
	v_mfma_f32_16x16x32_bf16 v[94:97], v[114:117], v[8:11], v[94:97]
	ds_read_b128 v[102:105], v48 offset:7168
	ds_read_b128 v[106:109], v48 offset:5120
	ds_read_b128 v[110:113], v48 offset:3072
	ds_read_b128 v[114:117], v48 offset:1024
	s_waitcnt lgkmcnt(8)
	v_mfma_f32_16x16x32_bf16 v[8:11], v[118:121], v[8:11], v[12:15]
	s_waitcnt lgkmcnt(0)
	v_mfma_f32_16x16x32_bf16 v[12:15], v[114:117], v[4:7], v[16:19]
	v_mfma_f32_16x16x32_bf16 v[16:19], v[110:113], v[4:7], v[20:23]
	v_mfma_f32_16x16x32_bf16 v[20:23], v[106:109], v[4:7], v[24:27]
	v_mfma_f32_16x16x32_bf16 v[24:27], v[102:105], v[4:7], v[28:31]
	v_mfma_f32_16x16x32_bf16 v[28:31], v[98:101], v[4:7], v[38:41]
	v_mfma_f32_16x16x32_bf16 v[38:41], v[90:93], v[4:7], v[42:45]
	s_nop 2
	ds_read_b128 v[42:45], v48 offset:33792
	ds_read_b128 v[90:93], v48 offset:35840
	ds_read_b128 v[98:101], v48 offset:37888
	ds_read_b128 v[102:105], v48 offset:39936
	v_mfma_f32_16x16x32_bf16 v[50:53], v[86:89], v[4:7], v[50:53]
	ds_read_b128 v[86:89], v48 offset:41984
	ds_read_b128 v[106:109], v48 offset:44032
	ds_read_b128 v[110:113], v48 offset:46080
	ds_read_b128 v[114:117], v48 offset:48128
	v_mfma_f32_16x16x32_bf16 v[74:77], v[82:85], v[4:7], v[74:77]
	s_waitcnt lgkmcnt(7)
	v_mfma_f32_16x16x32_bf16 v[42:45], v[42:45], v[4:7], v[54:57]
	s_waitcnt lgkmcnt(6)
	v_mfma_f32_16x16x32_bf16 v[54:57], v[90:93], v[4:7], v[58:61]
	s_waitcnt lgkmcnt(5)
	v_mfma_f32_16x16x32_bf16 v[58:61], v[98:101], v[4:7], v[62:65]
	s_waitcnt lgkmcnt(4)
	v_mfma_f32_16x16x32_bf16 v[62:65], v[102:105], v[4:7], v[66:69]
	s_waitcnt lgkmcnt(3)
	v_mfma_f32_16x16x32_bf16 v[66:69], v[86:89], v[4:7], v[70:73]
	s_waitcnt lgkmcnt(2)
	v_mfma_f32_16x16x32_bf16 v[70:73], v[106:109], v[4:7], v[78:81]
	s_nop 2
	ds_read_b128 v[78:81], v48 offset:31744
	ds_read_b128 v[82:85], v48 offset:29696
	ds_read_b128 v[86:89], v48 offset:27648
	ds_read_b128 v[90:93], v48 offset:25600
	s_waitcnt lgkmcnt(5)
	v_mfma_f32_16x16x32_bf16 v[94:97], v[110:113], v[4:7], v[94:97]
	ds_read_b128 v[98:101], v48 offset:23552
	ds_read_b128 v[102:105], v48 offset:21504
	ds_read_b128 v[106:109], v48 offset:19456
	ds_read_b128 v[110:113], v48 offset:17408
	s_waitcnt lgkmcnt(8)
	v_mfma_f32_16x16x32_bf16 v[4:7], v[114:117], v[4:7], v[8:11]
	s_waitcnt lgkmcnt(0)
	v_mfma_f32_16x16x32_bf16 v[8:11], v[110:113], v[0:3], v[12:15]
	v_mfma_f32_16x16x32_bf16 v[12:15], v[106:109], v[0:3], v[16:19]
	v_mfma_f32_16x16x32_bf16 v[16:19], v[102:105], v[0:3], v[20:23]
	v_mfma_f32_16x16x32_bf16 v[20:23], v[98:101], v[0:3], v[24:27]
	v_mfma_f32_16x16x32_bf16 v[24:27], v[90:93], v[0:3], v[28:31]
	v_mfma_f32_16x16x32_bf16 v[28:31], v[86:89], v[0:3], v[38:41]
	s_nop 2
	ds_read_b128 v[38:41], v48 offset:50176
	ds_read_b128 v[86:89], v48 offset:52224
	ds_read_b128 v[90:93], v48 offset:54272
	ds_read_b128 v[98:101], v48 offset:56320
	v_mfma_f32_16x16x32_bf16 v[50:53], v[82:85], v[0:3], v[50:53]
	ds_read_b128 v[82:85], v48 offset:58368
	ds_read_b128 v[102:105], v48 offset:60416
	ds_read_b128 v[106:109], v48 offset:62464
	ds_read_b128 v[46:49], v48 offset:64512
	v_mfma_f32_16x16x32_bf16 v[74:77], v[78:81], v[0:3], v[74:77]
	s_waitcnt lgkmcnt(7)
	v_mfma_f32_16x16x32_bf16 v[38:41], v[38:41], v[0:3], v[42:45]
	s_waitcnt lgkmcnt(6)
	v_mfma_f32_16x16x32_bf16 v[42:45], v[86:89], v[0:3], v[54:57]
	s_waitcnt lgkmcnt(5)
	v_mfma_f32_16x16x32_bf16 v[54:57], v[90:93], v[0:3], v[58:61]
	s_waitcnt lgkmcnt(4)
	v_mfma_f32_16x16x32_bf16 v[58:61], v[98:101], v[0:3], v[62:65]
	s_waitcnt lgkmcnt(3)
	v_mfma_f32_16x16x32_bf16 v[62:65], v[82:85], v[0:3], v[66:69]
	s_waitcnt lgkmcnt(2)
	v_mfma_f32_16x16x32_bf16 v[66:69], v[102:105], v[0:3], v[70:73]
	s_waitcnt lgkmcnt(1)
	v_mfma_f32_16x16x32_bf16 v[70:73], v[106:109], v[0:3], v[94:97]
	s_waitcnt lgkmcnt(0)
	v_mfma_f32_16x16x32_bf16 v[0:3], v[46:49], v[0:3], v[4:7]
	s_nop 2
	v_mul_f32_e32 v200, v36, v8
	v_mul_f32_e32 v204, v36, v9
	v_cvt_pk_bf16_f32 v200, v200, v204
	v_mul_f32_e32 v201, v36, v10
	v_mul_f32_e32 v204, v36, v11
	v_cvt_pk_bf16_f32 v201, v201, v204
	v_mul_f32_e32 v202, v36, v12
	v_mul_f32_e32 v204, v36, v13
	v_cvt_pk_bf16_f32 v202, v202, v204
	v_mul_f32_e32 v203, v36, v14
	v_mul_f32_e32 v204, v36, v15
	v_cvt_pk_bf16_f32 v203, v203, v204
	s_nop 1
	v_permlane16_swap_b32_e32 v200, v202
	v_permlane16_swap_b32_e32 v201, v203
	global_store_dwordx4 v[214:215], v[200:203], off offset:512
	v_mul_f32_e32 v206, v36, v16
	v_mul_f32_e32 v210, v36, v17
	v_cvt_pk_bf16_f32 v206, v206, v210
	v_mul_f32_e32 v207, v36, v18
	v_mul_f32_e32 v210, v36, v19
	v_cvt_pk_bf16_f32 v207, v207, v210
	v_mul_f32_e32 v208, v36, v20
	v_mul_f32_e32 v210, v36, v21
	v_cvt_pk_bf16_f32 v208, v208, v210
	v_mul_f32_e32 v209, v36, v22
	v_mul_f32_e32 v210, v36, v23
	v_cvt_pk_bf16_f32 v209, v209, v210
	s_nop 1
	v_permlane16_swap_b32_e32 v206, v208
	v_permlane16_swap_b32_e32 v207, v209
	global_store_dwordx4 v[214:215], v[206:209], off offset:576
	v_mul_f32_e32 v200, v36, v24
	v_mul_f32_e32 v204, v36, v25
	v_cvt_pk_bf16_f32 v200, v200, v204
	v_mul_f32_e32 v201, v36, v26
	v_mul_f32_e32 v204, v36, v27
	v_cvt_pk_bf16_f32 v201, v201, v204
	v_mul_f32_e32 v202, v36, v28
	v_mul_f32_e32 v204, v36, v29
	v_cvt_pk_bf16_f32 v202, v202, v204
	v_mul_f32_e32 v203, v36, v30
	v_mul_f32_e32 v204, v36, v31
	v_cvt_pk_bf16_f32 v203, v203, v204
	s_nop 1
	v_permlane16_swap_b32_e32 v200, v202
	v_permlane16_swap_b32_e32 v201, v203
	global_store_dwordx4 v[214:215], v[200:203], off offset:640
	v_mul_f32_e32 v206, v36, v50
	v_mul_f32_e32 v210, v36, v51
	v_cvt_pk_bf16_f32 v206, v206, v210
	v_mul_f32_e32 v207, v36, v52
	v_mul_f32_e32 v210, v36, v53
	v_cvt_pk_bf16_f32 v207, v207, v210
	v_mul_f32_e32 v208, v36, v74
	v_mul_f32_e32 v210, v36, v75
	v_cvt_pk_bf16_f32 v208, v208, v210
	v_mul_f32_e32 v209, v36, v76
	v_mul_f32_e32 v210, v36, v77
	v_cvt_pk_bf16_f32 v209, v209, v210
	s_nop 1
	v_permlane16_swap_b32_e32 v206, v208
	v_permlane16_swap_b32_e32 v207, v209
	global_store_dwordx4 v[214:215], v[206:209], off offset:704
	v_mul_f32_e32 v200, v36, v38
	v_mul_f32_e32 v204, v36, v39
	v_cvt_pk_bf16_f32 v200, v200, v204
	v_mul_f32_e32 v201, v36, v40
	v_mul_f32_e32 v204, v36, v41
	v_cvt_pk_bf16_f32 v201, v201, v204
	v_mul_f32_e32 v202, v36, v42
	v_mul_f32_e32 v204, v36, v43
	v_cvt_pk_bf16_f32 v202, v202, v204
	v_mul_f32_e32 v203, v36, v44
	v_mul_f32_e32 v204, v36, v45
	v_cvt_pk_bf16_f32 v203, v203, v204
	s_nop 1
	v_permlane16_swap_b32_e32 v200, v202
	v_permlane16_swap_b32_e32 v201, v203
	global_store_dwordx4 v[214:215], v[200:203], off offset:768
	v_mul_f32_e32 v206, v36, v54
	v_mul_f32_e32 v210, v36, v55
	v_cvt_pk_bf16_f32 v206, v206, v210
	v_mul_f32_e32 v207, v36, v56
	v_mul_f32_e32 v210, v36, v57
	v_cvt_pk_bf16_f32 v207, v207, v210
	v_mul_f32_e32 v208, v36, v58
	v_mul_f32_e32 v210, v36, v59
	v_cvt_pk_bf16_f32 v208, v208, v210
	v_mul_f32_e32 v209, v36, v60
	v_mul_f32_e32 v210, v36, v61
	v_cvt_pk_bf16_f32 v209, v209, v210
	s_nop 1
	v_permlane16_swap_b32_e32 v206, v208
	v_permlane16_swap_b32_e32 v207, v209
	global_store_dwordx4 v[214:215], v[206:209], off offset:832
	v_mul_f32_e32 v200, v36, v62
	v_mul_f32_e32 v204, v36, v63
	v_cvt_pk_bf16_f32 v200, v200, v204
	v_mul_f32_e32 v201, v36, v64
	v_mul_f32_e32 v204, v36, v65
	v_cvt_pk_bf16_f32 v201, v201, v204
	v_mul_f32_e32 v202, v36, v66
	v_mul_f32_e32 v204, v36, v67
	v_cvt_pk_bf16_f32 v202, v202, v204
	v_mul_f32_e32 v203, v36, v68
	v_mul_f32_e32 v204, v36, v69
	v_cvt_pk_bf16_f32 v203, v203, v204
	s_nop 1
	v_permlane16_swap_b32_e32 v200, v202
	v_permlane16_swap_b32_e32 v201, v203
	global_store_dwordx4 v[214:215], v[200:203], off offset:896
	v_mul_f32_e32 v206, v36, v70
	v_mul_f32_e32 v210, v36, v71
	v_cvt_pk_bf16_f32 v206, v206, v210
	v_mul_f32_e32 v207, v36, v72
	v_mul_f32_e32 v210, v36, v73
	v_cvt_pk_bf16_f32 v207, v207, v210
	v_mul_f32_e32 v208, v36, v0
	v_mul_f32_e32 v210, v36, v1
	v_cvt_pk_bf16_f32 v208, v208, v210
	v_mul_f32_e32 v209, v36, v2
	v_mul_f32_e32 v210, v36, v3
	v_cvt_pk_bf16_f32 v209, v209, v210
	s_nop 1
	v_permlane16_swap_b32_e32 v206, v208
	v_permlane16_swap_b32_e32 v207, v209
	global_store_dwordx4 v[214:215], v[206:209], off offset:960
	s_waitcnt vmcnt(0)
	s_setprio 0
	s_barrier
